# np_il + MFMA-wave priority only from the 13th MFMA of each block; attention-A inline counted LDS waits made full waits (hides the baseline's latent MFMA-operand WAR hazard that this timing exposed)
# speedup vs baseline: 1.0669x; 1.0669x over previous
.LBB0_140:
	s_add_u32 s2, s22, 0xfff80080
	s_addc_u32 s20, s23, -1
	s_add_i32 s45, 0, 0x10000
	s_cmp_eq_u32 s44, 28
	s_cselect_b32 s25, s15, s20
	s_cselect_b32 s24, s40, s2
	v_add_u32_e32 v144, s45, v148
	s_cselect_b32 s21, s13, s43
	s_cselect_b32 s20, s41, s42
	s_add_u32 s100, s22, 0xfff80000
	s_addc_u32 s101, s23, -1
	s_add_i32 s2, 0, 0x14000
	s_mov_b32 m0, s35
	ds_read_b128 v[140:143], v144
	ds_read_b128 v[152:155], v144 offset:1024
	ds_read_b128 v[156:159], v144 offset:2048
	ds_read_b128 v[160:163], v144 offset:3072
	global_load_lds_dwordx4 v136, s[100:101]
	s_mov_b32 m0, s36
	v_add_u32_e32 v144, s2, v148
	ds_read_b128 v[164:167], v144
	ds_read_b128 v[168:171], v144 offset:1024
	ds_read_b128 v[172:175], v144 offset:2048
	ds_read_b128 v[176:179], v144 offset:3072
	global_load_lds_dwordx4 v138, s[100:101]
	s_add_i32 m0, s29, 0xc000
	ds_read_b128 v[180:183], v151
	ds_read_b128 v[184:187], v151 offset:1024
	ds_read_b128 v[188:191], v151 offset:2048
	ds_read_b128 v[192:195], v151 offset:3072
	global_load_lds_dwordx4 v136, s[22:23]
	s_add_i32 m0, s29, 0xe000
	ds_read_b128 v[206:209], v151 offset:4096
	ds_read_b128 v[210:213], v151 offset:5120
	ds_read_b128 v[214:217], v151 offset:6144
	ds_read_b128 v[218:221], v151 offset:7168
	global_load_lds_dwordx4 v138, s[22:23]
	s_waitcnt vmcnt(8)
	s_waitcnt lgkmcnt(0)
	s_barrier
	s_waitcnt lgkmcnt(0)
	v_mfma_f32_16x16x32_bf16 v[126:129], v[140:143], v[180:183], v[126:129]
	v_mfma_f32_16x16x32_bf16 v[122:125], v[156:159], v[180:183], v[122:125]
	v_mfma_f32_16x16x32_bf16 v[110:113], v[140:143], v[188:191], v[110:113]
	v_mfma_f32_16x16x32_bf16 v[106:109], v[156:159], v[188:191], v[106:109]
	v_mfma_f32_16x16x32_bf16 v[94:97], v[140:143], v[206:209], v[94:97]
	v_mfma_f32_16x16x32_bf16 v[90:93], v[156:159], v[206:209], v[90:93]
	v_mfma_f32_16x16x32_bf16 v[78:81], v[140:143], v[214:217], v[78:81]
	v_mfma_f32_16x16x32_bf16 v[74:77], v[156:159], v[214:217], v[74:77]
	v_mfma_f32_16x16x32_bf16 v[126:129], v[152:155], v[184:187], v[126:129]
	v_mfma_f32_16x16x32_bf16 v[122:125], v[160:163], v[184:187], v[122:125]
	v_mfma_f32_16x16x32_bf16 v[110:113], v[152:155], v[192:195], v[110:113]
	v_mfma_f32_16x16x32_bf16 v[106:109], v[160:163], v[192:195], v[106:109]
	s_setprio 1
	v_mfma_f32_16x16x32_bf16 v[94:97], v[152:155], v[210:213], v[94:97]
	v_mfma_f32_16x16x32_bf16 v[90:93], v[160:163], v[210:213], v[90:93]
	v_mfma_f32_16x16x32_bf16 v[78:81], v[152:155], v[218:221], v[78:81]
	v_mfma_f32_16x16x32_bf16 v[74:77], v[160:163], v[218:221], v[74:77]
	v_mfma_f32_16x16x32_bf16 v[118:121], v[164:167], v[180:183], v[118:121]
	v_mfma_f32_16x16x32_bf16 v[114:117], v[172:175], v[180:183], v[114:117]
	v_mfma_f32_16x16x32_bf16 v[102:105], v[164:167], v[188:191], v[102:105]
	v_mfma_f32_16x16x32_bf16 v[98:101], v[172:175], v[188:191], v[98:101]
	v_mfma_f32_16x16x32_bf16 v[86:89], v[164:167], v[206:209], v[86:89]
	v_mfma_f32_16x16x32_bf16 v[82:85], v[172:175], v[206:209], v[82:85]
	v_mfma_f32_16x16x32_bf16 v[70:73], v[164:167], v[214:217], v[70:73]
	v_mfma_f32_16x16x32_bf16 v[66:69], v[172:175], v[214:217], v[66:69]
	v_mfma_f32_16x16x32_bf16 v[118:121], v[168:171], v[184:187], v[118:121]
	v_mfma_f32_16x16x32_bf16 v[114:117], v[176:179], v[184:187], v[114:117]
	v_mfma_f32_16x16x32_bf16 v[102:105], v[168:171], v[192:195], v[102:105]
	v_mfma_f32_16x16x32_bf16 v[98:101], v[176:179], v[192:195], v[98:101]
	v_mfma_f32_16x16x32_bf16 v[86:89], v[168:171], v[210:213], v[86:89]
	v_mfma_f32_16x16x32_bf16 v[82:85], v[176:179], v[210:213], v[82:85]
	v_mfma_f32_16x16x32_bf16 v[70:73], v[168:171], v[218:221], v[70:73]
	v_mfma_f32_16x16x32_bf16 v[66:69], v[176:179], v[218:221], v[66:69]
	s_setprio 0
	s_barrier
	s_add_u32 s46, s20, 0x80000
	s_addc_u32 s47, s21, 0
	s_add_i32 s45, s45, s28
	s_mov_b32 m0, s45
	ds_read_b128 v[180:183], v151 offset:16384
	ds_read_b128 v[184:187], v151 offset:17408
	global_load_lds_dwordx4 v0, s[20:21]
	s_add_i32 m0, s45, 0x2000
	s_add_i32 s2, s2, s28
	ds_read_b128 v[188:191], v151 offset:18432
	ds_read_b128 v[192:195], v151 offset:19456
	global_load_lds_dwordx4 v130, s[20:21]
	s_mov_b32 m0, s2
	ds_read_b128 v[206:209], v151 offset:20480
	ds_read_b128 v[210:213], v151 offset:21504
	global_load_lds_dwordx4 v0, s[46:47]
	s_add_i32 m0, s2, 0x2000
	ds_read_b128 v[214:217], v151 offset:22528
	ds_read_b128 v[218:221], v151 offset:23552
	global_load_lds_dwordx4 v130, s[46:47]
	s_waitcnt vmcnt(6)
	s_waitcnt lgkmcnt(0)
	s_barrier
	s_waitcnt lgkmcnt(0)
	v_mfma_f32_16x16x32_bf16 v[62:65], v[140:143], v[180:183], v[62:65]
	v_mfma_f32_16x16x32_bf16 v[58:61], v[156:159], v[180:183], v[58:61]
	v_mfma_f32_16x16x32_bf16 v[46:49], v[140:143], v[188:191], v[46:49]
	v_mfma_f32_16x16x32_bf16 v[42:45], v[156:159], v[188:191], v[42:45]
	v_mfma_f32_16x16x32_bf16 v[30:33], v[140:143], v[206:209], v[30:33]
	v_mfma_f32_16x16x32_bf16 v[26:29], v[156:159], v[206:209], v[26:29]
	v_mfma_f32_16x16x32_bf16 v[14:17], v[140:143], v[214:217], v[14:17]
	v_mfma_f32_16x16x32_bf16 v[10:13], v[156:159], v[214:217], v[10:13]
	v_mfma_f32_16x16x32_bf16 v[62:65], v[152:155], v[184:187], v[62:65]
	v_mfma_f32_16x16x32_bf16 v[58:61], v[160:163], v[184:187], v[58:61]
	v_mfma_f32_16x16x32_bf16 v[46:49], v[152:155], v[192:195], v[46:49]
	v_mfma_f32_16x16x32_bf16 v[42:45], v[160:163], v[192:195], v[42:45]
	s_setprio 1
	v_mfma_f32_16x16x32_bf16 v[30:33], v[152:155], v[210:213], v[30:33]
	v_mfma_f32_16x16x32_bf16 v[26:29], v[160:163], v[210:213], v[26:29]
	v_mfma_f32_16x16x32_bf16 v[14:17], v[152:155], v[218:221], v[14:17]
	v_mfma_f32_16x16x32_bf16 v[10:13], v[160:163], v[218:221], v[10:13]
	v_mfma_f32_16x16x32_bf16 v[54:57], v[164:167], v[180:183], v[54:57]
	v_mfma_f32_16x16x32_bf16 v[50:53], v[172:175], v[180:183], v[50:53]
	v_mfma_f32_16x16x32_bf16 v[38:41], v[164:167], v[188:191], v[38:41]
	v_mfma_f32_16x16x32_bf16 v[34:37], v[172:175], v[188:191], v[34:37]
	v_mfma_f32_16x16x32_bf16 v[22:25], v[164:167], v[206:209], v[22:25]
	v_mfma_f32_16x16x32_bf16 v[18:21], v[172:175], v[206:209], v[18:21]
	v_mfma_f32_16x16x32_bf16 v[6:9], v[164:167], v[214:217], v[6:9]
	v_mfma_f32_16x16x32_bf16 v[2:5], v[172:175], v[214:217], v[2:5]
	v_mfma_f32_16x16x32_bf16 v[54:57], v[168:171], v[184:187], v[54:57]
	v_mfma_f32_16x16x32_bf16 v[50:53], v[176:179], v[184:187], v[50:53]
	v_mfma_f32_16x16x32_bf16 v[38:41], v[168:171], v[192:195], v[38:41]
	v_mfma_f32_16x16x32_bf16 v[34:37], v[176:179], v[192:195], v[34:37]
	v_mfma_f32_16x16x32_bf16 v[22:25], v[168:171], v[210:213], v[22:25]
	v_mfma_f32_16x16x32_bf16 v[18:21], v[176:179], v[210:213], v[18:21]
	v_mfma_f32_16x16x32_bf16 v[6:9], v[168:171], v[218:221], v[6:9]
	v_mfma_f32_16x16x32_bf16 v[2:5], v[176:179], v[218:221], v[2:5]
	s_setprio 0
	s_barrier
	s_add_u32 s24, s24, 0x80000
	s_addc_u32 s25, s25, 0
	s_add_u32 s100, s24, 0xfff80000
	s_addc_u32 s101, s25, -1
	s_add_i32 s2, 0, 0x18000
	s_add_i32 s45, 0, 0x1c000
	v_add_u32_e32 v160, s2, v148
	v_add_u32_e32 v176, s45, v148
	s_mov_b32 m0, s29
	ds_read_b128 v[140:143], v160
	ds_read_b128 v[152:155], v160 offset:1024
	ds_read_b128 v[156:159], v160 offset:2048
	ds_read_b128 v[160:163], v160 offset:3072
	global_load_lds_dwordx4 v134, s[100:101]
	s_mov_b32 m0, s30
	ds_read_b128 v[164:167], v176
	ds_read_b128 v[168:171], v176 offset:1024
	ds_read_b128 v[172:175], v176 offset:2048
	ds_read_b128 v[176:179], v176 offset:3072
	global_load_lds_dwordx4 v132, s[100:101]
	s_mov_b32 m0, s31
	ds_read_b128 v[180:183], v151 offset:32768
	ds_read_b128 v[184:187], v151 offset:33792
	ds_read_b128 v[188:191], v151 offset:34816
	ds_read_b128 v[192:195], v151 offset:35840
	global_load_lds_dwordx4 v134, s[24:25]
	s_mov_b32 m0, s33
	ds_read_b128 v[206:209], v151 offset:36864
	ds_read_b128 v[210:213], v151 offset:37888
	ds_read_b128 v[214:217], v151 offset:38912
	ds_read_b128 v[218:221], v151 offset:39936
	global_load_lds_dwordx4 v132, s[24:25]
	s_waitcnt vmcnt(8)
	s_waitcnt lgkmcnt(0)
	s_barrier
	s_waitcnt lgkmcnt(0)
	v_mfma_f32_16x16x32_bf16 v[126:129], v[140:143], v[180:183], v[126:129]
	v_mfma_f32_16x16x32_bf16 v[122:125], v[156:159], v[180:183], v[122:125]
	v_mfma_f32_16x16x32_bf16 v[110:113], v[140:143], v[188:191], v[110:113]
	v_mfma_f32_16x16x32_bf16 v[106:109], v[156:159], v[188:191], v[106:109]
	v_mfma_f32_16x16x32_bf16 v[94:97], v[140:143], v[206:209], v[94:97]
	v_mfma_f32_16x16x32_bf16 v[90:93], v[156:159], v[206:209], v[90:93]
	v_mfma_f32_16x16x32_bf16 v[78:81], v[140:143], v[214:217], v[78:81]
	v_mfma_f32_16x16x32_bf16 v[74:77], v[156:159], v[214:217], v[74:77]
	v_mfma_f32_16x16x32_bf16 v[126:129], v[152:155], v[184:187], v[126:129]
	v_mfma_f32_16x16x32_bf16 v[122:125], v[160:163], v[184:187], v[122:125]
	v_mfma_f32_16x16x32_bf16 v[110:113], v[152:155], v[192:195], v[110:113]
	v_mfma_f32_16x16x32_bf16 v[106:109], v[160:163], v[192:195], v[106:109]
	s_setprio 1
	v_mfma_f32_16x16x32_bf16 v[94:97], v[152:155], v[210:213], v[94:97]
	v_mfma_f32_16x16x32_bf16 v[90:93], v[160:163], v[210:213], v[90:93]
	v_mfma_f32_16x16x32_bf16 v[78:81], v[152:155], v[218:221], v[78:81]
	v_mfma_f32_16x16x32_bf16 v[74:77], v[160:163], v[218:221], v[74:77]
	v_mfma_f32_16x16x32_bf16 v[118:121], v[164:167], v[180:183], v[118:121]
	v_mfma_f32_16x16x32_bf16 v[114:117], v[172:175], v[180:183], v[114:117]
	v_mfma_f32_16x16x32_bf16 v[102:105], v[164:167], v[188:191], v[102:105]
	v_mfma_f32_16x16x32_bf16 v[98:101], v[172:175], v[188:191], v[98:101]
	v_mfma_f32_16x16x32_bf16 v[86:89], v[164:167], v[206:209], v[86:89]
	v_mfma_f32_16x16x32_bf16 v[82:85], v[172:175], v[206:209], v[82:85]
	v_mfma_f32_16x16x32_bf16 v[70:73], v[164:167], v[214:217], v[70:73]
	v_mfma_f32_16x16x32_bf16 v[66:69], v[172:175], v[214:217], v[66:69]
	v_mfma_f32_16x16x32_bf16 v[118:121], v[168:171], v[184:187], v[118:121]
	v_mfma_f32_16x16x32_bf16 v[114:117], v[176:179], v[184:187], v[114:117]
	v_mfma_f32_16x16x32_bf16 v[102:105], v[168:171], v[192:195], v[102:105]
	v_mfma_f32_16x16x32_bf16 v[98:101], v[176:179], v[192:195], v[98:101]
	v_mfma_f32_16x16x32_bf16 v[86:89], v[168:171], v[210:213], v[86:89]
	v_mfma_f32_16x16x32_bf16 v[82:85], v[176:179], v[210:213], v[82:85]
	v_mfma_f32_16x16x32_bf16 v[70:73], v[168:171], v[218:221], v[70:73]
	v_mfma_f32_16x16x32_bf16 v[66:69], v[176:179], v[218:221], v[66:69]
	s_setprio 0
	s_barrier
	s_add_u32 s20, s20, 0x80080
	s_addc_u32 s21, s21, 0
	s_add_u32 s46, s46, 0xfff80080
	s_addc_u32 s47, s47, -1
	s_add_i32 s2, s2, s28
	s_mov_b32 m0, s2
	ds_read_b128 v[180:183], v151 offset:49152
	ds_read_b128 v[184:187], v151 offset:50176
	global_load_lds_dwordx4 v0, s[46:47]
	s_add_i32 m0, s2, 0x2000
	s_add_i32 s2, s45, s28
	ds_read_b128 v[188:191], v151 offset:51200
	ds_read_b128 v[192:195], v151 offset:52224
	global_load_lds_dwordx4 v130, s[46:47]
	s_mov_b32 m0, s2
	ds_read_b128 v[206:209], v151 offset:53248
	ds_read_b128 v[210:213], v151 offset:54272
	global_load_lds_dwordx4 v0, s[20:21]
	s_add_i32 m0, s2, 0x2000
	ds_read_b128 v[214:217], v151 offset:55296
	ds_read_b128 v[218:221], v151 offset:56320
	global_load_lds_dwordx4 v130, s[20:21]
	s_waitcnt vmcnt(6)
	s_waitcnt lgkmcnt(0)
	s_barrier
	s_waitcnt lgkmcnt(0)
	v_mfma_f32_16x16x32_bf16 v[62:65], v[140:143], v[180:183], v[62:65]
	v_mfma_f32_16x16x32_bf16 v[58:61], v[156:159], v[180:183], v[58:61]
	v_mfma_f32_16x16x32_bf16 v[46:49], v[140:143], v[188:191], v[46:49]
	v_mfma_f32_16x16x32_bf16 v[42:45], v[156:159], v[188:191], v[42:45]
	v_mfma_f32_16x16x32_bf16 v[30:33], v[140:143], v[206:209], v[30:33]
	v_mfma_f32_16x16x32_bf16 v[26:29], v[156:159], v[206:209], v[26:29]
	v_mfma_f32_16x16x32_bf16 v[14:17], v[140:143], v[214:217], v[14:17]
	v_mfma_f32_16x16x32_bf16 v[10:13], v[156:159], v[214:217], v[10:13]
	v_mfma_f32_16x16x32_bf16 v[62:65], v[152:155], v[184:187], v[62:65]
	v_mfma_f32_16x16x32_bf16 v[58:61], v[160:163], v[184:187], v[58:61]
	v_mfma_f32_16x16x32_bf16 v[46:49], v[152:155], v[192:195], v[46:49]
	v_mfma_f32_16x16x32_bf16 v[42:45], v[160:163], v[192:195], v[42:45]
	s_setprio 1
	v_mfma_f32_16x16x32_bf16 v[30:33], v[152:155], v[210:213], v[30:33]
	v_mfma_f32_16x16x32_bf16 v[26:29], v[160:163], v[210:213], v[26:29]
	v_mfma_f32_16x16x32_bf16 v[14:17], v[152:155], v[218:221], v[14:17]
	v_mfma_f32_16x16x32_bf16 v[10:13], v[160:163], v[218:221], v[10:13]
	v_mfma_f32_16x16x32_bf16 v[54:57], v[164:167], v[180:183], v[54:57]
	v_mfma_f32_16x16x32_bf16 v[50:53], v[172:175], v[180:183], v[50:53]
	v_mfma_f32_16x16x32_bf16 v[38:41], v[164:167], v[188:191], v[38:41]
	v_mfma_f32_16x16x32_bf16 v[34:37], v[172:175], v[188:191], v[34:37]
	v_mfma_f32_16x16x32_bf16 v[22:25], v[164:167], v[206:209], v[22:25]
	v_mfma_f32_16x16x32_bf16 v[18:21], v[172:175], v[206:209], v[18:21]
	v_mfma_f32_16x16x32_bf16 v[6:9], v[164:167], v[214:217], v[6:9]
	v_mfma_f32_16x16x32_bf16 v[2:5], v[172:175], v[214:217], v[2:5]
	v_mfma_f32_16x16x32_bf16 v[54:57], v[168:171], v[184:187], v[54:57]
	v_mfma_f32_16x16x32_bf16 v[50:53], v[176:179], v[184:187], v[50:53]
	v_mfma_f32_16x16x32_bf16 v[38:41], v[168:171], v[192:195], v[38:41]
	v_mfma_f32_16x16x32_bf16 v[34:37], v[176:179], v[192:195], v[34:37]
	v_mfma_f32_16x16x32_bf16 v[22:25], v[168:171], v[210:213], v[22:25]
	v_mfma_f32_16x16x32_bf16 v[18:21], v[176:179], v[210:213], v[18:21]
	v_mfma_f32_16x16x32_bf16 v[6:9], v[168:171], v[218:221], v[6:9]
	v_mfma_f32_16x16x32_bf16 v[2:5], v[176:179], v[218:221], v[2:5]
	s_setprio 0
	s_barrier
	s_add_i32 s44, s44, 2
	s_add_u32 s22, s22, 0x100
	s_addc_u32 s23, s23, 0
	s_add_u32 s42, s42, 0x100
	s_addc_u32 s43, s43, 0
	s_cmp_gt_u32 s44, 29
	s_cbranch_scc0 .LBB0_140
	s_nop 0
	s_nop 0
	s_nop 0
	s_nop 0
	s_nop 0
	s_nop 0
	s_nop 0
	s_nop 0
	s_and_b64 vcc, exec, s[10:11]
	s_cbranch_vccz .LBB0_143
	s_barrier

.LBB0_168:
	s_add_u32 s2, s26, 0xfff80080
	s_addc_u32 s24, s27, -1
	s_add_i32 s50, 0, 0x10000
	s_cmp_eq_u32 s49, 28
	s_cselect_b32 s29, s19, s24
	s_cselect_b32 s28, s44, s2
	v_add_u32_e32 v144, s50, v152
	s_cselect_b32 s25, s17, s47
	s_cselect_b32 s24, s45, s46
	s_add_u32 s100, s26, 0xfff80000
	s_addc_u32 s101, s27, -1
	s_add_i32 s2, 0, 0x14000
	s_mov_b32 m0, s39
	ds_read_b128 v[140:143], v144
	ds_read_b128 v[148:151], v144 offset:1024
	ds_read_b128 v[156:159], v144 offset:2048
	ds_read_b128 v[160:163], v144 offset:3072
	global_load_lds_dwordx4 v136, s[100:101]
	s_mov_b32 m0, s40
	v_add_u32_e32 v144, s2, v152
	ds_read_b128 v[164:167], v144
	ds_read_b128 v[168:171], v144 offset:1024
	ds_read_b128 v[172:175], v144 offset:2048
	ds_read_b128 v[176:179], v144 offset:3072
	global_load_lds_dwordx4 v138, s[100:101]
	s_add_i32 m0, s33, 0xc000
	ds_read_b128 v[180:183], v155
	ds_read_b128 v[184:187], v155 offset:1024
	ds_read_b128 v[188:191], v155 offset:2048
	ds_read_b128 v[192:195], v155 offset:3072
	global_load_lds_dwordx4 v136, s[26:27]
	s_add_i32 m0, s33, 0xe000
	ds_read_b128 v[206:209], v155 offset:4096
	ds_read_b128 v[210:213], v155 offset:5120
	ds_read_b128 v[214:217], v155 offset:6144
	ds_read_b128 v[218:221], v155 offset:7168
	global_load_lds_dwordx4 v138, s[26:27]
	s_waitcnt vmcnt(8)
	s_waitcnt lgkmcnt(0)
	s_barrier
	s_waitcnt lgkmcnt(0)
	v_mfma_f32_16x16x32_bf16 v[122:125], v[140:143], v[180:183], v[122:125]
	v_mfma_f32_16x16x32_bf16 v[114:117], v[156:159], v[180:183], v[114:117]
	v_mfma_f32_16x16x32_bf16 v[106:109], v[140:143], v[188:191], v[106:109]
	v_mfma_f32_16x16x32_bf16 v[98:101], v[156:159], v[188:191], v[98:101]
	v_mfma_f32_16x16x32_bf16 v[90:93], v[140:143], v[206:209], v[90:93]
	v_mfma_f32_16x16x32_bf16 v[82:85], v[156:159], v[206:209], v[82:85]
	v_mfma_f32_16x16x32_bf16 v[74:77], v[140:143], v[214:217], v[74:77]
	v_mfma_f32_16x16x32_bf16 v[66:69], v[156:159], v[214:217], v[66:69]
	v_mfma_f32_16x16x32_bf16 v[122:125], v[148:151], v[184:187], v[122:125]
	v_mfma_f32_16x16x32_bf16 v[114:117], v[160:163], v[184:187], v[114:117]
	v_mfma_f32_16x16x32_bf16 v[106:109], v[148:151], v[192:195], v[106:109]
	v_mfma_f32_16x16x32_bf16 v[98:101], v[160:163], v[192:195], v[98:101]
	s_setprio 1
	v_mfma_f32_16x16x32_bf16 v[90:93], v[148:151], v[210:213], v[90:93]
	v_mfma_f32_16x16x32_bf16 v[82:85], v[160:163], v[210:213], v[82:85]
	v_mfma_f32_16x16x32_bf16 v[74:77], v[148:151], v[218:221], v[74:77]
	v_mfma_f32_16x16x32_bf16 v[66:69], v[160:163], v[218:221], v[66:69]
	v_mfma_f32_16x16x32_bf16 v[126:129], v[164:167], v[180:183], v[126:129]
	v_mfma_f32_16x16x32_bf16 v[118:121], v[172:175], v[180:183], v[118:121]
	v_mfma_f32_16x16x32_bf16 v[110:113], v[164:167], v[188:191], v[110:113]
	v_mfma_f32_16x16x32_bf16 v[102:105], v[172:175], v[188:191], v[102:105]
	v_mfma_f32_16x16x32_bf16 v[94:97], v[164:167], v[206:209], v[94:97]
	v_mfma_f32_16x16x32_bf16 v[86:89], v[172:175], v[206:209], v[86:89]
	v_mfma_f32_16x16x32_bf16 v[78:81], v[164:167], v[214:217], v[78:81]
	v_mfma_f32_16x16x32_bf16 v[70:73], v[172:175], v[214:217], v[70:73]
	v_mfma_f32_16x16x32_bf16 v[126:129], v[168:171], v[184:187], v[126:129]
	v_mfma_f32_16x16x32_bf16 v[118:121], v[176:179], v[184:187], v[118:121]
	v_mfma_f32_16x16x32_bf16 v[110:113], v[168:171], v[192:195], v[110:113]
	v_mfma_f32_16x16x32_bf16 v[102:105], v[176:179], v[192:195], v[102:105]
	v_mfma_f32_16x16x32_bf16 v[94:97], v[168:171], v[210:213], v[94:97]
	v_mfma_f32_16x16x32_bf16 v[86:89], v[176:179], v[210:213], v[86:89]
	v_mfma_f32_16x16x32_bf16 v[78:81], v[168:171], v[218:221], v[78:81]
	v_mfma_f32_16x16x32_bf16 v[70:73], v[176:179], v[218:221], v[70:73]
	s_setprio 0
	s_barrier
	s_add_u32 s52, s24, 0x80000
	s_addc_u32 s53, s25, 0
	s_add_i32 s50, s50, s35
	s_mov_b32 m0, s50
	ds_read_b128 v[180:183], v155 offset:16384
	ds_read_b128 v[184:187], v155 offset:17408
	global_load_lds_dwordx4 v0, s[24:25]
	s_add_i32 m0, s50, 0x2000
	s_add_i32 s2, s2, s35
	ds_read_b128 v[188:191], v155 offset:18432
	ds_read_b128 v[192:195], v155 offset:19456
	global_load_lds_dwordx4 v130, s[24:25]
	s_mov_b32 m0, s2
	ds_read_b128 v[206:209], v155 offset:20480
	ds_read_b128 v[210:213], v155 offset:21504
	global_load_lds_dwordx4 v0, s[52:53]
	s_add_i32 m0, s2, 0x2000
	ds_read_b128 v[214:217], v155 offset:22528
	ds_read_b128 v[218:221], v155 offset:23552
	global_load_lds_dwordx4 v130, s[52:53]
	s_waitcnt vmcnt(6)
	s_waitcnt lgkmcnt(0)
	s_barrier
	s_waitcnt lgkmcnt(0)
	v_mfma_f32_16x16x32_bf16 v[58:61], v[140:143], v[180:183], v[58:61]
	v_mfma_f32_16x16x32_bf16 v[50:53], v[156:159], v[180:183], v[50:53]
	v_mfma_f32_16x16x32_bf16 v[42:45], v[140:143], v[188:191], v[42:45]
	v_mfma_f32_16x16x32_bf16 v[34:37], v[156:159], v[188:191], v[34:37]
	v_mfma_f32_16x16x32_bf16 v[26:29], v[140:143], v[206:209], v[26:29]
	v_mfma_f32_16x16x32_bf16 v[18:21], v[156:159], v[206:209], v[18:21]
	v_mfma_f32_16x16x32_bf16 v[10:13], v[140:143], v[214:217], v[10:13]
	v_mfma_f32_16x16x32_bf16 v[6:9], v[156:159], v[214:217], v[6:9]
	v_mfma_f32_16x16x32_bf16 v[58:61], v[148:151], v[184:187], v[58:61]
	v_mfma_f32_16x16x32_bf16 v[50:53], v[160:163], v[184:187], v[50:53]
	v_mfma_f32_16x16x32_bf16 v[42:45], v[148:151], v[192:195], v[42:45]
	v_mfma_f32_16x16x32_bf16 v[34:37], v[160:163], v[192:195], v[34:37]
	s_setprio 1
	v_mfma_f32_16x16x32_bf16 v[26:29], v[148:151], v[210:213], v[26:29]
	v_mfma_f32_16x16x32_bf16 v[18:21], v[160:163], v[210:213], v[18:21]
	v_mfma_f32_16x16x32_bf16 v[10:13], v[148:151], v[218:221], v[10:13]
	v_mfma_f32_16x16x32_bf16 v[6:9], v[160:163], v[218:221], v[6:9]
	v_mfma_f32_16x16x32_bf16 v[62:65], v[164:167], v[180:183], v[62:65]
	v_mfma_f32_16x16x32_bf16 v[54:57], v[172:175], v[180:183], v[54:57]
	v_mfma_f32_16x16x32_bf16 v[46:49], v[164:167], v[188:191], v[46:49]
	v_mfma_f32_16x16x32_bf16 v[38:41], v[172:175], v[188:191], v[38:41]
	v_mfma_f32_16x16x32_bf16 v[30:33], v[164:167], v[206:209], v[30:33]
	v_mfma_f32_16x16x32_bf16 v[22:25], v[172:175], v[206:209], v[22:25]
	v_mfma_f32_16x16x32_bf16 v[14:17], v[164:167], v[214:217], v[14:17]
	v_mfma_f32_16x16x32_bf16 v[2:5], v[172:175], v[214:217], v[2:5]
	v_mfma_f32_16x16x32_bf16 v[62:65], v[168:171], v[184:187], v[62:65]
	v_mfma_f32_16x16x32_bf16 v[54:57], v[176:179], v[184:187], v[54:57]
	v_mfma_f32_16x16x32_bf16 v[46:49], v[168:171], v[192:195], v[46:49]
	v_mfma_f32_16x16x32_bf16 v[38:41], v[176:179], v[192:195], v[38:41]
	v_mfma_f32_16x16x32_bf16 v[30:33], v[168:171], v[210:213], v[30:33]
	v_mfma_f32_16x16x32_bf16 v[22:25], v[176:179], v[210:213], v[22:25]
	v_mfma_f32_16x16x32_bf16 v[14:17], v[168:171], v[218:221], v[14:17]
	v_mfma_f32_16x16x32_bf16 v[2:5], v[176:179], v[218:221], v[2:5]
	s_setprio 0
	s_barrier
	s_add_u32 s28, s28, 0x80000
	s_addc_u32 s29, s29, 0
	s_add_u32 s100, s28, 0xfff80000
	s_addc_u32 s101, s29, -1
	s_add_i32 s2, 0, 0x18000
	s_add_i32 s50, 0, 0x1c000
	v_add_u32_e32 v160, s2, v152
	v_add_u32_e32 v176, s50, v152
	s_mov_b32 m0, s33
	ds_read_b128 v[140:143], v160
	ds_read_b128 v[148:151], v160 offset:1024
	ds_read_b128 v[156:159], v160 offset:2048
	ds_read_b128 v[160:163], v160 offset:3072
	global_load_lds_dwordx4 v134, s[100:101]
	s_mov_b32 m0, s36
	ds_read_b128 v[164:167], v176
	ds_read_b128 v[168:171], v176 offset:1024
	ds_read_b128 v[172:175], v176 offset:2048
	ds_read_b128 v[176:179], v176 offset:3072
	global_load_lds_dwordx4 v132, s[100:101]
	s_mov_b32 m0, s37
	ds_read_b128 v[180:183], v155 offset:32768
	ds_read_b128 v[184:187], v155 offset:33792
	ds_read_b128 v[188:191], v155 offset:34816
	ds_read_b128 v[192:195], v155 offset:35840
	global_load_lds_dwordx4 v134, s[28:29]
	s_mov_b32 m0, s38
	ds_read_b128 v[206:209], v155 offset:36864
	ds_read_b128 v[210:213], v155 offset:37888
	ds_read_b128 v[214:217], v155 offset:38912
	ds_read_b128 v[218:221], v155 offset:39936
	global_load_lds_dwordx4 v132, s[28:29]
	s_waitcnt vmcnt(8)
	s_waitcnt lgkmcnt(0)
	s_barrier
	s_waitcnt lgkmcnt(0)
	v_mfma_f32_16x16x32_bf16 v[122:125], v[140:143], v[180:183], v[122:125]
	v_mfma_f32_16x16x32_bf16 v[114:117], v[156:159], v[180:183], v[114:117]
	v_mfma_f32_16x16x32_bf16 v[106:109], v[140:143], v[188:191], v[106:109]
	v_mfma_f32_16x16x32_bf16 v[98:101], v[156:159], v[188:191], v[98:101]
	v_mfma_f32_16x16x32_bf16 v[90:93], v[140:143], v[206:209], v[90:93]
	v_mfma_f32_16x16x32_bf16 v[82:85], v[156:159], v[206:209], v[82:85]
	v_mfma_f32_16x16x32_bf16 v[74:77], v[140:143], v[214:217], v[74:77]
	v_mfma_f32_16x16x32_bf16 v[66:69], v[156:159], v[214:217], v[66:69]
	v_mfma_f32_16x16x32_bf16 v[122:125], v[148:151], v[184:187], v[122:125]
	v_mfma_f32_16x16x32_bf16 v[114:117], v[160:163], v[184:187], v[114:117]
	v_mfma_f32_16x16x32_bf16 v[106:109], v[148:151], v[192:195], v[106:109]
	v_mfma_f32_16x16x32_bf16 v[98:101], v[160:163], v[192:195], v[98:101]
	s_setprio 1
	v_mfma_f32_16x16x32_bf16 v[90:93], v[148:151], v[210:213], v[90:93]
	v_mfma_f32_16x16x32_bf16 v[82:85], v[160:163], v[210:213], v[82:85]
	v_mfma_f32_16x16x32_bf16 v[74:77], v[148:151], v[218:221], v[74:77]
	v_mfma_f32_16x16x32_bf16 v[66:69], v[160:163], v[218:221], v[66:69]
	v_mfma_f32_16x16x32_bf16 v[126:129], v[164:167], v[180:183], v[126:129]
	v_mfma_f32_16x16x32_bf16 v[118:121], v[172:175], v[180:183], v[118:121]
	v_mfma_f32_16x16x32_bf16 v[110:113], v[164:167], v[188:191], v[110:113]
	v_mfma_f32_16x16x32_bf16 v[102:105], v[172:175], v[188:191], v[102:105]
	v_mfma_f32_16x16x32_bf16 v[94:97], v[164:167], v[206:209], v[94:97]
	v_mfma_f32_16x16x32_bf16 v[86:89], v[172:175], v[206:209], v[86:89]
	v_mfma_f32_16x16x32_bf16 v[78:81], v[164:167], v[214:217], v[78:81]
	v_mfma_f32_16x16x32_bf16 v[70:73], v[172:175], v[214:217], v[70:73]
	v_mfma_f32_16x16x32_bf16 v[126:129], v[168:171], v[184:187], v[126:129]
	v_mfma_f32_16x16x32_bf16 v[118:121], v[176:179], v[184:187], v[118:121]
	v_mfma_f32_16x16x32_bf16 v[110:113], v[168:171], v[192:195], v[110:113]
	v_mfma_f32_16x16x32_bf16 v[102:105], v[176:179], v[192:195], v[102:105]
	v_mfma_f32_16x16x32_bf16 v[94:97], v[168:171], v[210:213], v[94:97]
	v_mfma_f32_16x16x32_bf16 v[86:89], v[176:179], v[210:213], v[86:89]
	v_mfma_f32_16x16x32_bf16 v[78:81], v[168:171], v[218:221], v[78:81]
	v_mfma_f32_16x16x32_bf16 v[70:73], v[176:179], v[218:221], v[70:73]
	s_setprio 0
	s_barrier
	s_add_u32 s24, s24, 0x80080
	s_addc_u32 s25, s25, 0
	s_add_u32 s52, s52, 0xfff80080
	s_addc_u32 s53, s53, -1
	s_add_i32 s2, s2, s35
	s_mov_b32 m0, s2
	ds_read_b128 v[180:183], v155 offset:49152
	ds_read_b128 v[184:187], v155 offset:50176
	global_load_lds_dwordx4 v0, s[52:53]
	s_add_i32 m0, s2, 0x2000
	s_add_i32 s2, s50, s35
	ds_read_b128 v[188:191], v155 offset:51200
	ds_read_b128 v[192:195], v155 offset:52224
	global_load_lds_dwordx4 v130, s[52:53]
	s_mov_b32 m0, s2
	ds_read_b128 v[206:209], v155 offset:53248
	ds_read_b128 v[210:213], v155 offset:54272
	global_load_lds_dwordx4 v0, s[24:25]
	s_add_i32 m0, s2, 0x2000
	ds_read_b128 v[214:217], v155 offset:55296
	ds_read_b128 v[218:221], v155 offset:56320
	global_load_lds_dwordx4 v130, s[24:25]
	s_waitcnt vmcnt(6)
	s_waitcnt lgkmcnt(0)
	s_barrier
	s_waitcnt lgkmcnt(0)
	v_mfma_f32_16x16x32_bf16 v[58:61], v[140:143], v[180:183], v[58:61]
	v_mfma_f32_16x16x32_bf16 v[50:53], v[156:159], v[180:183], v[50:53]
	v_mfma_f32_16x16x32_bf16 v[42:45], v[140:143], v[188:191], v[42:45]
	v_mfma_f32_16x16x32_bf16 v[34:37], v[156:159], v[188:191], v[34:37]
	v_mfma_f32_16x16x32_bf16 v[26:29], v[140:143], v[206:209], v[26:29]
	v_mfma_f32_16x16x32_bf16 v[18:21], v[156:159], v[206:209], v[18:21]
	v_mfma_f32_16x16x32_bf16 v[10:13], v[140:143], v[214:217], v[10:13]
	v_mfma_f32_16x16x32_bf16 v[6:9], v[156:159], v[214:217], v[6:9]
	v_mfma_f32_16x16x32_bf16 v[58:61], v[148:151], v[184:187], v[58:61]
	v_mfma_f32_16x16x32_bf16 v[50:53], v[160:163], v[184:187], v[50:53]
	v_mfma_f32_16x16x32_bf16 v[42:45], v[148:151], v[192:195], v[42:45]
	v_mfma_f32_16x16x32_bf16 v[34:37], v[160:163], v[192:195], v[34:37]
	s_setprio 1
	v_mfma_f32_16x16x32_bf16 v[26:29], v[148:151], v[210:213], v[26:29]
	v_mfma_f32_16x16x32_bf16 v[18:21], v[160:163], v[210:213], v[18:21]
	v_mfma_f32_16x16x32_bf16 v[10:13], v[148:151], v[218:221], v[10:13]
	v_mfma_f32_16x16x32_bf16 v[6:9], v[160:163], v[218:221], v[6:9]
	v_mfma_f32_16x16x32_bf16 v[62:65], v[164:167], v[180:183], v[62:65]
	v_mfma_f32_16x16x32_bf16 v[54:57], v[172:175], v[180:183], v[54:57]
	v_mfma_f32_16x16x32_bf16 v[46:49], v[164:167], v[188:191], v[46:49]
	v_mfma_f32_16x16x32_bf16 v[38:41], v[172:175], v[188:191], v[38:41]
	v_mfma_f32_16x16x32_bf16 v[30:33], v[164:167], v[206:209], v[30:33]
	v_mfma_f32_16x16x32_bf16 v[22:25], v[172:175], v[206:209], v[22:25]
	v_mfma_f32_16x16x32_bf16 v[14:17], v[164:167], v[214:217], v[14:17]
	v_mfma_f32_16x16x32_bf16 v[2:5], v[172:175], v[214:217], v[2:5]
	v_mfma_f32_16x16x32_bf16 v[62:65], v[168:171], v[184:187], v[62:65]
	v_mfma_f32_16x16x32_bf16 v[54:57], v[176:179], v[184:187], v[54:57]
	v_mfma_f32_16x16x32_bf16 v[46:49], v[168:171], v[192:195], v[46:49]
	v_mfma_f32_16x16x32_bf16 v[38:41], v[176:179], v[192:195], v[38:41]
	v_mfma_f32_16x16x32_bf16 v[30:33], v[168:171], v[210:213], v[30:33]
	v_mfma_f32_16x16x32_bf16 v[22:25], v[176:179], v[210:213], v[22:25]
	v_mfma_f32_16x16x32_bf16 v[14:17], v[168:171], v[218:221], v[14:17]
	v_mfma_f32_16x16x32_bf16 v[2:5], v[176:179], v[218:221], v[2:5]
	s_setprio 0
	s_barrier
	s_add_i32 s49, s49, 2
	s_add_u32 s26, s26, 0x100
	s_addc_u32 s27, s27, 0
	s_add_u32 s46, s46, 0x100
	s_addc_u32 s47, s47, 0
	s_cmp_gt_u32 s49, 29
	s_cbranch_scc0 .LBB0_168
	s_nop 0
	s_nop 0
	s_nop 0
	s_nop 0
	s_nop 0
	s_nop 0
	s_nop 0
	s_nop 0
	s_and_b64 vcc, exec, s[14:15]
	s_cbranch_vccz .LBB0_171
	s_barrier

.LBB0_281:
	s_add_u32 s20, s18, 0x100
	s_addc_u32 s21, s19, 0
	s_add_i32 s2, 0, 0x10000
	s_cmpk_eq_i32 s42, 0x52
	s_cselect_b32 s25, s11, s21
	s_cselect_b32 s24, s10, s20
	s_cselect_b32 s23, s17, s41
	s_cselect_b32 s22, s16, s40
	s_add_u32 s100, s18, 0xffea8000
	s_addc_u32 s101, s19, -1
	s_add_i32 s43, 0, 0x14000
	v_add_u32_e32 v142, s2, v226
	v_add_u32_e32 v160, s43, v226
	s_mov_b32 m0, s36
	ds_read_b128 v[126:129], v142
	ds_read_b128 v[134:137], v142 offset:1024
	ds_read_b128 v[138:141], v142 offset:2048
	ds_read_b128 v[142:145], v142 offset:3072
	global_load_lds_dwordx4 v194, s[100:101]
	s_mov_b32 m0, s37
	ds_read_b128 v[148:151], v160
	ds_read_b128 v[152:155], v160 offset:1024
	ds_read_b128 v[156:159], v160 offset:2048
	ds_read_b128 v[160:163], v160 offset:3072
	global_load_lds_dwordx4 v206, s[100:101]
	s_add_i32 m0, s26, 0xc000
	ds_read_b128 v[164:167], v228
	ds_read_b128 v[168:171], v228 offset:1024
	ds_read_b128 v[172:175], v228 offset:2048
	ds_read_b128 v[176:179], v228 offset:3072
	global_load_lds_dwordx4 v194, s[18:19]
	s_add_i32 m0, s26, 0xe000
	ds_read_b128 v[180:183], v228 offset:4096
	ds_read_b128 v[184:187], v228 offset:5120
	ds_read_b128 v[208:211], v228 offset:6144
	ds_read_b128 v[212:215], v228 offset:7168
	global_load_lds_dwordx4 v206, s[18:19]
	s_waitcnt vmcnt(8)
	s_waitcnt lgkmcnt(0)
	s_barrier
	s_waitcnt lgkmcnt(0)
	v_mfma_f32_16x16x32_bf16 v[130:133], v[126:129], v[164:167], v[130:133]
	v_mfma_f32_16x16x32_bf16 v[122:125], v[138:141], v[164:167], v[122:125]
	v_mfma_f32_16x16x32_bf16 v[110:113], v[126:129], v[172:175], v[110:113]
	v_mfma_f32_16x16x32_bf16 v[106:109], v[138:141], v[172:175], v[106:109]
	v_mfma_f32_16x16x32_bf16 v[94:97], v[126:129], v[180:183], v[94:97]
	v_mfma_f32_16x16x32_bf16 v[90:93], v[138:141], v[180:183], v[90:93]
	v_mfma_f32_16x16x32_bf16 v[78:81], v[126:129], v[208:211], v[78:81]
	v_mfma_f32_16x16x32_bf16 v[74:77], v[138:141], v[208:211], v[74:77]
	v_mfma_f32_16x16x32_bf16 v[130:133], v[134:137], v[168:171], v[130:133]
	v_mfma_f32_16x16x32_bf16 v[122:125], v[142:145], v[168:171], v[122:125]
	v_mfma_f32_16x16x32_bf16 v[110:113], v[134:137], v[176:179], v[110:113]
	v_mfma_f32_16x16x32_bf16 v[106:109], v[142:145], v[176:179], v[106:109]
	s_setprio 1
	v_mfma_f32_16x16x32_bf16 v[94:97], v[134:137], v[184:187], v[94:97]
	v_mfma_f32_16x16x32_bf16 v[90:93], v[142:145], v[184:187], v[90:93]
	v_mfma_f32_16x16x32_bf16 v[78:81], v[134:137], v[212:215], v[78:81]
	v_mfma_f32_16x16x32_bf16 v[74:77], v[142:145], v[212:215], v[74:77]
	v_mfma_f32_16x16x32_bf16 v[118:121], v[148:151], v[164:167], v[118:121]
	v_mfma_f32_16x16x32_bf16 v[114:117], v[156:159], v[164:167], v[114:117]
	v_mfma_f32_16x16x32_bf16 v[102:105], v[148:151], v[172:175], v[102:105]
	v_mfma_f32_16x16x32_bf16 v[98:101], v[156:159], v[172:175], v[98:101]
	v_mfma_f32_16x16x32_bf16 v[86:89], v[148:151], v[180:183], v[86:89]
	v_mfma_f32_16x16x32_bf16 v[82:85], v[156:159], v[180:183], v[82:85]
	v_mfma_f32_16x16x32_bf16 v[70:73], v[148:151], v[208:211], v[70:73]
	v_mfma_f32_16x16x32_bf16 v[66:69], v[156:159], v[208:211], v[66:69]
	v_mfma_f32_16x16x32_bf16 v[118:121], v[152:155], v[168:171], v[118:121]
	v_mfma_f32_16x16x32_bf16 v[114:117], v[160:163], v[168:171], v[114:117]
	v_mfma_f32_16x16x32_bf16 v[102:105], v[152:155], v[176:179], v[102:105]
	v_mfma_f32_16x16x32_bf16 v[98:101], v[160:163], v[176:179], v[98:101]
	v_mfma_f32_16x16x32_bf16 v[86:89], v[152:155], v[184:187], v[86:89]
	v_mfma_f32_16x16x32_bf16 v[82:85], v[160:163], v[184:187], v[82:85]
	v_mfma_f32_16x16x32_bf16 v[70:73], v[152:155], v[212:215], v[70:73]
	v_mfma_f32_16x16x32_bf16 v[66:69], v[160:163], v[212:215], v[66:69]
	s_setprio 0
	s_barrier
	s_add_u32 s18, s22, 0x158000
	s_addc_u32 s19, s23, 0
	s_add_i32 s2, s2, s1
	s_mov_b32 m0, s2
	ds_read_b128 v[164:167], v228 offset:16384
	ds_read_b128 v[168:171], v228 offset:17408
	global_load_lds_dwordx4 v0, s[22:23]
	s_add_i32 m0, s2, 0x2000
	s_add_i32 s2, s43, s1
	ds_read_b128 v[172:175], v228 offset:18432
	ds_read_b128 v[176:179], v228 offset:19456
	global_load_lds_dwordx4 v188, s[22:23]
	s_mov_b32 m0, s2
	ds_read_b128 v[180:183], v228 offset:20480
	ds_read_b128 v[184:187], v228 offset:21504
	global_load_lds_dwordx4 v0, s[18:19]
	s_add_i32 m0, s2, 0x2000
	ds_read_b128 v[208:211], v228 offset:22528
	ds_read_b128 v[212:215], v228 offset:23552
	global_load_lds_dwordx4 v188, s[18:19]
	s_waitcnt vmcnt(6)
	s_waitcnt lgkmcnt(0)
	s_barrier
	s_waitcnt lgkmcnt(0)
	v_mfma_f32_16x16x32_bf16 v[62:65], v[126:129], v[164:167], v[62:65]
	v_mfma_f32_16x16x32_bf16 v[58:61], v[138:141], v[164:167], v[58:61]
	v_mfma_f32_16x16x32_bf16 v[46:49], v[126:129], v[172:175], v[46:49]
	v_mfma_f32_16x16x32_bf16 v[42:45], v[138:141], v[172:175], v[42:45]
	v_mfma_f32_16x16x32_bf16 v[30:33], v[126:129], v[180:183], v[30:33]
	v_mfma_f32_16x16x32_bf16 v[26:29], v[138:141], v[180:183], v[26:29]
	v_mfma_f32_16x16x32_bf16 v[14:17], v[126:129], v[208:211], v[14:17]
	v_mfma_f32_16x16x32_bf16 v[10:13], v[138:141], v[208:211], v[10:13]
	v_mfma_f32_16x16x32_bf16 v[62:65], v[134:137], v[168:171], v[62:65]
	v_mfma_f32_16x16x32_bf16 v[58:61], v[142:145], v[168:171], v[58:61]
	v_mfma_f32_16x16x32_bf16 v[46:49], v[134:137], v[176:179], v[46:49]
	v_mfma_f32_16x16x32_bf16 v[42:45], v[142:145], v[176:179], v[42:45]
	s_setprio 1
	v_mfma_f32_16x16x32_bf16 v[30:33], v[134:137], v[184:187], v[30:33]
	v_mfma_f32_16x16x32_bf16 v[26:29], v[142:145], v[184:187], v[26:29]
	v_mfma_f32_16x16x32_bf16 v[14:17], v[134:137], v[212:215], v[14:17]
	v_mfma_f32_16x16x32_bf16 v[10:13], v[142:145], v[212:215], v[10:13]
	v_mfma_f32_16x16x32_bf16 v[54:57], v[148:151], v[164:167], v[54:57]
	v_mfma_f32_16x16x32_bf16 v[50:53], v[156:159], v[164:167], v[50:53]
	v_mfma_f32_16x16x32_bf16 v[38:41], v[148:151], v[172:175], v[38:41]
	v_mfma_f32_16x16x32_bf16 v[34:37], v[156:159], v[172:175], v[34:37]
	v_mfma_f32_16x16x32_bf16 v[22:25], v[148:151], v[180:183], v[22:25]
	v_mfma_f32_16x16x32_bf16 v[18:21], v[156:159], v[180:183], v[18:21]
	v_mfma_f32_16x16x32_bf16 v[6:9], v[148:151], v[208:211], v[6:9]
	v_mfma_f32_16x16x32_bf16 v[2:5], v[156:159], v[208:211], v[2:5]
	v_mfma_f32_16x16x32_bf16 v[54:57], v[152:155], v[168:171], v[54:57]
	v_mfma_f32_16x16x32_bf16 v[50:53], v[160:163], v[168:171], v[50:53]
	v_mfma_f32_16x16x32_bf16 v[38:41], v[152:155], v[176:179], v[38:41]
	v_mfma_f32_16x16x32_bf16 v[34:37], v[160:163], v[176:179], v[34:37]
	v_mfma_f32_16x16x32_bf16 v[22:25], v[152:155], v[184:187], v[22:25]
	v_mfma_f32_16x16x32_bf16 v[18:21], v[160:163], v[184:187], v[18:21]
	v_mfma_f32_16x16x32_bf16 v[6:9], v[152:155], v[212:215], v[6:9]
	v_mfma_f32_16x16x32_bf16 v[2:5], v[160:163], v[212:215], v[2:5]
	s_setprio 0
	s_barrier
	s_add_u32 s18, s24, 0x158000
	s_addc_u32 s19, s25, 0
	s_add_i32 s2, 0, 0x18000
	s_add_i32 s43, 0, 0x1c000
	v_add_u32_e32 v142, s2, v226
	v_add_u32_e32 v160, s43, v226
	s_mov_b32 m0, s26
	ds_read_b128 v[126:129], v142
	ds_read_b128 v[134:137], v142 offset:1024
	ds_read_b128 v[138:141], v142 offset:2048
	ds_read_b128 v[142:145], v142 offset:3072
	global_load_lds_dwordx4 v192, s[24:25]
	s_mov_b32 m0, s27
	ds_read_b128 v[148:151], v160
	ds_read_b128 v[152:155], v160 offset:1024
	ds_read_b128 v[156:159], v160 offset:2048
	ds_read_b128 v[160:163], v160 offset:3072
	global_load_lds_dwordx4 v190, s[24:25]
	s_mov_b32 m0, s30
	ds_read_b128 v[164:167], v228 offset:32768
	ds_read_b128 v[168:171], v228 offset:33792
	ds_read_b128 v[172:175], v228 offset:34816
	ds_read_b128 v[176:179], v228 offset:35840
	global_load_lds_dwordx4 v192, s[18:19]
	s_mov_b32 m0, s31
	ds_read_b128 v[180:183], v228 offset:36864
	ds_read_b128 v[184:187], v228 offset:37888
	ds_read_b128 v[208:211], v228 offset:38912
	ds_read_b128 v[212:215], v228 offset:39936
	global_load_lds_dwordx4 v190, s[18:19]
	s_waitcnt vmcnt(8)
	s_waitcnt lgkmcnt(0)
	s_barrier
	s_waitcnt lgkmcnt(0)
	v_mfma_f32_16x16x32_bf16 v[130:133], v[126:129], v[164:167], v[130:133]
	v_mfma_f32_16x16x32_bf16 v[122:125], v[138:141], v[164:167], v[122:125]
	v_mfma_f32_16x16x32_bf16 v[110:113], v[126:129], v[172:175], v[110:113]
	v_mfma_f32_16x16x32_bf16 v[106:109], v[138:141], v[172:175], v[106:109]
	v_mfma_f32_16x16x32_bf16 v[94:97], v[126:129], v[180:183], v[94:97]
	v_mfma_f32_16x16x32_bf16 v[90:93], v[138:141], v[180:183], v[90:93]
	v_mfma_f32_16x16x32_bf16 v[78:81], v[126:129], v[208:211], v[78:81]
	v_mfma_f32_16x16x32_bf16 v[74:77], v[138:141], v[208:211], v[74:77]
	v_mfma_f32_16x16x32_bf16 v[130:133], v[134:137], v[168:171], v[130:133]
	v_mfma_f32_16x16x32_bf16 v[122:125], v[142:145], v[168:171], v[122:125]
	v_mfma_f32_16x16x32_bf16 v[110:113], v[134:137], v[176:179], v[110:113]
	v_mfma_f32_16x16x32_bf16 v[106:109], v[142:145], v[176:179], v[106:109]
	s_setprio 1
	v_mfma_f32_16x16x32_bf16 v[94:97], v[134:137], v[184:187], v[94:97]
	v_mfma_f32_16x16x32_bf16 v[90:93], v[142:145], v[184:187], v[90:93]
	v_mfma_f32_16x16x32_bf16 v[78:81], v[134:137], v[212:215], v[78:81]
	v_mfma_f32_16x16x32_bf16 v[74:77], v[142:145], v[212:215], v[74:77]
	v_mfma_f32_16x16x32_bf16 v[118:121], v[148:151], v[164:167], v[118:121]
	v_mfma_f32_16x16x32_bf16 v[114:117], v[156:159], v[164:167], v[114:117]
	v_mfma_f32_16x16x32_bf16 v[102:105], v[148:151], v[172:175], v[102:105]
	v_mfma_f32_16x16x32_bf16 v[98:101], v[156:159], v[172:175], v[98:101]
	v_mfma_f32_16x16x32_bf16 v[86:89], v[148:151], v[180:183], v[86:89]
	v_mfma_f32_16x16x32_bf16 v[82:85], v[156:159], v[180:183], v[82:85]
	v_mfma_f32_16x16x32_bf16 v[70:73], v[148:151], v[208:211], v[70:73]
	v_mfma_f32_16x16x32_bf16 v[66:69], v[156:159], v[208:211], v[66:69]
	v_mfma_f32_16x16x32_bf16 v[118:121], v[152:155], v[168:171], v[118:121]
	v_mfma_f32_16x16x32_bf16 v[114:117], v[160:163], v[168:171], v[114:117]
	v_mfma_f32_16x16x32_bf16 v[102:105], v[152:155], v[176:179], v[102:105]
	v_mfma_f32_16x16x32_bf16 v[98:101], v[160:163], v[176:179], v[98:101]
	v_mfma_f32_16x16x32_bf16 v[86:89], v[152:155], v[184:187], v[86:89]
	v_mfma_f32_16x16x32_bf16 v[82:85], v[160:163], v[184:187], v[82:85]
	v_mfma_f32_16x16x32_bf16 v[70:73], v[152:155], v[212:215], v[70:73]
	v_mfma_f32_16x16x32_bf16 v[66:69], v[160:163], v[212:215], v[66:69]
	s_setprio 0
	s_barrier
	s_add_u32 s18, s22, 0x158080
	s_addc_u32 s19, s23, 0
	s_add_u32 s22, s22, 0x80
	s_addc_u32 s23, s23, 0
	s_add_i32 s2, s2, s1
	s_mov_b32 m0, s2
	ds_read_b128 v[164:167], v228 offset:49152
	ds_read_b128 v[168:171], v228 offset:50176
	global_load_lds_dwordx4 v0, s[22:23]
	s_add_i32 m0, s2, 0x2000
	s_add_i32 s2, s43, s1
	ds_read_b128 v[172:175], v228 offset:51200
	ds_read_b128 v[176:179], v228 offset:52224
	global_load_lds_dwordx4 v188, s[22:23]
	s_mov_b32 m0, s2
	ds_read_b128 v[180:183], v228 offset:53248
	ds_read_b128 v[184:187], v228 offset:54272
	global_load_lds_dwordx4 v0, s[18:19]
	s_add_i32 m0, s2, 0x2000
	ds_read_b128 v[208:211], v228 offset:55296
	ds_read_b128 v[212:215], v228 offset:56320
	global_load_lds_dwordx4 v188, s[18:19]
	s_waitcnt vmcnt(6)
	s_waitcnt lgkmcnt(0)
	s_barrier
	s_waitcnt lgkmcnt(0)
	v_mfma_f32_16x16x32_bf16 v[62:65], v[126:129], v[164:167], v[62:65]
	v_mfma_f32_16x16x32_bf16 v[58:61], v[138:141], v[164:167], v[58:61]
	v_mfma_f32_16x16x32_bf16 v[46:49], v[126:129], v[172:175], v[46:49]
	v_mfma_f32_16x16x32_bf16 v[42:45], v[138:141], v[172:175], v[42:45]
	v_mfma_f32_16x16x32_bf16 v[30:33], v[126:129], v[180:183], v[30:33]
	v_mfma_f32_16x16x32_bf16 v[26:29], v[138:141], v[180:183], v[26:29]
	v_mfma_f32_16x16x32_bf16 v[14:17], v[126:129], v[208:211], v[14:17]
	v_mfma_f32_16x16x32_bf16 v[10:13], v[138:141], v[208:211], v[10:13]
	v_mfma_f32_16x16x32_bf16 v[62:65], v[134:137], v[168:171], v[62:65]
	v_mfma_f32_16x16x32_bf16 v[58:61], v[142:145], v[168:171], v[58:61]
	v_mfma_f32_16x16x32_bf16 v[46:49], v[134:137], v[176:179], v[46:49]
	v_mfma_f32_16x16x32_bf16 v[42:45], v[142:145], v[176:179], v[42:45]
	s_setprio 1
	v_mfma_f32_16x16x32_bf16 v[30:33], v[134:137], v[184:187], v[30:33]
	v_mfma_f32_16x16x32_bf16 v[26:29], v[142:145], v[184:187], v[26:29]
	v_mfma_f32_16x16x32_bf16 v[14:17], v[134:137], v[212:215], v[14:17]
	v_mfma_f32_16x16x32_bf16 v[10:13], v[142:145], v[212:215], v[10:13]
	v_mfma_f32_16x16x32_bf16 v[54:57], v[148:151], v[164:167], v[54:57]
	v_mfma_f32_16x16x32_bf16 v[50:53], v[156:159], v[164:167], v[50:53]
	v_mfma_f32_16x16x32_bf16 v[38:41], v[148:151], v[172:175], v[38:41]
	v_mfma_f32_16x16x32_bf16 v[34:37], v[156:159], v[172:175], v[34:37]
	v_mfma_f32_16x16x32_bf16 v[22:25], v[148:151], v[180:183], v[22:25]
	v_mfma_f32_16x16x32_bf16 v[18:21], v[156:159], v[180:183], v[18:21]
	v_mfma_f32_16x16x32_bf16 v[6:9], v[148:151], v[208:211], v[6:9]
	v_mfma_f32_16x16x32_bf16 v[2:5], v[156:159], v[208:211], v[2:5]
	v_mfma_f32_16x16x32_bf16 v[54:57], v[152:155], v[168:171], v[54:57]
	v_mfma_f32_16x16x32_bf16 v[50:53], v[160:163], v[168:171], v[50:53]
	v_mfma_f32_16x16x32_bf16 v[38:41], v[152:155], v[176:179], v[38:41]
	v_mfma_f32_16x16x32_bf16 v[34:37], v[160:163], v[176:179], v[34:37]
	v_mfma_f32_16x16x32_bf16 v[22:25], v[152:155], v[184:187], v[22:25]
	v_mfma_f32_16x16x32_bf16 v[18:21], v[160:163], v[184:187], v[18:21]
	v_mfma_f32_16x16x32_bf16 v[6:9], v[152:155], v[212:215], v[6:9]
	v_mfma_f32_16x16x32_bf16 v[2:5], v[160:163], v[212:215], v[2:5]
	s_setprio 0
	s_barrier
	s_add_i32 s42, s42, 2
	s_add_u32 s40, s40, 0x100
	s_addc_u32 s41, s41, 0
	s_cmpk_gt_u32 s42, 0x53
	s_mov_b64 s[18:19], s[20:21]
	s_cbranch_scc0 .LBB0_281
	s_nop 0
	s_nop 0
	s_nop 0
	s_nop 0
	s_nop 0
	s_nop 0
	s_nop 0
	s_nop 0
	s_nop 0
	s_nop 0
	s_nop 0
	v_lshl_or_b32 v210, s3, 8, v227
	v_lshl_add_u32 v224, s34, 8, v147
	v_ashrrev_i32_e32 v211, 31, v210
	v_lshlrev_b64 v[126:127], 1, v[210:211]
	v_ashrrev_i32_e32 v225, 31, v224
	v_lshl_add_u64 v[128:129], s[12:13], 0, v[126:127]
	v_lshlrev_b64 v[134:135], 12, v[224:225]
	v_lshl_add_u64 v[136:137], v[128:129], 0, v[134:135]
	global_load_dwordx4 v[240:243], v[136:137], off
	global_load_dwordx4 v[244:247], v[136:137], off offset:256
	v_or_b32_e32 v222, 16, v224
	v_or_b32_e32 v220, 32, v224
	v_or_b32_e32 v218, 48, v224
	v_add_u32_e32 v216, 0x80, v224
	v_add_u32_e32 v214, 0x90, v224
	v_add_u32_e32 v212, 0xa0, v224
	v_add_u32_e32 v208, 0xb0, v224
	v_ashrrev_i32_e32 v223, 31, v222
	v_ashrrev_i32_e32 v221, 31, v220
	v_ashrrev_i32_e32 v219, 31, v218
	v_ashrrev_i32_e32 v217, 31, v216
	v_ashrrev_i32_e32 v215, 31, v214
	v_ashrrev_i32_e32 v213, 31, v212
	v_ashrrev_i32_e32 v209, 31, v208
	v_lshlrev_b64 v[136:137], 12, v[222:223]
	v_lshlrev_b64 v[138:139], 12, v[220:221]
	v_lshlrev_b64 v[140:141], 12, v[218:219]
	v_lshlrev_b64 v[142:143], 12, v[216:217]
	v_lshlrev_b64 v[144:145], 12, v[214:215]
	v_lshlrev_b64 v[148:149], 12, v[212:213]
	v_lshlrev_b64 v[150:151], 12, v[208:209]
	v_lshl_add_u64 v[134:135], s[12:13], 0, v[134:135]
	v_lshl_add_u64 v[136:137], v[128:129], 0, v[136:137]
	v_lshl_add_u64 v[138:139], v[128:129], 0, v[138:139]
	v_lshl_add_u64 v[140:141], v[128:129], 0, v[140:141]
	v_lshl_add_u64 v[142:143], v[128:129], 0, v[142:143]
	v_lshl_add_u64 v[144:145], v[128:129], 0, v[144:145]
	v_lshl_add_u64 v[248:249], v[128:129], 0, v[148:149]
	v_lshl_add_u64 v[128:129], v[128:129], 0, v[150:151]
	v_lshl_add_u64 v[250:251], v[134:135], 0, v[126:127]
	global_load_dwordx4 v[184:187], v[136:137], off
	global_load_dwordx4 v[180:183], v[136:137], off offset:256
	global_load_dwordx4 v[176:179], v[138:139], off
	global_load_dwordx4 v[172:175], v[138:139], off offset:256
	global_load_dwordx4 v[168:171], v[140:141], off
	global_load_dwordx4 v[164:167], v[140:141], off offset:256
	global_load_dwordx4 v[160:163], v[142:143], off
	global_load_dwordx4 v[156:159], v[142:143], off offset:256
	global_load_dwordx4 v[152:155], v[144:145], off
	global_load_dwordx4 v[148:151], v[144:145], off offset:256
	s_nop 0
	global_load_dwordx4 v[142:145], v[248:249], off
	global_load_dwordx4 v[138:141], v[248:249], off offset:256
	global_load_dwordx4 v[134:137], v[128:129], off
	s_nop 0
	global_load_dwordx4 v[126:129], v[128:129], off offset:256
	s_lshl_b32 s18, s3, 2
	s_ashr_i32 s19, s18, 31
	s_waitcnt vmcnt(0)
	v_lshlrev_b32_e32 v248, 16, v240
	v_and_b32_e32 v249, 0xffff0000, v240
	v_lshlrev_b32_e32 v240, 16, v241
	v_and_b32_e32 v241, 0xffff0000, v241
	v_lshlrev_b32_e32 v252, 16, v242
	v_and_b32_e32 v253, 0xffff0000, v242
	v_lshlrev_b32_e32 v242, 16, v243
	v_and_b32_e32 v243, 0xffff0000, v243
	v_pk_fma_f32 v[132:133], v[132:133], 0.5, v[240:241] op_sel_hi:[1,0,1]
	v_pk_fma_f32 v[240:241], v[124:125], 0.5, v[242:243] op_sel_hi:[1,0,1]
	v_pk_fma_f32 v[124:125], v[122:123], 0.5, v[252:253] op_sel_hi:[1,0,1]
	v_pk_fma_f32 v[130:131], v[130:131], 0.5, v[248:249] op_sel_hi:[1,0,1]
	v_lshlrev_b32_e32 v236, 16, v244
	v_cvt_pk_bf16_f32 v122, v130, v131
	v_cvt_pk_bf16_f32 v123, v132, v133
	v_cvt_pk_bf16_f32 v124, v124, v125
	v_cvt_pk_bf16_f32 v125, v240, v241
	global_store_dwordx4 v[250:251], v[122:125], off
	v_lshlrev_b32_e32 v130, 16, v122
	v_lshlrev_b32_e32 v131, 16, v123
	v_and_b32_e32 v122, 0xffff0000, v122
	v_and_b32_e32 v123, 0xffff0000, v123
	v_lshlrev_b32_e32 v132, 16, v124
	v_and_b32_e32 v124, 0xffff0000, v124
	v_lshlrev_b32_e32 v133, 16, v125
	v_and_b32_e32 v125, 0xffff0000, v125
	v_mul_f32_e32 v122, v122, v122
	v_mul_f32_e32 v123, v123, v123
	v_mul_f32_e32 v124, v124, v124
	v_mul_f32_e32 v125, v125, v125
	v_fmac_f32_e32 v122, v130, v130
	v_fmac_f32_e32 v123, v131, v131
	v_fmac_f32_e32 v124, v132, v132
	v_fmac_f32_e32 v125, v133, v133
	v_add_f32_e32 v122, v122, v123
	v_add_f32_e32 v123, v124, v125
	v_and_b32_e32 v237, 0xffff0000, v244
	v_add_f32_e32 v132, v122, v123
	v_lshlrev_b32_e32 v122, 16, v245
	v_and_b32_e32 v123, 0xffff0000, v245
	v_lshlrev_b32_e32 v124, 16, v246
	v_and_b32_e32 v125, 0xffff0000, v246
	v_lshlrev_b32_e32 v130, 16, v247
	v_and_b32_e32 v131, 0xffff0000, v247
	v_pk_fma_f32 v[120:121], v[120:121], 0.5, v[122:123] op_sel_hi:[1,0,1]
	v_pk_fma_f32 v[118:119], v[118:119], 0.5, v[236:237] op_sel_hi:[1,0,1]
	v_pk_fma_f32 v[122:123], v[116:117], 0.5, v[130:131] op_sel_hi:[1,0,1]
	v_pk_fma_f32 v[116:117], v[114:115], 0.5, v[124:125] op_sel_hi:[1,0,1]
	v_cvt_pk_bf16_f32 v114, v118, v119
	v_cvt_pk_bf16_f32 v115, v120, v121
	s_nop 0
	v_cvt_pk_bf16_f32 v116, v116, v117
	v_cvt_pk_bf16_f32 v117, v122, v123
	global_store_dwordx4 v[250:251], v[114:117], off offset:256
	v_lshlrev_b32_e32 v118, 16, v114
	v_lshlrev_b32_e32 v119, 16, v115
	v_and_b32_e32 v114, 0xffff0000, v114
	v_and_b32_e32 v115, 0xffff0000, v115
	v_mul_f32_e32 v114, v114, v114
	v_mul_f32_e32 v115, v115, v115
	v_lshlrev_b32_e32 v120, 16, v116
	v_and_b32_e32 v116, 0xffff0000, v116
	v_lshlrev_b32_e32 v121, 16, v117
	v_and_b32_e32 v117, 0xffff0000, v117
	v_fmac_f32_e32 v114, v118, v118
	v_fmac_f32_e32 v115, v119, v119
	v_add_f32_e32 v114, v114, v115
	v_mul_f32_e32 v115, v116, v116
	v_mul_f32_e32 v116, v117, v117
	v_fmac_f32_e32 v115, v120, v120
	v_fmac_f32_e32 v116, v121, v121
	v_add_f32_e32 v115, v115, v116
	v_add_f32_e32 v114, v114, v115
	s_mov_b32 s2, 0
	v_add_f32_e32 v114, v132, v114
	v_mbcnt_lo_u32_b32 v115, -1, s2
	v_mbcnt_hi_u32_b32 v115, -1, v115
	v_lshlrev_b32_e32 v115, 2, v115
	v_xor_b32_e32 v115, 64, v115
	ds_bpermute_b32 v115, v115, v114
	s_mov_b32 s2, 0
	s_waitcnt lgkmcnt(0)
	v_add_f32_e32 v114, v114, v115
	v_mbcnt_lo_u32_b32 v115, -1, s2
	v_mbcnt_hi_u32_b32 v115, -1, v115
	v_lshlrev_b32_e32 v115, 2, v115
	v_xor_b32_e32 v115, 0x80, v115
	ds_bpermute_b32 v115, v115, v114
	s_and_saveexec_b64 s[20:21], s[6:7]
	s_cbranch_execz .LBB0_284
	v_lshlrev_b64 v[116:117], 7, v[224:225]
	v_lshl_add_u64 v[116:117], s[14:15], 0, v[116:117]
	v_lshl_add_u64 v[116:117], s[18:19], 2, v[116:117]
	s_lshl_b32 s50, s35, 2
	v_lshl_add_u64 v[116:117], v[116:117], 0, s[50:51]
	s_waitcnt lgkmcnt(0)
	v_add_f32_e32 v114, v114, v115
	global_store_dword v[116:117], v114, off

.LBB0_322:
	s_add_u32 s22, s20, 0x100
	s_addc_u32 s23, s21, 0
	s_add_i32 s2, 0, 0x10000
	s_cmpk_eq_i32 s42, 0x52
	s_cselect_b32 s27, s9, s23
	s_cselect_b32 s26, s8, s22
	s_cselect_b32 s25, s19, s41
	s_cselect_b32 s24, s18, s40
	s_add_u32 s100, s20, 0xffea8000
	s_addc_u32 s101, s21, -1
	s_add_i32 s43, 0, 0x14000
	v_add_u32_e32 v142, s2, v240
	v_add_u32_e32 v160, s43, v240
	s_mov_b32 m0, s35
	ds_read_b128 v[130:133], v142
	ds_read_b128 v[134:137], v142 offset:1024
	ds_read_b128 v[138:141], v142 offset:2048
	ds_read_b128 v[142:145], v142 offset:3072
	global_load_lds_dwordx4 v208, s[100:101]
	s_mov_b32 m0, s36
	ds_read_b128 v[148:151], v160
	ds_read_b128 v[152:155], v160 offset:1024
	ds_read_b128 v[156:159], v160 offset:2048
	ds_read_b128 v[160:163], v160 offset:3072
	global_load_lds_dwordx4 v210, s[100:101]
	s_add_i32 m0, s1, 0xc000
	ds_read_b128 v[164:167], v242
	ds_read_b128 v[168:171], v242 offset:1024
	ds_read_b128 v[172:175], v242 offset:2048
	ds_read_b128 v[176:179], v242 offset:3072
	global_load_lds_dwordx4 v208, s[20:21]
	s_add_i32 m0, s1, 0xe000
	ds_read_b128 v[180:183], v242 offset:4096
	ds_read_b128 v[184:187], v242 offset:5120
	ds_read_b128 v[188:191], v242 offset:6144
	ds_read_b128 v[212:215], v242 offset:7168
	global_load_lds_dwordx4 v210, s[20:21]
	s_waitcnt vmcnt(8)
	s_waitcnt lgkmcnt(0)
	s_barrier
	s_waitcnt lgkmcnt(0)
	v_mfma_f32_16x16x32_bf16 v[126:129], v[130:133], v[164:167], v[126:129]
	v_mfma_f32_16x16x32_bf16 v[122:125], v[138:141], v[164:167], v[122:125]
	v_mfma_f32_16x16x32_bf16 v[110:113], v[130:133], v[172:175], v[110:113]
	v_mfma_f32_16x16x32_bf16 v[106:109], v[138:141], v[172:175], v[106:109]
	v_mfma_f32_16x16x32_bf16 v[94:97], v[130:133], v[180:183], v[94:97]
	v_mfma_f32_16x16x32_bf16 v[90:93], v[138:141], v[180:183], v[90:93]
	v_mfma_f32_16x16x32_bf16 v[78:81], v[130:133], v[188:191], v[78:81]
	v_mfma_f32_16x16x32_bf16 v[74:77], v[138:141], v[188:191], v[74:77]
	v_mfma_f32_16x16x32_bf16 v[126:129], v[134:137], v[168:171], v[126:129]
	v_mfma_f32_16x16x32_bf16 v[122:125], v[142:145], v[168:171], v[122:125]
	v_mfma_f32_16x16x32_bf16 v[110:113], v[134:137], v[176:179], v[110:113]
	v_mfma_f32_16x16x32_bf16 v[106:109], v[142:145], v[176:179], v[106:109]
	s_setprio 1
	v_mfma_f32_16x16x32_bf16 v[94:97], v[134:137], v[184:187], v[94:97]
	v_mfma_f32_16x16x32_bf16 v[90:93], v[142:145], v[184:187], v[90:93]
	v_mfma_f32_16x16x32_bf16 v[78:81], v[134:137], v[212:215], v[78:81]
	v_mfma_f32_16x16x32_bf16 v[74:77], v[142:145], v[212:215], v[74:77]
	v_mfma_f32_16x16x32_bf16 v[118:121], v[148:151], v[164:167], v[118:121]
	v_mfma_f32_16x16x32_bf16 v[114:117], v[156:159], v[164:167], v[114:117]
	v_mfma_f32_16x16x32_bf16 v[102:105], v[148:151], v[172:175], v[102:105]
	v_mfma_f32_16x16x32_bf16 v[98:101], v[156:159], v[172:175], v[98:101]
	v_mfma_f32_16x16x32_bf16 v[86:89], v[148:151], v[180:183], v[86:89]
	v_mfma_f32_16x16x32_bf16 v[82:85], v[156:159], v[180:183], v[82:85]
	v_mfma_f32_16x16x32_bf16 v[70:73], v[148:151], v[188:191], v[70:73]
	v_mfma_f32_16x16x32_bf16 v[66:69], v[156:159], v[188:191], v[66:69]
	v_mfma_f32_16x16x32_bf16 v[118:121], v[152:155], v[168:171], v[118:121]
	v_mfma_f32_16x16x32_bf16 v[114:117], v[160:163], v[168:171], v[114:117]
	v_mfma_f32_16x16x32_bf16 v[102:105], v[152:155], v[176:179], v[102:105]
	v_mfma_f32_16x16x32_bf16 v[98:101], v[160:163], v[176:179], v[98:101]
	v_mfma_f32_16x16x32_bf16 v[86:89], v[152:155], v[184:187], v[86:89]
	v_mfma_f32_16x16x32_bf16 v[82:85], v[160:163], v[184:187], v[82:85]
	v_mfma_f32_16x16x32_bf16 v[70:73], v[152:155], v[212:215], v[70:73]
	v_mfma_f32_16x16x32_bf16 v[66:69], v[160:163], v[212:215], v[66:69]
	s_setprio 0
	s_barrier
	s_add_u32 s20, s24, 0x158000
	s_addc_u32 s21, s25, 0
	s_add_i32 s2, s2, s0
	s_mov_b32 m0, s2
	ds_read_b128 v[164:167], v242 offset:16384
	ds_read_b128 v[168:171], v242 offset:17408
	global_load_lds_dwordx4 v0, s[24:25]
	s_add_i32 m0, s2, 0x2000
	s_add_i32 s2, s43, s0
	ds_read_b128 v[172:175], v242 offset:18432
	ds_read_b128 v[176:179], v242 offset:19456
	global_load_lds_dwordx4 v192, s[24:25]
	s_mov_b32 m0, s2
	ds_read_b128 v[180:183], v242 offset:20480
	ds_read_b128 v[184:187], v242 offset:21504
	global_load_lds_dwordx4 v0, s[20:21]
	s_add_i32 m0, s2, 0x2000
	ds_read_b128 v[188:191], v242 offset:22528
	ds_read_b128 v[212:215], v242 offset:23552
	global_load_lds_dwordx4 v192, s[20:21]
	s_waitcnt vmcnt(6)
	s_waitcnt lgkmcnt(0)
	s_barrier
	s_waitcnt lgkmcnt(0)
	v_mfma_f32_16x16x32_bf16 v[62:65], v[130:133], v[164:167], v[62:65]
	v_mfma_f32_16x16x32_bf16 v[58:61], v[138:141], v[164:167], v[58:61]
	v_mfma_f32_16x16x32_bf16 v[46:49], v[130:133], v[172:175], v[46:49]
	v_mfma_f32_16x16x32_bf16 v[42:45], v[138:141], v[172:175], v[42:45]
	v_mfma_f32_16x16x32_bf16 v[30:33], v[130:133], v[180:183], v[30:33]
	v_mfma_f32_16x16x32_bf16 v[26:29], v[138:141], v[180:183], v[26:29]
	v_mfma_f32_16x16x32_bf16 v[14:17], v[130:133], v[188:191], v[14:17]
	v_mfma_f32_16x16x32_bf16 v[10:13], v[138:141], v[188:191], v[10:13]
	v_mfma_f32_16x16x32_bf16 v[62:65], v[134:137], v[168:171], v[62:65]
	v_mfma_f32_16x16x32_bf16 v[58:61], v[142:145], v[168:171], v[58:61]
	v_mfma_f32_16x16x32_bf16 v[46:49], v[134:137], v[176:179], v[46:49]
	v_mfma_f32_16x16x32_bf16 v[42:45], v[142:145], v[176:179], v[42:45]
	s_setprio 1
	v_mfma_f32_16x16x32_bf16 v[30:33], v[134:137], v[184:187], v[30:33]
	v_mfma_f32_16x16x32_bf16 v[26:29], v[142:145], v[184:187], v[26:29]
	v_mfma_f32_16x16x32_bf16 v[14:17], v[134:137], v[212:215], v[14:17]
	v_mfma_f32_16x16x32_bf16 v[10:13], v[142:145], v[212:215], v[10:13]
	v_mfma_f32_16x16x32_bf16 v[54:57], v[148:151], v[164:167], v[54:57]
	v_mfma_f32_16x16x32_bf16 v[50:53], v[156:159], v[164:167], v[50:53]
	v_mfma_f32_16x16x32_bf16 v[38:41], v[148:151], v[172:175], v[38:41]
	v_mfma_f32_16x16x32_bf16 v[34:37], v[156:159], v[172:175], v[34:37]
	v_mfma_f32_16x16x32_bf16 v[22:25], v[148:151], v[180:183], v[22:25]
	v_mfma_f32_16x16x32_bf16 v[18:21], v[156:159], v[180:183], v[18:21]
	v_mfma_f32_16x16x32_bf16 v[6:9], v[148:151], v[188:191], v[6:9]
	v_mfma_f32_16x16x32_bf16 v[2:5], v[156:159], v[188:191], v[2:5]
	v_mfma_f32_16x16x32_bf16 v[54:57], v[152:155], v[168:171], v[54:57]
	v_mfma_f32_16x16x32_bf16 v[50:53], v[160:163], v[168:171], v[50:53]
	v_mfma_f32_16x16x32_bf16 v[38:41], v[152:155], v[176:179], v[38:41]
	v_mfma_f32_16x16x32_bf16 v[34:37], v[160:163], v[176:179], v[34:37]
	v_mfma_f32_16x16x32_bf16 v[22:25], v[152:155], v[184:187], v[22:25]
	v_mfma_f32_16x16x32_bf16 v[18:21], v[160:163], v[184:187], v[18:21]
	v_mfma_f32_16x16x32_bf16 v[6:9], v[152:155], v[212:215], v[6:9]
	v_mfma_f32_16x16x32_bf16 v[2:5], v[160:163], v[212:215], v[2:5]
	s_setprio 0
	s_barrier
	s_add_u32 s20, s26, 0x158000
	s_addc_u32 s21, s27, 0
	s_add_i32 s2, 0, 0x18000
	s_add_i32 s43, 0, 0x1c000
	v_add_u32_e32 v142, s2, v240
	v_add_u32_e32 v160, s43, v240
	s_mov_b32 m0, s1
	ds_read_b128 v[130:133], v142
	ds_read_b128 v[134:137], v142 offset:1024
	ds_read_b128 v[138:141], v142 offset:2048
	ds_read_b128 v[142:145], v142 offset:3072
	global_load_lds_dwordx4 v206, s[26:27]
	s_mov_b32 m0, s30
	ds_read_b128 v[148:151], v160
	ds_read_b128 v[152:155], v160 offset:1024
	ds_read_b128 v[156:159], v160 offset:2048
	ds_read_b128 v[160:163], v160 offset:3072
	global_load_lds_dwordx4 v194, s[26:27]
	s_mov_b32 m0, s31
	ds_read_b128 v[164:167], v242 offset:32768
	ds_read_b128 v[168:171], v242 offset:33792
	ds_read_b128 v[172:175], v242 offset:34816
	ds_read_b128 v[176:179], v242 offset:35840
	global_load_lds_dwordx4 v206, s[20:21]
	s_mov_b32 m0, s33
	ds_read_b128 v[180:183], v242 offset:36864
	ds_read_b128 v[184:187], v242 offset:37888
	ds_read_b128 v[188:191], v242 offset:38912
	ds_read_b128 v[212:215], v242 offset:39936
	global_load_lds_dwordx4 v194, s[20:21]
	s_waitcnt vmcnt(8)
	s_waitcnt lgkmcnt(0)
	s_barrier
	s_waitcnt lgkmcnt(0)
	v_mfma_f32_16x16x32_bf16 v[126:129], v[130:133], v[164:167], v[126:129]
	v_mfma_f32_16x16x32_bf16 v[122:125], v[138:141], v[164:167], v[122:125]
	v_mfma_f32_16x16x32_bf16 v[110:113], v[130:133], v[172:175], v[110:113]
	v_mfma_f32_16x16x32_bf16 v[106:109], v[138:141], v[172:175], v[106:109]
	v_mfma_f32_16x16x32_bf16 v[94:97], v[130:133], v[180:183], v[94:97]
	v_mfma_f32_16x16x32_bf16 v[90:93], v[138:141], v[180:183], v[90:93]
	v_mfma_f32_16x16x32_bf16 v[78:81], v[130:133], v[188:191], v[78:81]
	v_mfma_f32_16x16x32_bf16 v[74:77], v[138:141], v[188:191], v[74:77]
	v_mfma_f32_16x16x32_bf16 v[126:129], v[134:137], v[168:171], v[126:129]
	v_mfma_f32_16x16x32_bf16 v[122:125], v[142:145], v[168:171], v[122:125]
	v_mfma_f32_16x16x32_bf16 v[110:113], v[134:137], v[176:179], v[110:113]
	v_mfma_f32_16x16x32_bf16 v[106:109], v[142:145], v[176:179], v[106:109]
	s_setprio 1
	v_mfma_f32_16x16x32_bf16 v[94:97], v[134:137], v[184:187], v[94:97]
	v_mfma_f32_16x16x32_bf16 v[90:93], v[142:145], v[184:187], v[90:93]
	v_mfma_f32_16x16x32_bf16 v[78:81], v[134:137], v[212:215], v[78:81]
	v_mfma_f32_16x16x32_bf16 v[74:77], v[142:145], v[212:215], v[74:77]
	v_mfma_f32_16x16x32_bf16 v[118:121], v[148:151], v[164:167], v[118:121]
	v_mfma_f32_16x16x32_bf16 v[114:117], v[156:159], v[164:167], v[114:117]
	v_mfma_f32_16x16x32_bf16 v[102:105], v[148:151], v[172:175], v[102:105]
	v_mfma_f32_16x16x32_bf16 v[98:101], v[156:159], v[172:175], v[98:101]
	v_mfma_f32_16x16x32_bf16 v[86:89], v[148:151], v[180:183], v[86:89]
	v_mfma_f32_16x16x32_bf16 v[82:85], v[156:159], v[180:183], v[82:85]
	v_mfma_f32_16x16x32_bf16 v[70:73], v[148:151], v[188:191], v[70:73]
	v_mfma_f32_16x16x32_bf16 v[66:69], v[156:159], v[188:191], v[66:69]
	v_mfma_f32_16x16x32_bf16 v[118:121], v[152:155], v[168:171], v[118:121]
	v_mfma_f32_16x16x32_bf16 v[114:117], v[160:163], v[168:171], v[114:117]
	v_mfma_f32_16x16x32_bf16 v[102:105], v[152:155], v[176:179], v[102:105]
	v_mfma_f32_16x16x32_bf16 v[98:101], v[160:163], v[176:179], v[98:101]
	v_mfma_f32_16x16x32_bf16 v[86:89], v[152:155], v[184:187], v[86:89]
	v_mfma_f32_16x16x32_bf16 v[82:85], v[160:163], v[184:187], v[82:85]
	v_mfma_f32_16x16x32_bf16 v[70:73], v[152:155], v[212:215], v[70:73]
	v_mfma_f32_16x16x32_bf16 v[66:69], v[160:163], v[212:215], v[66:69]
	s_setprio 0
	s_barrier
	s_add_u32 s20, s24, 0x158080
	s_addc_u32 s21, s25, 0
	s_add_u32 s24, s24, 0x80
	s_addc_u32 s25, s25, 0
	s_add_i32 s2, s2, s0
	s_mov_b32 m0, s2
	ds_read_b128 v[164:167], v242 offset:49152
	ds_read_b128 v[168:171], v242 offset:50176
	global_load_lds_dwordx4 v0, s[24:25]
	s_add_i32 m0, s2, 0x2000
	s_add_i32 s2, s43, s0
	ds_read_b128 v[172:175], v242 offset:51200
	ds_read_b128 v[176:179], v242 offset:52224
	global_load_lds_dwordx4 v192, s[24:25]
	s_mov_b32 m0, s2
	ds_read_b128 v[180:183], v242 offset:53248
	ds_read_b128 v[184:187], v242 offset:54272
	global_load_lds_dwordx4 v0, s[20:21]
	s_add_i32 m0, s2, 0x2000
	ds_read_b128 v[188:191], v242 offset:55296
	ds_read_b128 v[212:215], v242 offset:56320
	global_load_lds_dwordx4 v192, s[20:21]
	s_waitcnt vmcnt(6)
	s_waitcnt lgkmcnt(0)
	s_barrier
	s_waitcnt lgkmcnt(0)
	v_mfma_f32_16x16x32_bf16 v[62:65], v[130:133], v[164:167], v[62:65]
	v_mfma_f32_16x16x32_bf16 v[58:61], v[138:141], v[164:167], v[58:61]
	v_mfma_f32_16x16x32_bf16 v[46:49], v[130:133], v[172:175], v[46:49]
	v_mfma_f32_16x16x32_bf16 v[42:45], v[138:141], v[172:175], v[42:45]
	v_mfma_f32_16x16x32_bf16 v[30:33], v[130:133], v[180:183], v[30:33]
	v_mfma_f32_16x16x32_bf16 v[26:29], v[138:141], v[180:183], v[26:29]
	v_mfma_f32_16x16x32_bf16 v[14:17], v[130:133], v[188:191], v[14:17]
	v_mfma_f32_16x16x32_bf16 v[10:13], v[138:141], v[188:191], v[10:13]
	v_mfma_f32_16x16x32_bf16 v[62:65], v[134:137], v[168:171], v[62:65]
	v_mfma_f32_16x16x32_bf16 v[58:61], v[142:145], v[168:171], v[58:61]
	v_mfma_f32_16x16x32_bf16 v[46:49], v[134:137], v[176:179], v[46:49]
	v_mfma_f32_16x16x32_bf16 v[42:45], v[142:145], v[176:179], v[42:45]
	s_setprio 1
	v_mfma_f32_16x16x32_bf16 v[30:33], v[134:137], v[184:187], v[30:33]
	v_mfma_f32_16x16x32_bf16 v[26:29], v[142:145], v[184:187], v[26:29]
	v_mfma_f32_16x16x32_bf16 v[14:17], v[134:137], v[212:215], v[14:17]
	v_mfma_f32_16x16x32_bf16 v[10:13], v[142:145], v[212:215], v[10:13]
	v_mfma_f32_16x16x32_bf16 v[54:57], v[148:151], v[164:167], v[54:57]
	v_mfma_f32_16x16x32_bf16 v[50:53], v[156:159], v[164:167], v[50:53]
	v_mfma_f32_16x16x32_bf16 v[38:41], v[148:151], v[172:175], v[38:41]
	v_mfma_f32_16x16x32_bf16 v[34:37], v[156:159], v[172:175], v[34:37]
	v_mfma_f32_16x16x32_bf16 v[22:25], v[148:151], v[180:183], v[22:25]
	v_mfma_f32_16x16x32_bf16 v[18:21], v[156:159], v[180:183], v[18:21]
	v_mfma_f32_16x16x32_bf16 v[6:9], v[148:151], v[188:191], v[6:9]
	v_mfma_f32_16x16x32_bf16 v[2:5], v[156:159], v[188:191], v[2:5]
	v_mfma_f32_16x16x32_bf16 v[54:57], v[152:155], v[168:171], v[54:57]
	v_mfma_f32_16x16x32_bf16 v[50:53], v[160:163], v[168:171], v[50:53]
	v_mfma_f32_16x16x32_bf16 v[38:41], v[152:155], v[176:179], v[38:41]
	v_mfma_f32_16x16x32_bf16 v[34:37], v[160:163], v[176:179], v[34:37]
	v_mfma_f32_16x16x32_bf16 v[22:25], v[152:155], v[184:187], v[22:25]
	v_mfma_f32_16x16x32_bf16 v[18:21], v[160:163], v[184:187], v[18:21]
	v_mfma_f32_16x16x32_bf16 v[6:9], v[152:155], v[212:215], v[6:9]
	v_mfma_f32_16x16x32_bf16 v[2:5], v[160:163], v[212:215], v[2:5]
	s_setprio 0
	s_barrier
	s_add_i32 s42, s42, 2
	s_add_u32 s40, s40, 0x100
	s_addc_u32 s41, s41, 0
	s_cmpk_gt_u32 s42, 0x53
	s_mov_b64 s[20:21], s[22:23]
	s_cbranch_scc0 .LBB0_322
	s_nop 0
	s_nop 0
	s_nop 0
	s_nop 0
	s_nop 0
	s_nop 0
	s_nop 0
	s_nop 0
	s_nop 0
	s_nop 0
	s_nop 0
	s_and_b64 vcc, exec, s[16:17]
	s_cbranch_vccz .LBB0_325
	s_barrier

.LBB0_408:
	s_add_u32 s2, s24, 0xfff80080
	s_addc_u32 s22, s25, -1
	s_add_i32 s45, 0, 0x10000
	s_cmp_eq_u32 s44, 28
	s_cselect_b32 s27, s17, s22
	s_cselect_b32 s26, s40, s2
	v_add_u32_e32 v144, s45, v148
	s_cselect_b32 s23, s15, s43
	s_cselect_b32 s22, s41, s42
	s_add_u32 s100, s24, 0xfff80000
	s_addc_u32 s101, s25, -1
	s_add_i32 s2, 0, 0x14000
	s_mov_b32 m0, s35
	ds_read_b128 v[140:143], v144
	ds_read_b128 v[152:155], v144 offset:1024
	ds_read_b128 v[156:159], v144 offset:2048
	ds_read_b128 v[160:163], v144 offset:3072
	global_load_lds_dwordx4 v136, s[100:101]
	s_mov_b32 m0, s36
	v_add_u32_e32 v144, s2, v148
	ds_read_b128 v[164:167], v144
	ds_read_b128 v[168:171], v144 offset:1024
	ds_read_b128 v[172:175], v144 offset:2048
	ds_read_b128 v[176:179], v144 offset:3072
	global_load_lds_dwordx4 v138, s[100:101]
	s_add_i32 m0, s29, 0xc000
	ds_read_b128 v[180:183], v151
	ds_read_b128 v[184:187], v151 offset:1024
	ds_read_b128 v[188:191], v151 offset:2048
	ds_read_b128 v[192:195], v151 offset:3072
	global_load_lds_dwordx4 v136, s[24:25]
	s_add_i32 m0, s29, 0xe000
	ds_read_b128 v[206:209], v151 offset:4096
	ds_read_b128 v[210:213], v151 offset:5120
	ds_read_b128 v[214:217], v151 offset:6144
	ds_read_b128 v[218:221], v151 offset:7168
	global_load_lds_dwordx4 v138, s[24:25]
	s_waitcnt vmcnt(8)
	s_waitcnt lgkmcnt(0)
	s_barrier
	s_waitcnt lgkmcnt(0)
	v_mfma_f32_16x16x32_bf16 v[126:129], v[140:143], v[180:183], v[126:129]
	v_mfma_f32_16x16x32_bf16 v[122:125], v[156:159], v[180:183], v[122:125]
	v_mfma_f32_16x16x32_bf16 v[110:113], v[140:143], v[188:191], v[110:113]
	v_mfma_f32_16x16x32_bf16 v[106:109], v[156:159], v[188:191], v[106:109]
	v_mfma_f32_16x16x32_bf16 v[94:97], v[140:143], v[206:209], v[94:97]
	v_mfma_f32_16x16x32_bf16 v[90:93], v[156:159], v[206:209], v[90:93]
	v_mfma_f32_16x16x32_bf16 v[78:81], v[140:143], v[214:217], v[78:81]
	v_mfma_f32_16x16x32_bf16 v[74:77], v[156:159], v[214:217], v[74:77]
	v_mfma_f32_16x16x32_bf16 v[126:129], v[152:155], v[184:187], v[126:129]
	v_mfma_f32_16x16x32_bf16 v[122:125], v[160:163], v[184:187], v[122:125]
	v_mfma_f32_16x16x32_bf16 v[110:113], v[152:155], v[192:195], v[110:113]
	v_mfma_f32_16x16x32_bf16 v[106:109], v[160:163], v[192:195], v[106:109]
	s_setprio 1
	v_mfma_f32_16x16x32_bf16 v[94:97], v[152:155], v[210:213], v[94:97]
	v_mfma_f32_16x16x32_bf16 v[90:93], v[160:163], v[210:213], v[90:93]
	v_mfma_f32_16x16x32_bf16 v[78:81], v[152:155], v[218:221], v[78:81]
	v_mfma_f32_16x16x32_bf16 v[74:77], v[160:163], v[218:221], v[74:77]
	v_mfma_f32_16x16x32_bf16 v[118:121], v[164:167], v[180:183], v[118:121]
	v_mfma_f32_16x16x32_bf16 v[114:117], v[172:175], v[180:183], v[114:117]
	v_mfma_f32_16x16x32_bf16 v[102:105], v[164:167], v[188:191], v[102:105]
	v_mfma_f32_16x16x32_bf16 v[98:101], v[172:175], v[188:191], v[98:101]
	v_mfma_f32_16x16x32_bf16 v[86:89], v[164:167], v[206:209], v[86:89]
	v_mfma_f32_16x16x32_bf16 v[82:85], v[172:175], v[206:209], v[82:85]
	v_mfma_f32_16x16x32_bf16 v[70:73], v[164:167], v[214:217], v[70:73]
	v_mfma_f32_16x16x32_bf16 v[66:69], v[172:175], v[214:217], v[66:69]
	v_mfma_f32_16x16x32_bf16 v[118:121], v[168:171], v[184:187], v[118:121]
	v_mfma_f32_16x16x32_bf16 v[114:117], v[176:179], v[184:187], v[114:117]
	v_mfma_f32_16x16x32_bf16 v[102:105], v[168:171], v[192:195], v[102:105]
	v_mfma_f32_16x16x32_bf16 v[98:101], v[176:179], v[192:195], v[98:101]
	v_mfma_f32_16x16x32_bf16 v[86:89], v[168:171], v[210:213], v[86:89]
	v_mfma_f32_16x16x32_bf16 v[82:85], v[176:179], v[210:213], v[82:85]
	v_mfma_f32_16x16x32_bf16 v[70:73], v[168:171], v[218:221], v[70:73]
	v_mfma_f32_16x16x32_bf16 v[66:69], v[176:179], v[218:221], v[66:69]
	s_setprio 0
	s_barrier
	s_add_u32 s46, s22, 0x80000
	s_addc_u32 s47, s23, 0
	s_add_i32 s45, s45, s28
	s_mov_b32 m0, s45
	ds_read_b128 v[180:183], v151 offset:16384
	ds_read_b128 v[184:187], v151 offset:17408
	global_load_lds_dwordx4 v0, s[22:23]
	s_add_i32 m0, s45, 0x2000
	s_add_i32 s2, s2, s28
	ds_read_b128 v[188:191], v151 offset:18432
	ds_read_b128 v[192:195], v151 offset:19456
	global_load_lds_dwordx4 v130, s[22:23]
	s_mov_b32 m0, s2
	ds_read_b128 v[206:209], v151 offset:20480
	ds_read_b128 v[210:213], v151 offset:21504
	global_load_lds_dwordx4 v0, s[46:47]
	s_add_i32 m0, s2, 0x2000
	ds_read_b128 v[214:217], v151 offset:22528
	ds_read_b128 v[218:221], v151 offset:23552
	global_load_lds_dwordx4 v130, s[46:47]
	s_waitcnt vmcnt(6)
	s_waitcnt lgkmcnt(0)
	s_barrier
	s_waitcnt lgkmcnt(0)
	v_mfma_f32_16x16x32_bf16 v[62:65], v[140:143], v[180:183], v[62:65]
	v_mfma_f32_16x16x32_bf16 v[58:61], v[156:159], v[180:183], v[58:61]
	v_mfma_f32_16x16x32_bf16 v[46:49], v[140:143], v[188:191], v[46:49]
	v_mfma_f32_16x16x32_bf16 v[42:45], v[156:159], v[188:191], v[42:45]
	v_mfma_f32_16x16x32_bf16 v[30:33], v[140:143], v[206:209], v[30:33]
	v_mfma_f32_16x16x32_bf16 v[26:29], v[156:159], v[206:209], v[26:29]
	v_mfma_f32_16x16x32_bf16 v[14:17], v[140:143], v[214:217], v[14:17]
	v_mfma_f32_16x16x32_bf16 v[10:13], v[156:159], v[214:217], v[10:13]
	v_mfma_f32_16x16x32_bf16 v[62:65], v[152:155], v[184:187], v[62:65]
	v_mfma_f32_16x16x32_bf16 v[58:61], v[160:163], v[184:187], v[58:61]
	v_mfma_f32_16x16x32_bf16 v[46:49], v[152:155], v[192:195], v[46:49]
	v_mfma_f32_16x16x32_bf16 v[42:45], v[160:163], v[192:195], v[42:45]
	s_setprio 1
	v_mfma_f32_16x16x32_bf16 v[30:33], v[152:155], v[210:213], v[30:33]
	v_mfma_f32_16x16x32_bf16 v[26:29], v[160:163], v[210:213], v[26:29]
	v_mfma_f32_16x16x32_bf16 v[14:17], v[152:155], v[218:221], v[14:17]
	v_mfma_f32_16x16x32_bf16 v[10:13], v[160:163], v[218:221], v[10:13]
	v_mfma_f32_16x16x32_bf16 v[54:57], v[164:167], v[180:183], v[54:57]
	v_mfma_f32_16x16x32_bf16 v[50:53], v[172:175], v[180:183], v[50:53]
	v_mfma_f32_16x16x32_bf16 v[38:41], v[164:167], v[188:191], v[38:41]
	v_mfma_f32_16x16x32_bf16 v[34:37], v[172:175], v[188:191], v[34:37]
	v_mfma_f32_16x16x32_bf16 v[22:25], v[164:167], v[206:209], v[22:25]
	v_mfma_f32_16x16x32_bf16 v[18:21], v[172:175], v[206:209], v[18:21]
	v_mfma_f32_16x16x32_bf16 v[6:9], v[164:167], v[214:217], v[6:9]
	v_mfma_f32_16x16x32_bf16 v[2:5], v[172:175], v[214:217], v[2:5]
	v_mfma_f32_16x16x32_bf16 v[54:57], v[168:171], v[184:187], v[54:57]
	v_mfma_f32_16x16x32_bf16 v[50:53], v[176:179], v[184:187], v[50:53]
	v_mfma_f32_16x16x32_bf16 v[38:41], v[168:171], v[192:195], v[38:41]
	v_mfma_f32_16x16x32_bf16 v[34:37], v[176:179], v[192:195], v[34:37]
	v_mfma_f32_16x16x32_bf16 v[22:25], v[168:171], v[210:213], v[22:25]
	v_mfma_f32_16x16x32_bf16 v[18:21], v[176:179], v[210:213], v[18:21]
	v_mfma_f32_16x16x32_bf16 v[6:9], v[168:171], v[218:221], v[6:9]
	v_mfma_f32_16x16x32_bf16 v[2:5], v[176:179], v[218:221], v[2:5]
	s_setprio 0
	s_barrier
	s_add_u32 s26, s26, 0x80000
	s_addc_u32 s27, s27, 0
	s_add_u32 s100, s26, 0xfff80000
	s_addc_u32 s101, s27, -1
	s_add_i32 s2, 0, 0x18000
	s_add_i32 s45, 0, 0x1c000
	v_add_u32_e32 v160, s2, v148
	v_add_u32_e32 v176, s45, v148
	s_mov_b32 m0, s29
	ds_read_b128 v[140:143], v160
	ds_read_b128 v[152:155], v160 offset:1024
	ds_read_b128 v[156:159], v160 offset:2048
	ds_read_b128 v[160:163], v160 offset:3072
	global_load_lds_dwordx4 v134, s[100:101]
	s_mov_b32 m0, s30
	ds_read_b128 v[164:167], v176
	ds_read_b128 v[168:171], v176 offset:1024
	ds_read_b128 v[172:175], v176 offset:2048
	ds_read_b128 v[176:179], v176 offset:3072
	global_load_lds_dwordx4 v132, s[100:101]
	s_mov_b32 m0, s31
	ds_read_b128 v[180:183], v151 offset:32768
	ds_read_b128 v[184:187], v151 offset:33792
	ds_read_b128 v[188:191], v151 offset:34816
	ds_read_b128 v[192:195], v151 offset:35840
	global_load_lds_dwordx4 v134, s[26:27]
	s_mov_b32 m0, s33
	ds_read_b128 v[206:209], v151 offset:36864
	ds_read_b128 v[210:213], v151 offset:37888
	ds_read_b128 v[214:217], v151 offset:38912
	ds_read_b128 v[218:221], v151 offset:39936
	global_load_lds_dwordx4 v132, s[26:27]
	s_waitcnt vmcnt(8)
	s_waitcnt lgkmcnt(0)
	s_barrier
	s_waitcnt lgkmcnt(0)
	v_mfma_f32_16x16x32_bf16 v[126:129], v[140:143], v[180:183], v[126:129]
	v_mfma_f32_16x16x32_bf16 v[122:125], v[156:159], v[180:183], v[122:125]
	v_mfma_f32_16x16x32_bf16 v[110:113], v[140:143], v[188:191], v[110:113]
	v_mfma_f32_16x16x32_bf16 v[106:109], v[156:159], v[188:191], v[106:109]
	v_mfma_f32_16x16x32_bf16 v[94:97], v[140:143], v[206:209], v[94:97]
	v_mfma_f32_16x16x32_bf16 v[90:93], v[156:159], v[206:209], v[90:93]
	v_mfma_f32_16x16x32_bf16 v[78:81], v[140:143], v[214:217], v[78:81]
	v_mfma_f32_16x16x32_bf16 v[74:77], v[156:159], v[214:217], v[74:77]
	v_mfma_f32_16x16x32_bf16 v[126:129], v[152:155], v[184:187], v[126:129]
	v_mfma_f32_16x16x32_bf16 v[122:125], v[160:163], v[184:187], v[122:125]
	v_mfma_f32_16x16x32_bf16 v[110:113], v[152:155], v[192:195], v[110:113]
	v_mfma_f32_16x16x32_bf16 v[106:109], v[160:163], v[192:195], v[106:109]
	s_setprio 1
	v_mfma_f32_16x16x32_bf16 v[94:97], v[152:155], v[210:213], v[94:97]
	v_mfma_f32_16x16x32_bf16 v[90:93], v[160:163], v[210:213], v[90:93]
	v_mfma_f32_16x16x32_bf16 v[78:81], v[152:155], v[218:221], v[78:81]
	v_mfma_f32_16x16x32_bf16 v[74:77], v[160:163], v[218:221], v[74:77]
	v_mfma_f32_16x16x32_bf16 v[118:121], v[164:167], v[180:183], v[118:121]
	v_mfma_f32_16x16x32_bf16 v[114:117], v[172:175], v[180:183], v[114:117]
	v_mfma_f32_16x16x32_bf16 v[102:105], v[164:167], v[188:191], v[102:105]
	v_mfma_f32_16x16x32_bf16 v[98:101], v[172:175], v[188:191], v[98:101]
	v_mfma_f32_16x16x32_bf16 v[86:89], v[164:167], v[206:209], v[86:89]
	v_mfma_f32_16x16x32_bf16 v[82:85], v[172:175], v[206:209], v[82:85]
	v_mfma_f32_16x16x32_bf16 v[70:73], v[164:167], v[214:217], v[70:73]
	v_mfma_f32_16x16x32_bf16 v[66:69], v[172:175], v[214:217], v[66:69]
	v_mfma_f32_16x16x32_bf16 v[118:121], v[168:171], v[184:187], v[118:121]
	v_mfma_f32_16x16x32_bf16 v[114:117], v[176:179], v[184:187], v[114:117]
	v_mfma_f32_16x16x32_bf16 v[102:105], v[168:171], v[192:195], v[102:105]
	v_mfma_f32_16x16x32_bf16 v[98:101], v[176:179], v[192:195], v[98:101]
	v_mfma_f32_16x16x32_bf16 v[86:89], v[168:171], v[210:213], v[86:89]
	v_mfma_f32_16x16x32_bf16 v[82:85], v[176:179], v[210:213], v[82:85]
	v_mfma_f32_16x16x32_bf16 v[70:73], v[168:171], v[218:221], v[70:73]
	v_mfma_f32_16x16x32_bf16 v[66:69], v[176:179], v[218:221], v[66:69]
	s_setprio 0
	s_barrier
	s_add_u32 s22, s22, 0x80080
	s_addc_u32 s23, s23, 0
	s_add_u32 s46, s46, 0xfff80080
	s_addc_u32 s47, s47, -1
	s_add_i32 s2, s2, s28
	s_mov_b32 m0, s2
	ds_read_b128 v[180:183], v151 offset:49152
	ds_read_b128 v[184:187], v151 offset:50176
	global_load_lds_dwordx4 v0, s[46:47]
	s_add_i32 m0, s2, 0x2000
	s_add_i32 s2, s45, s28
	ds_read_b128 v[188:191], v151 offset:51200
	ds_read_b128 v[192:195], v151 offset:52224
	global_load_lds_dwordx4 v130, s[46:47]
	s_mov_b32 m0, s2
	ds_read_b128 v[206:209], v151 offset:53248
	ds_read_b128 v[210:213], v151 offset:54272
	global_load_lds_dwordx4 v0, s[22:23]
	s_add_i32 m0, s2, 0x2000
	ds_read_b128 v[214:217], v151 offset:55296
	ds_read_b128 v[218:221], v151 offset:56320
	global_load_lds_dwordx4 v130, s[22:23]
	s_waitcnt vmcnt(6)
	s_waitcnt lgkmcnt(0)
	s_barrier
	s_waitcnt lgkmcnt(0)
	v_mfma_f32_16x16x32_bf16 v[62:65], v[140:143], v[180:183], v[62:65]
	v_mfma_f32_16x16x32_bf16 v[58:61], v[156:159], v[180:183], v[58:61]
	v_mfma_f32_16x16x32_bf16 v[46:49], v[140:143], v[188:191], v[46:49]
	v_mfma_f32_16x16x32_bf16 v[42:45], v[156:159], v[188:191], v[42:45]
	v_mfma_f32_16x16x32_bf16 v[30:33], v[140:143], v[206:209], v[30:33]
	v_mfma_f32_16x16x32_bf16 v[26:29], v[156:159], v[206:209], v[26:29]
	v_mfma_f32_16x16x32_bf16 v[14:17], v[140:143], v[214:217], v[14:17]
	v_mfma_f32_16x16x32_bf16 v[10:13], v[156:159], v[214:217], v[10:13]
	v_mfma_f32_16x16x32_bf16 v[62:65], v[152:155], v[184:187], v[62:65]
	v_mfma_f32_16x16x32_bf16 v[58:61], v[160:163], v[184:187], v[58:61]
	v_mfma_f32_16x16x32_bf16 v[46:49], v[152:155], v[192:195], v[46:49]
	v_mfma_f32_16x16x32_bf16 v[42:45], v[160:163], v[192:195], v[42:45]
	s_setprio 1
	v_mfma_f32_16x16x32_bf16 v[30:33], v[152:155], v[210:213], v[30:33]
	v_mfma_f32_16x16x32_bf16 v[26:29], v[160:163], v[210:213], v[26:29]
	v_mfma_f32_16x16x32_bf16 v[14:17], v[152:155], v[218:221], v[14:17]
	v_mfma_f32_16x16x32_bf16 v[10:13], v[160:163], v[218:221], v[10:13]
	v_mfma_f32_16x16x32_bf16 v[54:57], v[164:167], v[180:183], v[54:57]
	v_mfma_f32_16x16x32_bf16 v[50:53], v[172:175], v[180:183], v[50:53]
	v_mfma_f32_16x16x32_bf16 v[38:41], v[164:167], v[188:191], v[38:41]
	v_mfma_f32_16x16x32_bf16 v[34:37], v[172:175], v[188:191], v[34:37]
	v_mfma_f32_16x16x32_bf16 v[22:25], v[164:167], v[206:209], v[22:25]
	v_mfma_f32_16x16x32_bf16 v[18:21], v[172:175], v[206:209], v[18:21]
	v_mfma_f32_16x16x32_bf16 v[6:9], v[164:167], v[214:217], v[6:9]
	v_mfma_f32_16x16x32_bf16 v[2:5], v[172:175], v[214:217], v[2:5]
	v_mfma_f32_16x16x32_bf16 v[54:57], v[168:171], v[184:187], v[54:57]
	v_mfma_f32_16x16x32_bf16 v[50:53], v[176:179], v[184:187], v[50:53]
	v_mfma_f32_16x16x32_bf16 v[38:41], v[168:171], v[192:195], v[38:41]
	v_mfma_f32_16x16x32_bf16 v[34:37], v[176:179], v[192:195], v[34:37]
	v_mfma_f32_16x16x32_bf16 v[22:25], v[168:171], v[210:213], v[22:25]
	v_mfma_f32_16x16x32_bf16 v[18:21], v[176:179], v[210:213], v[18:21]
	v_mfma_f32_16x16x32_bf16 v[6:9], v[168:171], v[218:221], v[6:9]
	v_mfma_f32_16x16x32_bf16 v[2:5], v[176:179], v[218:221], v[2:5]
	s_setprio 0
	s_barrier
	s_add_i32 s44, s44, 2
	s_add_u32 s24, s24, 0x100
	s_addc_u32 s25, s25, 0
	s_add_u32 s42, s42, 0x100
	s_addc_u32 s43, s43, 0
	s_cmp_gt_u32 s44, 29
	s_cbranch_scc0 .LBB0_408
	s_nop 0
	s_nop 0
	s_nop 0
	s_nop 0
	s_nop 0
	s_nop 0
	s_nop 0
	s_nop 0
	s_and_b64 vcc, exec, s[12:13]
	s_cbranch_vccz .LBB0_411
	s_barrier

.LBB0_440:
	s_add_u32 s2, s18, 0xfff80080
	s_addc_u32 s10, s19, -1
	s_add_i32 s47, 0, 0x10000
	s_cmp_eq_u32 s46, 28
	s_cselect_b32 s29, s25, s10
	s_cselect_b32 s28, s34, s2
	s_cselect_b32 s11, s23, s45
	s_cselect_b32 s10, s43, s44
	s_add_u32 s100, s18, 0xfff80000
	s_addc_u32 s101, s19, -1
	s_add_i32 s2, 0, 0x14000
	v_add_u32_e32 v154, s47, v162
	v_add_u32_e32 v184, s2, v162
	s_mov_b32 m0, s38
	ds_read_b128 v[130:133], v154
	ds_read_b128 v[134:137], v154 offset:1024
	ds_read_b128 v[150:153], v154 offset:2048
	ds_read_b128 v[154:157], v154 offset:3072
	global_load_lds_dwordx4 v144, s[100:101]
	s_mov_b32 m0, s39
	ds_read_b128 v[158:161], v184
	ds_read_b128 v[176:179], v184 offset:1024
	ds_read_b128 v[180:183], v184 offset:2048
	ds_read_b128 v[184:187], v184 offset:3072
	global_load_lds_dwordx4 v148, s[100:101]
	s_add_i32 m0, s31, 0xc000
	ds_read_b128 v[188:191], v175
	ds_read_b128 v[192:195], v175 offset:1024
	ds_read_b128 v[206:209], v175 offset:2048
	ds_read_b128 v[210:213], v175 offset:3072
	global_load_lds_dwordx4 v144, s[18:19]
	s_add_i32 m0, s31, 0xe000
	ds_read_b128 v[214:217], v175 offset:4096
	ds_read_b128 v[218:221], v175 offset:5120
	ds_read_b128 v[222:225], v175 offset:6144
	ds_read_b128 v[226:229], v175 offset:7168
	global_load_lds_dwordx4 v148, s[18:19]
	s_waitcnt vmcnt(8)
	s_waitcnt lgkmcnt(0)
	s_barrier
	s_waitcnt lgkmcnt(0)
	v_mfma_f32_16x16x32_bf16 v[126:129], v[130:133], v[188:191], v[126:129]
	v_mfma_f32_16x16x32_bf16 v[122:125], v[150:153], v[188:191], v[122:125]
	v_mfma_f32_16x16x32_bf16 v[110:113], v[130:133], v[206:209], v[110:113]
	v_mfma_f32_16x16x32_bf16 v[106:109], v[150:153], v[206:209], v[106:109]
	v_mfma_f32_16x16x32_bf16 v[94:97], v[130:133], v[214:217], v[94:97]
	v_mfma_f32_16x16x32_bf16 v[90:93], v[150:153], v[214:217], v[90:93]
	v_mfma_f32_16x16x32_bf16 v[78:81], v[130:133], v[222:225], v[78:81]
	v_mfma_f32_16x16x32_bf16 v[74:77], v[150:153], v[222:225], v[74:77]
	v_mfma_f32_16x16x32_bf16 v[126:129], v[134:137], v[192:195], v[126:129]
	v_mfma_f32_16x16x32_bf16 v[122:125], v[154:157], v[192:195], v[122:125]
	v_mfma_f32_16x16x32_bf16 v[110:113], v[134:137], v[210:213], v[110:113]
	v_mfma_f32_16x16x32_bf16 v[106:109], v[154:157], v[210:213], v[106:109]
	s_setprio 1
	v_mfma_f32_16x16x32_bf16 v[94:97], v[134:137], v[218:221], v[94:97]
	v_mfma_f32_16x16x32_bf16 v[90:93], v[154:157], v[218:221], v[90:93]
	v_mfma_f32_16x16x32_bf16 v[78:81], v[134:137], v[226:229], v[78:81]
	v_mfma_f32_16x16x32_bf16 v[74:77], v[154:157], v[226:229], v[74:77]
	v_mfma_f32_16x16x32_bf16 v[118:121], v[158:161], v[188:191], v[118:121]
	v_mfma_f32_16x16x32_bf16 v[114:117], v[180:183], v[188:191], v[114:117]
	v_mfma_f32_16x16x32_bf16 v[102:105], v[158:161], v[206:209], v[102:105]
	v_mfma_f32_16x16x32_bf16 v[98:101], v[180:183], v[206:209], v[98:101]
	v_mfma_f32_16x16x32_bf16 v[86:89], v[158:161], v[214:217], v[86:89]
	v_mfma_f32_16x16x32_bf16 v[82:85], v[180:183], v[214:217], v[82:85]
	v_mfma_f32_16x16x32_bf16 v[70:73], v[158:161], v[222:225], v[70:73]
	v_mfma_f32_16x16x32_bf16 v[66:69], v[180:183], v[222:225], v[66:69]
	v_mfma_f32_16x16x32_bf16 v[118:121], v[176:179], v[192:195], v[118:121]
	v_mfma_f32_16x16x32_bf16 v[114:117], v[184:187], v[192:195], v[114:117]
	v_mfma_f32_16x16x32_bf16 v[102:105], v[176:179], v[210:213], v[102:105]
	v_mfma_f32_16x16x32_bf16 v[98:101], v[184:187], v[210:213], v[98:101]
	v_mfma_f32_16x16x32_bf16 v[86:89], v[176:179], v[218:221], v[86:89]
	v_mfma_f32_16x16x32_bf16 v[82:85], v[184:187], v[218:221], v[82:85]
	v_mfma_f32_16x16x32_bf16 v[70:73], v[176:179], v[226:229], v[70:73]
	v_mfma_f32_16x16x32_bf16 v[66:69], v[184:187], v[226:229], v[66:69]
	s_setprio 0
	s_barrier
	s_add_u32 s52, s10, 0x80000
	s_addc_u32 s53, s11, 0
	s_add_i32 s47, s47, s30
	s_mov_b32 m0, s47
	ds_read_b128 v[188:191], v175 offset:16384
	ds_read_b128 v[192:195], v175 offset:17408
	global_load_lds_dwordx4 v0, s[10:11]
	s_add_i32 m0, s47, 0x2000
	s_add_i32 s2, s2, s30
	ds_read_b128 v[206:209], v175 offset:18432
	ds_read_b128 v[210:213], v175 offset:19456
	global_load_lds_dwordx4 v138, s[10:11]
	s_mov_b32 m0, s2
	ds_read_b128 v[214:217], v175 offset:20480
	ds_read_b128 v[218:221], v175 offset:21504
	global_load_lds_dwordx4 v0, s[52:53]
	s_add_i32 m0, s2, 0x2000
	ds_read_b128 v[222:225], v175 offset:22528
	ds_read_b128 v[226:229], v175 offset:23552
	global_load_lds_dwordx4 v138, s[52:53]
	s_waitcnt vmcnt(6)
	s_waitcnt lgkmcnt(0)
	s_barrier
	s_waitcnt lgkmcnt(0)
	v_mfma_f32_16x16x32_bf16 v[62:65], v[130:133], v[188:191], v[62:65]
	v_mfma_f32_16x16x32_bf16 v[58:61], v[150:153], v[188:191], v[58:61]
	v_mfma_f32_16x16x32_bf16 v[46:49], v[130:133], v[206:209], v[46:49]
	v_mfma_f32_16x16x32_bf16 v[42:45], v[150:153], v[206:209], v[42:45]
	v_mfma_f32_16x16x32_bf16 v[30:33], v[130:133], v[214:217], v[30:33]
	v_mfma_f32_16x16x32_bf16 v[26:29], v[150:153], v[214:217], v[26:29]
	v_mfma_f32_16x16x32_bf16 v[14:17], v[130:133], v[222:225], v[14:17]
	v_mfma_f32_16x16x32_bf16 v[10:13], v[150:153], v[222:225], v[10:13]
	v_mfma_f32_16x16x32_bf16 v[62:65], v[134:137], v[192:195], v[62:65]
	v_mfma_f32_16x16x32_bf16 v[58:61], v[154:157], v[192:195], v[58:61]
	v_mfma_f32_16x16x32_bf16 v[46:49], v[134:137], v[210:213], v[46:49]
	v_mfma_f32_16x16x32_bf16 v[42:45], v[154:157], v[210:213], v[42:45]
	s_setprio 1
	v_mfma_f32_16x16x32_bf16 v[30:33], v[134:137], v[218:221], v[30:33]
	v_mfma_f32_16x16x32_bf16 v[26:29], v[154:157], v[218:221], v[26:29]
	v_mfma_f32_16x16x32_bf16 v[14:17], v[134:137], v[226:229], v[14:17]
	v_mfma_f32_16x16x32_bf16 v[10:13], v[154:157], v[226:229], v[10:13]
	v_mfma_f32_16x16x32_bf16 v[54:57], v[158:161], v[188:191], v[54:57]
	v_mfma_f32_16x16x32_bf16 v[50:53], v[180:183], v[188:191], v[50:53]
	v_mfma_f32_16x16x32_bf16 v[38:41], v[158:161], v[206:209], v[38:41]
	v_mfma_f32_16x16x32_bf16 v[34:37], v[180:183], v[206:209], v[34:37]
	v_mfma_f32_16x16x32_bf16 v[22:25], v[158:161], v[214:217], v[22:25]
	v_mfma_f32_16x16x32_bf16 v[18:21], v[180:183], v[214:217], v[18:21]
	v_mfma_f32_16x16x32_bf16 v[6:9], v[158:161], v[222:225], v[6:9]
	v_mfma_f32_16x16x32_bf16 v[2:5], v[180:183], v[222:225], v[2:5]
	v_mfma_f32_16x16x32_bf16 v[54:57], v[176:179], v[192:195], v[54:57]
	v_mfma_f32_16x16x32_bf16 v[50:53], v[184:187], v[192:195], v[50:53]
	v_mfma_f32_16x16x32_bf16 v[38:41], v[176:179], v[210:213], v[38:41]
	v_mfma_f32_16x16x32_bf16 v[34:37], v[184:187], v[210:213], v[34:37]
	v_mfma_f32_16x16x32_bf16 v[22:25], v[176:179], v[218:221], v[22:25]
	v_mfma_f32_16x16x32_bf16 v[18:21], v[184:187], v[218:221], v[18:21]
	v_mfma_f32_16x16x32_bf16 v[6:9], v[176:179], v[226:229], v[6:9]
	v_mfma_f32_16x16x32_bf16 v[2:5], v[184:187], v[226:229], v[2:5]
	s_setprio 0
	s_barrier
	s_add_u32 s28, s28, 0x80000
	s_addc_u32 s29, s29, 0
	s_add_u32 s100, s28, 0xfff80000
	s_addc_u32 s101, s29, -1
	s_add_i32 s2, 0, 0x18000
	s_add_i32 s47, 0, 0x1c000
	v_add_u32_e32 v154, s2, v162
	v_add_u32_e32 v184, s47, v162
	s_mov_b32 m0, s31
	ds_read_b128 v[130:133], v154
	ds_read_b128 v[134:137], v154 offset:1024
	ds_read_b128 v[150:153], v154 offset:2048
	ds_read_b128 v[154:157], v154 offset:3072
	global_load_lds_dwordx4 v142, s[100:101]
	s_mov_b32 m0, s35
	ds_read_b128 v[158:161], v184
	ds_read_b128 v[176:179], v184 offset:1024
	ds_read_b128 v[180:183], v184 offset:2048
	ds_read_b128 v[184:187], v184 offset:3072
	global_load_lds_dwordx4 v140, s[100:101]
	s_mov_b32 m0, s36
	ds_read_b128 v[188:191], v175 offset:32768
	ds_read_b128 v[192:195], v175 offset:33792
	ds_read_b128 v[206:209], v175 offset:34816
	ds_read_b128 v[210:213], v175 offset:35840
	global_load_lds_dwordx4 v142, s[28:29]
	s_mov_b32 m0, s37
	ds_read_b128 v[214:217], v175 offset:36864
	ds_read_b128 v[218:221], v175 offset:37888
	ds_read_b128 v[222:225], v175 offset:38912
	ds_read_b128 v[226:229], v175 offset:39936
	global_load_lds_dwordx4 v140, s[28:29]
	s_waitcnt vmcnt(8)
	s_waitcnt lgkmcnt(0)
	s_barrier
	s_waitcnt lgkmcnt(0)
	v_mfma_f32_16x16x32_bf16 v[126:129], v[130:133], v[188:191], v[126:129]
	v_mfma_f32_16x16x32_bf16 v[122:125], v[150:153], v[188:191], v[122:125]
	v_mfma_f32_16x16x32_bf16 v[110:113], v[130:133], v[206:209], v[110:113]
	v_mfma_f32_16x16x32_bf16 v[106:109], v[150:153], v[206:209], v[106:109]
	v_mfma_f32_16x16x32_bf16 v[94:97], v[130:133], v[214:217], v[94:97]
	v_mfma_f32_16x16x32_bf16 v[90:93], v[150:153], v[214:217], v[90:93]
	v_mfma_f32_16x16x32_bf16 v[78:81], v[130:133], v[222:225], v[78:81]
	v_mfma_f32_16x16x32_bf16 v[74:77], v[150:153], v[222:225], v[74:77]
	v_mfma_f32_16x16x32_bf16 v[126:129], v[134:137], v[192:195], v[126:129]
	v_mfma_f32_16x16x32_bf16 v[122:125], v[154:157], v[192:195], v[122:125]
	v_mfma_f32_16x16x32_bf16 v[110:113], v[134:137], v[210:213], v[110:113]
	v_mfma_f32_16x16x32_bf16 v[106:109], v[154:157], v[210:213], v[106:109]
	s_setprio 1
	v_mfma_f32_16x16x32_bf16 v[94:97], v[134:137], v[218:221], v[94:97]
	v_mfma_f32_16x16x32_bf16 v[90:93], v[154:157], v[218:221], v[90:93]
	v_mfma_f32_16x16x32_bf16 v[78:81], v[134:137], v[226:229], v[78:81]
	v_mfma_f32_16x16x32_bf16 v[74:77], v[154:157], v[226:229], v[74:77]
	v_mfma_f32_16x16x32_bf16 v[118:121], v[158:161], v[188:191], v[118:121]
	v_mfma_f32_16x16x32_bf16 v[114:117], v[180:183], v[188:191], v[114:117]
	v_mfma_f32_16x16x32_bf16 v[102:105], v[158:161], v[206:209], v[102:105]
	v_mfma_f32_16x16x32_bf16 v[98:101], v[180:183], v[206:209], v[98:101]
	v_mfma_f32_16x16x32_bf16 v[86:89], v[158:161], v[214:217], v[86:89]
	v_mfma_f32_16x16x32_bf16 v[82:85], v[180:183], v[214:217], v[82:85]
	v_mfma_f32_16x16x32_bf16 v[70:73], v[158:161], v[222:225], v[70:73]
	v_mfma_f32_16x16x32_bf16 v[66:69], v[180:183], v[222:225], v[66:69]
	v_mfma_f32_16x16x32_bf16 v[118:121], v[176:179], v[192:195], v[118:121]
	v_mfma_f32_16x16x32_bf16 v[114:117], v[184:187], v[192:195], v[114:117]
	v_mfma_f32_16x16x32_bf16 v[102:105], v[176:179], v[210:213], v[102:105]
	v_mfma_f32_16x16x32_bf16 v[98:101], v[184:187], v[210:213], v[98:101]
	v_mfma_f32_16x16x32_bf16 v[86:89], v[176:179], v[218:221], v[86:89]
	v_mfma_f32_16x16x32_bf16 v[82:85], v[184:187], v[218:221], v[82:85]
	v_mfma_f32_16x16x32_bf16 v[70:73], v[176:179], v[226:229], v[70:73]
	v_mfma_f32_16x16x32_bf16 v[66:69], v[184:187], v[226:229], v[66:69]
	s_setprio 0
	s_barrier
	s_add_u32 s10, s10, 0x80080
	s_addc_u32 s11, s11, 0
	s_add_u32 s52, s52, 0xfff80080
	s_addc_u32 s53, s53, -1
	s_add_i32 s2, s2, s30
	s_mov_b32 m0, s2
	ds_read_b128 v[188:191], v175 offset:49152
	ds_read_b128 v[192:195], v175 offset:50176
	global_load_lds_dwordx4 v0, s[52:53]
	s_add_i32 m0, s2, 0x2000
	s_add_i32 s2, s47, s30
	ds_read_b128 v[206:209], v175 offset:51200
	ds_read_b128 v[210:213], v175 offset:52224
	global_load_lds_dwordx4 v138, s[52:53]
	s_mov_b32 m0, s2
	ds_read_b128 v[214:217], v175 offset:53248
	ds_read_b128 v[218:221], v175 offset:54272
	global_load_lds_dwordx4 v0, s[10:11]
	s_add_i32 m0, s2, 0x2000
	ds_read_b128 v[222:225], v175 offset:55296
	ds_read_b128 v[226:229], v175 offset:56320
	global_load_lds_dwordx4 v138, s[10:11]
	s_waitcnt vmcnt(6)
	s_waitcnt lgkmcnt(0)
	s_barrier
	s_waitcnt lgkmcnt(0)
	v_mfma_f32_16x16x32_bf16 v[62:65], v[130:133], v[188:191], v[62:65]
	v_mfma_f32_16x16x32_bf16 v[58:61], v[150:153], v[188:191], v[58:61]
	v_mfma_f32_16x16x32_bf16 v[46:49], v[130:133], v[206:209], v[46:49]
	v_mfma_f32_16x16x32_bf16 v[42:45], v[150:153], v[206:209], v[42:45]
	v_mfma_f32_16x16x32_bf16 v[30:33], v[130:133], v[214:217], v[30:33]
	v_mfma_f32_16x16x32_bf16 v[26:29], v[150:153], v[214:217], v[26:29]
	v_mfma_f32_16x16x32_bf16 v[14:17], v[130:133], v[222:225], v[14:17]
	v_mfma_f32_16x16x32_bf16 v[10:13], v[150:153], v[222:225], v[10:13]
	v_mfma_f32_16x16x32_bf16 v[62:65], v[134:137], v[192:195], v[62:65]
	v_mfma_f32_16x16x32_bf16 v[58:61], v[154:157], v[192:195], v[58:61]
	v_mfma_f32_16x16x32_bf16 v[46:49], v[134:137], v[210:213], v[46:49]
	v_mfma_f32_16x16x32_bf16 v[42:45], v[154:157], v[210:213], v[42:45]
	s_setprio 1
	v_mfma_f32_16x16x32_bf16 v[30:33], v[134:137], v[218:221], v[30:33]
	v_mfma_f32_16x16x32_bf16 v[26:29], v[154:157], v[218:221], v[26:29]
	v_mfma_f32_16x16x32_bf16 v[14:17], v[134:137], v[226:229], v[14:17]
	v_mfma_f32_16x16x32_bf16 v[10:13], v[154:157], v[226:229], v[10:13]
	v_mfma_f32_16x16x32_bf16 v[54:57], v[158:161], v[188:191], v[54:57]
	v_mfma_f32_16x16x32_bf16 v[50:53], v[180:183], v[188:191], v[50:53]
	v_mfma_f32_16x16x32_bf16 v[38:41], v[158:161], v[206:209], v[38:41]
	v_mfma_f32_16x16x32_bf16 v[34:37], v[180:183], v[206:209], v[34:37]
	v_mfma_f32_16x16x32_bf16 v[22:25], v[158:161], v[214:217], v[22:25]
	v_mfma_f32_16x16x32_bf16 v[18:21], v[180:183], v[214:217], v[18:21]
	v_mfma_f32_16x16x32_bf16 v[6:9], v[158:161], v[222:225], v[6:9]
	v_mfma_f32_16x16x32_bf16 v[2:5], v[180:183], v[222:225], v[2:5]
	v_mfma_f32_16x16x32_bf16 v[54:57], v[176:179], v[192:195], v[54:57]
	v_mfma_f32_16x16x32_bf16 v[50:53], v[184:187], v[192:195], v[50:53]
	v_mfma_f32_16x16x32_bf16 v[38:41], v[176:179], v[210:213], v[38:41]
	v_mfma_f32_16x16x32_bf16 v[34:37], v[184:187], v[210:213], v[34:37]
	v_mfma_f32_16x16x32_bf16 v[22:25], v[176:179], v[218:221], v[22:25]
	v_mfma_f32_16x16x32_bf16 v[18:21], v[184:187], v[218:221], v[18:21]
	v_mfma_f32_16x16x32_bf16 v[6:9], v[176:179], v[226:229], v[6:9]
	v_mfma_f32_16x16x32_bf16 v[2:5], v[184:187], v[226:229], v[2:5]
	s_setprio 0
	s_barrier
	s_add_i32 s46, s46, 2
	s_add_u32 s18, s18, 0x100
	s_addc_u32 s19, s19, 0
	s_add_u32 s44, s44, 0x100
	s_addc_u32 s45, s45, 0
	s_cmp_gt_u32 s46, 29
	s_cbranch_scc0 .LBB0_440
	s_nop 0
	s_nop 0
	s_nop 0
	s_nop 0
	s_nop 0
	s_nop 0
	s_nop 0
	s_nop 0
	s_and_b64 vcc, exec, s[20:21]
	s_cbranch_vccz .LBB0_443
	s_barrier

.LBB0_746:
	s_add_i32 s2, s74, 0xffff8000
	s_and_b32 s34, s2, 0x18000
	s_cmp_lg_u32 0, -1
	s_cselect_b32 s2, 0, 0
	s_add_i32 s2, s34, s2
	v_add_u32_e32 v236, s2, v227
	ds_read_b128 v[130:133], v236 offset:0
	v_add_u32_e32 v237, s2, v226
	ds_read_b128 v[244:247], v237 offset:0
	s_waitcnt lgkmcnt(0)
	v_add_u32_e32 v243, s2, v225
	v_mfma_f32_32x32x16_bf16 v[130:145], v[130:133], v[176:179], 0
	ds_read_b128 v[248:251], v243 offset:0
	v_exp_f32_e32 v252, v194
	v_exp_f32_e32 v253, v195
	s_waitcnt lgkmcnt(0)
	v_add_u32_e32 v235, s2, v224
	v_mfma_f32_32x32x16_bf16 v[130:145], v[244:247], v[172:175], v[130:145]
	ds_read_b128 v[244:247], v235 offset:0
	v_exp_f32_e32 v232, v192
	v_exp_f32_e32 v196, v193
	s_waitcnt lgkmcnt(0)
	ds_read_b128 v[192:195], v236 offset:0x80
	v_exp_f32_e32 v197, v190
	v_mfma_f32_32x32x16_bf16 v[130:145], v[248:251], v[168:171], v[130:145]
	v_exp_f32_e32 v236, v191
	s_waitcnt lgkmcnt(0)
	v_exp_f32_e32 v248, v189
	v_mfma_f32_32x32x16_bf16 v[130:145], v[244:247], v[164:167], v[130:145]
	ds_read_b128 v[244:247], v237 offset:0x80
	v_exp_f32_e32 v237, v188
	s_waitcnt lgkmcnt(0)
	ds_read_b128 v[188:191], v243 offset:0x80
	v_exp_f32_e32 v186, v186
	v_mfma_f32_32x32x16_bf16 v[130:145], v[192:195], v[160:163], v[130:145]
	v_exp_f32_e32 v187, v187
	s_waitcnt lgkmcnt(0)
	ds_read_b128 v[192:195], v235 offset:0x80
	v_exp_f32_e32 v235, v184
	v_mfma_f32_32x32x16_bf16 v[130:145], v[244:247], v[156:159], v[130:145]
	v_exp_f32_e32 v185, v185
	s_waitcnt lgkmcnt(0)
	s_nop 0
	v_mfma_f32_32x32x16_bf16 v[130:145], v[188:191], v[152:155], v[130:145]
	v_exp_f32_e32 v188, v182
	v_exp_f32_e32 v189, v183
	s_waitcnt lgkmcnt(0)
	v_exp_f32_e32 v190, v180
	v_mfma_f32_32x32x16_bf16 v[130:145], v[192:195], v[148:151], v[130:145]
	v_exp_f32_e32 v191, v181
	v_add_f32_e32 v180, 0, v252
	v_add_f32_e32 v180, v253, v180
	v_add_f32_e32 v180, v232, v180
	v_add_f32_e32 v180, v196, v180
	v_add_f32_e32 v180, v197, v180
	v_add_f32_e32 v180, v236, v180
	v_add_f32_e32 v180, v237, v180
	v_add_f32_e32 v180, v248, v180
	v_add_f32_e32 v180, v186, v180
	v_add_f32_e32 v180, v187, v180
	v_add_f32_e32 v180, v235, v180
	v_add_f32_e32 v180, v185, v180
	v_add_f32_e32 v180, v188, v180
	v_add_f32_e32 v180, v189, v180
	v_add_f32_e32 v180, v190, v180
	v_add_f32_e32 v243, v191, v180
	v_mov_b32_e32 v244, v243
	s_nop 1
	v_permlane32_swap_b32_e32 v243, v244
	v_cvt_pk_bf16_f32 v180, v252, v253
	v_cvt_pk_bf16_f32 v181, v232, v196
	v_cvt_pk_bf16_f32 v182, v197, v236
	v_cvt_pk_bf16_f32 v183, v237, v248
	v_cvt_pk_bf16_f32 v184, v186, v187
	v_cvt_pk_bf16_f32 v185, v235, v185
	v_cvt_pk_bf16_f32 v186, v188, v189
	v_cvt_pk_bf16_f32 v187, v190, v191
	s_nop 0
	v_permlane32_swap_b32_e32 v180, v182
	v_permlane32_swap_b32_e32 v181, v183
	v_permlane32_swap_b32_e32 v184, v186
	v_permlane32_swap_b32_e32 v185, v187
	s_add_i32 s78, s74, 0x10000
	s_and_b32 s3, s78, 0x18000
	v_add_u32_e32 v196, s3, v228
	ds_read_b64_tr_b16 v[188:189], v196 offset:0
	ds_read_b64_tr_b16 v[190:191], v196 offset:0x1000
	ds_read_b64_tr_b16 v[192:193], v196 offset:0x2000
	ds_read_b64_tr_b16 v[194:195], v196 offset:0x3000
	ds_read_b64_tr_b16 v[246:247], v196 offset:0x200
	ds_read_b64_tr_b16 v[248:249], v196 offset:0x1200
	ds_read_b64_tr_b16 v[250:251], v196 offset:0x2200
	ds_read_b64_tr_b16 v[252:253], v196 offset:0x3200
	s_waitcnt lgkmcnt(0)
	s_nop 0
	v_mfma_f32_32x32x16_bf16 v[114:129], v[180:183], v[188:191], v[114:129]
	v_mfma_f32_32x32x16_bf16 v[114:129], v[184:187], v[192:195], v[114:129]
	ds_read_b64_tr_b16 v[188:189], v196 offset:0x400
	ds_read_b64_tr_b16 v[190:191], v196 offset:0x1400
	ds_read_b64_tr_b16 v[192:193], v196 offset:0x2400
	ds_read_b64_tr_b16 v[194:195], v196 offset:0x3400
	s_waitcnt lgkmcnt(0)
	v_mfma_f32_32x32x16_bf16 v[98:113], v[180:183], v[246:249], v[98:113]
	v_mfma_f32_32x32x16_bf16 v[98:113], v[184:187], v[250:253], v[98:113]
	ds_read_b64_tr_b16 v[246:247], v196 offset:0x600
	ds_read_b64_tr_b16 v[248:249], v196 offset:0x1600
	ds_read_b64_tr_b16 v[250:251], v196 offset:0x2600
	ds_read_b64_tr_b16 v[252:253], v196 offset:0x3600
	s_waitcnt lgkmcnt(0)
	v_mfma_f32_32x32x16_bf16 v[82:97], v[180:183], v[188:191], v[82:97]
	v_mfma_f32_32x32x16_bf16 v[82:97], v[184:187], v[192:195], v[82:97]
	ds_read_b64_tr_b16 v[188:189], v196 offset:0x800
	ds_read_b64_tr_b16 v[190:191], v196 offset:0x1800
	ds_read_b64_tr_b16 v[192:193], v196 offset:0x2800
	ds_read_b64_tr_b16 v[194:195], v196 offset:0x3800
	s_waitcnt lgkmcnt(0)
	v_mfma_f32_32x32x16_bf16 v[66:81], v[180:183], v[246:249], v[66:81]
	v_mfma_f32_32x32x16_bf16 v[66:81], v[184:187], v[250:253], v[66:81]
	ds_read_b64_tr_b16 v[246:247], v196 offset:0xa00
	ds_read_b64_tr_b16 v[248:249], v196 offset:0x1a00
	ds_read_b64_tr_b16 v[250:251], v196 offset:0x2a00
	ds_read_b64_tr_b16 v[252:253], v196 offset:0x3a00
	s_waitcnt lgkmcnt(0)
	v_mfma_f32_32x32x16_bf16 v[50:65], v[180:183], v[188:191], v[50:65]
	v_mfma_f32_32x32x16_bf16 v[50:65], v[184:187], v[192:195], v[50:65]
	ds_read_b64_tr_b16 v[188:189], v196 offset:0xc00
	ds_read_b64_tr_b16 v[190:191], v196 offset:0x1c00
	ds_read_b64_tr_b16 v[192:193], v196 offset:0x2c00
	ds_read_b64_tr_b16 v[194:195], v196 offset:0x3c00
	s_waitcnt lgkmcnt(0)
	v_mfma_f32_32x32x16_bf16 v[34:49], v[180:183], v[246:249], v[34:49]
	v_mfma_f32_32x32x16_bf16 v[34:49], v[184:187], v[250:253], v[34:49]
	ds_read_b64_tr_b16 v[246:247], v196 offset:0xe00
	ds_read_b64_tr_b16 v[248:249], v196 offset:0x1e00
	ds_read_b64_tr_b16 v[250:251], v196 offset:0x2e00
	ds_read_b64_tr_b16 v[252:253], v196 offset:0x3e00
	s_waitcnt lgkmcnt(0)
	v_mfma_f32_32x32x16_bf16 v[18:33], v[180:183], v[188:191], v[18:33]
	v_mfma_f32_32x32x16_bf16 v[18:33], v[184:187], v[192:195], v[18:33]
	s_waitcnt lgkmcnt(0)
	v_mfma_f32_32x32x16_bf16 v[2:17], v[180:183], v[246:249], v[2:17]
	s_cmp_le_u32 s93, s33
	v_mfma_f32_32x32x16_bf16 v[2:17], v[184:187], v[250:253], v[2:17]
	s_cbranch_scc1 .LBB0_748
	ds_read2_b32 v[180:181], v240 offset0:58 offset1:59
	v_add_u32_e32 v182, 32, v241
	v_cmp_lt_i32_e32 vcc, -1, v182
	v_mov_b32_e32 v246, 0
	s_waitcnt lgkmcnt(0)
	v_pk_add_f32 v[130:131], v[130:131], v[180:181] op_sel:[0,1] op_sel_hi:[1,0]
	ds_read2_b32 v[180:181], v240 offset0:56 offset1:57
	v_cndmask_b32_e32 v130, v234, v130, vcc
	v_cmp_lt_i32_e32 vcc, 0, v182
	s_waitcnt lgkmcnt(0)
	v_pk_add_f32 v[132:133], v[132:133], v[180:181] op_sel:[0,1] op_sel_hi:[1,0]
	ds_read2_b32 v[180:181], v240 offset0:50 offset1:51
	v_cndmask_b32_e32 v131, v234, v131, vcc
	v_cmp_lt_i32_e32 vcc, 1, v182
	s_waitcnt lgkmcnt(0)
	v_pk_add_f32 v[134:135], v[134:135], v[180:181] op_sel:[0,1] op_sel_hi:[1,0]
	ds_read2_b32 v[180:181], v240 offset0:48 offset1:49
	v_cndmask_b32_e32 v132, v234, v132, vcc
	v_cmp_lt_i32_e32 vcc, 2, v182
	s_waitcnt lgkmcnt(0)
	v_pk_add_f32 v[136:137], v[136:137], v[180:181] op_sel:[0,1] op_sel_hi:[1,0]
	ds_read2_b32 v[180:181], v240 offset0:42 offset1:43
	v_cndmask_b32_e32 v133, v234, v133, vcc
	v_cmp_lt_i32_e32 vcc, 7, v182
	s_waitcnt lgkmcnt(0)
	v_pk_add_f32 v[138:139], v[138:139], v[180:181] op_sel:[0,1] op_sel_hi:[1,0]
	ds_read2_b32 v[180:181], v240 offset0:40 offset1:41
	v_cndmask_b32_e32 v134, v234, v134, vcc
	v_cmp_lt_i32_e32 vcc, 8, v182
	s_waitcnt lgkmcnt(0)
	v_pk_add_f32 v[140:141], v[140:141], v[180:181] op_sel:[0,1] op_sel_hi:[1,0]
	ds_read2_b32 v[180:181], v240 offset0:34 offset1:35
	v_cndmask_b32_e32 v135, v234, v135, vcc
	v_cmp_lt_i32_e32 vcc, 9, v182
	s_waitcnt lgkmcnt(0)
	v_pk_add_f32 v[142:143], v[142:143], v[180:181] op_sel:[0,1] op_sel_hi:[1,0]
	v_cndmask_b32_e32 v136, v234, v136, vcc
	v_cmp_lt_i32_e32 vcc, 10, v182
	ds_read2_b32 v[180:181], v240 offset0:32 offset1:33
	s_waitcnt lgkmcnt(0)
	v_pk_add_f32 v[144:145], v[144:145], v[180:181] op_sel:[0,1] op_sel_hi:[1,0]
	v_cndmask_b32_e32 v137, v234, v137, vcc
	v_cmp_lt_i32_e32 vcc, 15, v182
	s_nop 1
	v_cndmask_b32_e32 v138, v234, v138, vcc
	v_cmp_lt_i32_e32 vcc, 16, v182
	s_nop 1
	v_cndmask_b32_e32 v139, v234, v139, vcc
	v_cmp_lt_i32_e32 vcc, 17, v182
	s_nop 1
	v_cndmask_b32_e32 v140, v234, v140, vcc
	v_cmp_lt_i32_e32 vcc, 18, v182
	s_nop 1
	v_cndmask_b32_e32 v141, v234, v141, vcc
	v_cmp_lt_i32_e32 vcc, 23, v182
	s_nop 1
	v_cndmask_b32_e32 v142, v234, v142, vcc
	v_cmp_lt_i32_e32 vcc, 24, v182
	s_nop 1
	v_cndmask_b32_e32 v143, v234, v143, vcc
	v_cmp_lt_i32_e32 vcc, 25, v182
	s_nop 1
	v_cndmask_b32_e32 v144, v234, v144, vcc
	v_cmp_lt_i32_e32 vcc, 26, v182
	s_nop 1
	v_cndmask_b32_e32 v145, v234, v145, vcc
	s_branch .LBB0_749

.LBB0_759:
	v_cndmask_b32_e64 v209, v247, v242, s[10:11]
	v_sub_f32_e32 v180, v246, v209
	v_mul_f32_e32 v188, 0x3e0293ee, v180
	v_fmamk_f32 v210, v142, 0x3e0293ee, v188
	v_fmamk_f32 v211, v143, 0x3e0293ee, v188
	v_fmamk_f32 v184, v130, 0x3e0293ee, v188
	v_fmamk_f32 v185, v131, 0x3e0293ee, v188
	v_fmamk_f32 v189, v132, 0x3e0293ee, v188
	v_fmamk_f32 v190, v133, 0x3e0293ee, v188
	v_fmamk_f32 v191, v134, 0x3e0293ee, v188
	v_fmamk_f32 v192, v135, 0x3e0293ee, v188
	v_fmamk_f32 v193, v136, 0x3e0293ee, v188
	v_fmamk_f32 v194, v137, 0x3e0293ee, v188
	v_fmamk_f32 v195, v138, 0x3e0293ee, v188
	v_fmamk_f32 v196, v139, 0x3e0293ee, v188
	v_fmamk_f32 v197, v140, 0x3e0293ee, v188
	v_fmamk_f32 v208, v141, 0x3e0293ee, v188
	v_fmamk_f32 v232, v144, 0x3e0293ee, v188
	v_fmac_f32_e32 v188, 0x3e0293ee, v145
	s_and_b32 s2, s74, 0x18000
	s_cmp_lg_u32 0, -1
	s_cselect_b32 s3, 0, 0
	s_add_i32 s2, s2, s3
	v_add_u32_e32 v235, s2, v227
	ds_read_b128 v[130:133], v235 offset:0
	v_add_u32_e32 v236, s2, v226
	ds_read_b128 v[180:183], v236 offset:0
	s_waitcnt lgkmcnt(0)
	v_add_u32_e32 v237, s2, v225
	v_mfma_f32_32x32x16_bf16 v[130:145], v[130:133], v[176:179], 0
	v_exp_f32_e32 v242, v184
	v_exp_f32_e32 v246, v185
	ds_read_b128 v[184:187], v237 offset:0
	s_waitcnt lgkmcnt(0)
	v_add_u32_e32 v247, s2, v224
	v_mfma_f32_32x32x16_bf16 v[130:145], v[180:183], v[172:175], v[130:145]
	ds_read_b128 v[180:183], v247 offset:0
	v_exp_f32_e32 v189, v189
	v_exp_f32_e32 v190, v190
	s_waitcnt lgkmcnt(0)
	v_exp_f32_e32 v191, v191
	v_mfma_f32_32x32x16_bf16 v[130:145], v[184:187], v[168:171], v[130:145]
	ds_read_b128 v[184:187], v235 offset:0x80
	v_exp_f32_e32 v192, v192
	s_waitcnt lgkmcnt(0)
	v_exp_f32_e32 v193, v193
	v_mfma_f32_32x32x16_bf16 v[130:145], v[180:183], v[164:167], v[130:145]
	ds_read_b128 v[180:183], v236 offset:0x80
	v_exp_f32_e32 v194, v194
	s_waitcnt lgkmcnt(0)
	v_exp_f32_e32 v195, v195
	v_mfma_f32_32x32x16_bf16 v[130:145], v[184:187], v[160:163], v[130:145]
	ds_read_b128 v[184:187], v237 offset:0x80
	v_exp_f32_e32 v196, v196
	s_waitcnt lgkmcnt(0)
	v_exp_f32_e32 v197, v197
	v_mfma_f32_32x32x16_bf16 v[130:145], v[180:183], v[156:159], v[130:145]
	ds_read_b128 v[180:183], v247 offset:0x80
	v_exp_f32_e32 v208, v208
	s_waitcnt lgkmcnt(0)
	s_nop 0
	v_mfma_f32_32x32x16_bf16 v[130:145], v[184:187], v[152:155], v[130:145]
	v_exp_f32_e32 v186, v210
	v_exp_f32_e32 v187, v211
	s_waitcnt lgkmcnt(0)
	v_exp_f32_e32 v232, v232
	v_mfma_f32_32x32x16_bf16 v[130:145], v[180:183], v[148:151], v[130:145]
	v_exp_f32_e32 v188, v188
	v_add_f32_e32 v180, 0, v242
	v_add_f32_e32 v180, v246, v180
	v_add_f32_e32 v180, v189, v180
	v_add_f32_e32 v180, v190, v180
	v_add_f32_e32 v180, v191, v180
	v_add_f32_e32 v180, v192, v180
	v_add_f32_e32 v180, v193, v180
	v_add_f32_e32 v180, v194, v180
	v_add_f32_e32 v180, v195, v180
	v_add_f32_e32 v180, v196, v180
	v_add_f32_e32 v180, v197, v180
	v_add_f32_e32 v180, v208, v180
	v_add_f32_e32 v180, v186, v180
	v_add_f32_e32 v180, v187, v180
	v_add_f32_e32 v180, v232, v180
	v_add_f32_e32 v210, v188, v180
	v_mov_b32_e32 v211, v210
	s_nop 1
	v_permlane32_swap_b32_e32 v210, v211
	v_cvt_pk_bf16_f32 v180, v242, v246
	v_cvt_pk_bf16_f32 v181, v189, v190
	v_cvt_pk_bf16_f32 v182, v191, v192
	v_cvt_pk_bf16_f32 v183, v193, v194
	v_cvt_pk_bf16_f32 v184, v195, v196
	v_cvt_pk_bf16_f32 v185, v197, v208
	v_cvt_pk_bf16_f32 v186, v186, v187
	v_cvt_pk_bf16_f32 v187, v232, v188
	s_nop 0
	v_permlane32_swap_b32_e32 v180, v182
	v_permlane32_swap_b32_e32 v181, v183
	v_permlane32_swap_b32_e32 v184, v186
	v_permlane32_swap_b32_e32 v185, v187
	v_add_u32_e32 v196, s34, v228
	ds_read_b64_tr_b16 v[188:189], v196 offset:0
	ds_read_b64_tr_b16 v[190:191], v196 offset:0x1000
	ds_read_b64_tr_b16 v[192:193], v196 offset:0x2000
	ds_read_b64_tr_b16 v[194:195], v196 offset:0x3000
	ds_read_b64_tr_b16 v[246:247], v196 offset:0x200
	ds_read_b64_tr_b16 v[248:249], v196 offset:0x1200
	ds_read_b64_tr_b16 v[250:251], v196 offset:0x2200
	ds_read_b64_tr_b16 v[252:253], v196 offset:0x3200
	s_waitcnt lgkmcnt(0)
	s_nop 0
	v_mfma_f32_32x32x16_bf16 v[114:129], v[180:183], v[188:191], v[114:129]
	v_mfma_f32_32x32x16_bf16 v[114:129], v[184:187], v[192:195], v[114:129]
	ds_read_b64_tr_b16 v[188:189], v196 offset:0x400
	ds_read_b64_tr_b16 v[190:191], v196 offset:0x1400
	ds_read_b64_tr_b16 v[192:193], v196 offset:0x2400
	ds_read_b64_tr_b16 v[194:195], v196 offset:0x3400
	s_waitcnt lgkmcnt(0)
	v_mfma_f32_32x32x16_bf16 v[98:113], v[180:183], v[246:249], v[98:113]
	v_mfma_f32_32x32x16_bf16 v[98:113], v[184:187], v[250:253], v[98:113]
	ds_read_b64_tr_b16 v[246:247], v196 offset:0x600
	ds_read_b64_tr_b16 v[248:249], v196 offset:0x1600
	ds_read_b64_tr_b16 v[250:251], v196 offset:0x2600
	ds_read_b64_tr_b16 v[252:253], v196 offset:0x3600
	s_waitcnt lgkmcnt(0)
	v_mfma_f32_32x32x16_bf16 v[82:97], v[180:183], v[188:191], v[82:97]
	v_mfma_f32_32x32x16_bf16 v[82:97], v[184:187], v[192:195], v[82:97]
	ds_read_b64_tr_b16 v[188:189], v196 offset:0x800
	ds_read_b64_tr_b16 v[190:191], v196 offset:0x1800
	ds_read_b64_tr_b16 v[192:193], v196 offset:0x2800
	ds_read_b64_tr_b16 v[194:195], v196 offset:0x3800
	s_waitcnt lgkmcnt(0)
	v_mfma_f32_32x32x16_bf16 v[66:81], v[180:183], v[246:249], v[66:81]
	v_mfma_f32_32x32x16_bf16 v[66:81], v[184:187], v[250:253], v[66:81]
	ds_read_b64_tr_b16 v[246:247], v196 offset:0xa00
	ds_read_b64_tr_b16 v[248:249], v196 offset:0x1a00
	ds_read_b64_tr_b16 v[250:251], v196 offset:0x2a00
	ds_read_b64_tr_b16 v[252:253], v196 offset:0x3a00
	s_waitcnt lgkmcnt(0)
	v_mfma_f32_32x32x16_bf16 v[50:65], v[180:183], v[188:191], v[50:65]
	v_mfma_f32_32x32x16_bf16 v[50:65], v[184:187], v[192:195], v[50:65]
	ds_read_b64_tr_b16 v[188:189], v196 offset:0xc00
	ds_read_b64_tr_b16 v[190:191], v196 offset:0x1c00
	ds_read_b64_tr_b16 v[192:193], v196 offset:0x2c00
	ds_read_b64_tr_b16 v[194:195], v196 offset:0x3c00
	s_waitcnt lgkmcnt(0)
	v_mfma_f32_32x32x16_bf16 v[34:49], v[180:183], v[246:249], v[34:49]
	v_mfma_f32_32x32x16_bf16 v[34:49], v[184:187], v[250:253], v[34:49]
	ds_read_b64_tr_b16 v[246:247], v196 offset:0xe00
	ds_read_b64_tr_b16 v[248:249], v196 offset:0x1e00
	ds_read_b64_tr_b16 v[250:251], v196 offset:0x2e00
	ds_read_b64_tr_b16 v[252:253], v196 offset:0x3e00
	s_waitcnt lgkmcnt(0)
	v_mfma_f32_32x32x16_bf16 v[18:33], v[180:183], v[188:191], v[18:33]
	v_mfma_f32_32x32x16_bf16 v[18:33], v[184:187], v[192:195], v[18:33]
	s_waitcnt lgkmcnt(0)
	v_mfma_f32_32x32x16_bf16 v[2:17], v[180:183], v[246:249], v[2:17]
	s_add_i32 s2, s93, 0xffffff90
	s_cmp_le_i32 s2, s4
	v_mfma_f32_32x32x16_bf16 v[2:17], v[184:187], v[250:253], v[2:17]
	s_cbranch_scc1 .LBB0_761
	ds_read2_b32 v[180:181], v240 offset0:26 offset1:27
	v_cmp_lt_i32_e32 vcc, -1, v241
	v_mov_b32_e32 v246, 0
	s_waitcnt lgkmcnt(0)
	v_pk_add_f32 v[130:131], v[130:131], v[180:181] op_sel:[0,1] op_sel_hi:[1,0]
	ds_read2_b32 v[180:181], v240 offset0:24 offset1:25
	v_cndmask_b32_e32 v130, v234, v130, vcc
	v_cmp_lt_i32_e32 vcc, 0, v241
	s_waitcnt lgkmcnt(0)
	v_pk_add_f32 v[132:133], v[132:133], v[180:181] op_sel:[0,1] op_sel_hi:[1,0]
	ds_read2_b32 v[180:181], v240 offset0:18 offset1:19
	v_cndmask_b32_e32 v131, v234, v131, vcc
	v_cmp_lt_i32_e32 vcc, 1, v241
	s_waitcnt lgkmcnt(0)
	v_pk_add_f32 v[134:135], v[134:135], v[180:181] op_sel:[0,1] op_sel_hi:[1,0]
	ds_read2_b32 v[180:181], v240 offset0:16 offset1:17
	v_cndmask_b32_e32 v132, v234, v132, vcc
	v_cmp_lt_i32_e32 vcc, 2, v241
	s_waitcnt lgkmcnt(0)
	v_pk_add_f32 v[136:137], v[136:137], v[180:181] op_sel:[0,1] op_sel_hi:[1,0]
	ds_read2_b32 v[180:181], v240 offset0:10 offset1:11
	v_cndmask_b32_e32 v133, v234, v133, vcc
	v_cmp_lt_i32_e32 vcc, 7, v241
	s_waitcnt lgkmcnt(0)
	v_pk_add_f32 v[138:139], v[138:139], v[180:181] op_sel:[0,1] op_sel_hi:[1,0]
	ds_read2_b32 v[180:181], v240 offset0:8 offset1:9
	v_cndmask_b32_e32 v134, v234, v134, vcc
	v_cmp_lt_i32_e32 vcc, 8, v241
	s_waitcnt lgkmcnt(0)
	v_pk_add_f32 v[140:141], v[140:141], v[180:181] op_sel:[0,1] op_sel_hi:[1,0]
	ds_read2_b32 v[180:181], v240 offset0:2 offset1:3
	v_cndmask_b32_e32 v135, v234, v135, vcc
	v_cmp_lt_i32_e32 vcc, 9, v241
	s_waitcnt lgkmcnt(0)
	v_pk_add_f32 v[142:143], v[142:143], v[180:181] op_sel:[0,1] op_sel_hi:[1,0]
	v_cndmask_b32_e32 v136, v234, v136, vcc
	v_cmp_lt_i32_e32 vcc, 10, v241
	ds_read2_b32 v[180:181], v240 offset1:1
	s_waitcnt lgkmcnt(0)
	v_pk_add_f32 v[144:145], v[144:145], v[180:181] op_sel:[0,1] op_sel_hi:[1,0]
	v_cndmask_b32_e32 v137, v234, v137, vcc
	v_cmp_lt_i32_e32 vcc, 15, v241
	s_nop 1
	v_cndmask_b32_e32 v138, v234, v138, vcc
	v_cmp_lt_i32_e32 vcc, 16, v241
	s_nop 1
	v_cndmask_b32_e32 v139, v234, v139, vcc
	v_cmp_lt_i32_e32 vcc, 17, v241
	s_nop 1
	v_cndmask_b32_e32 v140, v234, v140, vcc
	v_cmp_lt_i32_e32 vcc, 18, v241
	s_nop 1
	v_cndmask_b32_e32 v141, v234, v141, vcc
	v_cmp_lt_i32_e32 vcc, 23, v241
	s_nop 1
	v_cndmask_b32_e32 v142, v234, v142, vcc
	v_cmp_lt_i32_e32 vcc, 24, v241
	s_nop 1
	v_cndmask_b32_e32 v143, v234, v143, vcc
	v_cmp_lt_i32_e32 vcc, 25, v241
	s_nop 1
	v_cndmask_b32_e32 v144, v234, v144, vcc
	v_cmp_lt_i32_e32 vcc, 26, v241
	s_nop 1
	v_cndmask_b32_e32 v145, v234, v145, vcc
	s_branch .LBB0_762

.LBB0_768:
	s_waitcnt vmcnt(0)
	s_waitcnt lgkmcnt(0)
	s_barrier
	s_addk_i32 s95, 0x100
	s_cmp_lg_u32 0, -1
	s_cselect_b32 s0, 0, 0
	s_add_i32 s1, s0, 0x18000
	v_add_u32_e32 v0, s1, v227
	ds_read_b128 v[130:133], v0 offset:0
	v_add_u32_e32 v206, s1, v226
	ds_read_b128 v[226:229], v206 offset:0
	s_waitcnt lgkmcnt(0)
	v_add_u32_e32 v207, s1, v225
	v_mfma_f32_32x32x16_bf16 v[130:145], v[130:133], v[176:179], 0
	ds_read_b128 v[176:179], v207 offset:0
	v_exp_f32_e32 v194, v194
	v_exp_f32_e32 v195, v195
	s_waitcnt lgkmcnt(0)
	v_add_u32_e32 v209, s1, v224
	v_mfma_f32_32x32x16_bf16 v[130:145], v[226:229], v[172:175], v[130:145]
	ds_read_b128 v[172:175], v209 offset:0
	v_exp_f32_e32 v192, v192
	v_exp_f32_e32 v193, v193
	s_waitcnt lgkmcnt(0)
	s_nop 0
	v_mfma_f32_32x32x16_bf16 v[130:145], v[176:179], v[168:171], v[130:145]
	ds_read_b128 v[168:171], v0 offset:0x80
	v_exp_f32_e32 v176, v190
	v_exp_f32_e32 v177, v191
	s_waitcnt lgkmcnt(0)
	s_nop 0
	v_mfma_f32_32x32x16_bf16 v[130:145], v[172:175], v[164:167], v[130:145]
	ds_read_b128 v[164:167], v206 offset:0x80
	v_exp_f32_e32 v172, v188
	v_exp_f32_e32 v173, v189
	s_waitcnt lgkmcnt(0)
	s_nop 0
	v_mfma_f32_32x32x16_bf16 v[130:145], v[168:171], v[160:163], v[130:145]
	ds_read_b128 v[160:163], v207 offset:0x80
	v_exp_f32_e32 v168, v186
	v_exp_f32_e32 v169, v187
	s_waitcnt lgkmcnt(0)
	s_nop 0
	v_mfma_f32_32x32x16_bf16 v[130:145], v[164:167], v[156:159], v[130:145]
	v_exp_f32_e32 v164, v184
	v_exp_f32_e32 v165, v185
	ds_read_b128 v[156:159], v209 offset:0x80
	s_waitcnt lgkmcnt(0)
	s_nop 0
	v_mfma_f32_32x32x16_bf16 v[130:145], v[160:163], v[152:155], v[130:145]
	v_exp_f32_e32 v160, v182
	v_exp_f32_e32 v161, v183
	s_waitcnt lgkmcnt(0)
	s_nop 0
	v_mfma_f32_32x32x16_bf16 v[130:145], v[156:159], v[148:151], v[130:145]
	v_exp_f32_e32 v149, v180
	v_exp_f32_e32 v157, v181
	v_add_f32_e32 v0, 0, v194
	v_add_f32_e32 v0, v195, v0
	v_add_f32_e32 v0, v192, v0
	v_add_f32_e32 v0, v193, v0
	v_add_f32_e32 v0, v176, v0
	v_add_f32_e32 v0, v177, v0
	v_add_f32_e32 v0, v172, v0
	v_add_f32_e32 v0, v173, v0
	v_add_f32_e32 v0, v168, v0
	v_add_f32_e32 v0, v169, v0
	v_add_f32_e32 v0, v164, v0
	v_add_f32_e32 v0, v165, v0
	v_add_f32_e32 v0, v160, v0
	v_add_f32_e32 v0, v161, v0
	v_add_f32_e32 v0, v149, v0
	v_add_f32_e32 v0, v157, v0
	v_mov_b32_e32 v148, v0
	v_cvt_pk_bf16_f32 v150, v194, v195
	v_cvt_pk_bf16_f32 v151, v192, v193
	v_cvt_pk_bf16_f32 v152, v176, v177
	v_cvt_pk_bf16_f32 v153, v172, v173
	v_cvt_pk_bf16_f32 v154, v168, v169
	v_cvt_pk_bf16_f32 v155, v164, v165
	v_cvt_pk_bf16_f32 v156, v160, v161
	v_cvt_pk_bf16_f32 v157, v149, v157
	s_nop 1
	v_permlane32_swap_b32_e32 v0, v148
	v_permlane32_swap_b32_e32 v150, v152
	v_permlane32_swap_b32_e32 v151, v153
	v_permlane32_swap_b32_e32 v154, v156
	v_permlane32_swap_b32_e32 v155, v157
	s_add_i32 s0, s0, 0x14000
	v_add_u32_e32 v149, s0, v222
	ds_read_b64_tr_b16 v[158:159], v149 offset:0
	ds_read_b64_tr_b16 v[160:161], v149 offset:0x1000
	ds_read_b64_tr_b16 v[162:163], v149 offset:0x2000
	ds_read_b64_tr_b16 v[164:165], v149 offset:0x3000
	ds_read_b64_tr_b16 v[166:167], v149 offset:0x200
	ds_read_b64_tr_b16 v[168:169], v149 offset:0x1200
	ds_read_b64_tr_b16 v[170:171], v149 offset:0x2200
	ds_read_b64_tr_b16 v[172:173], v149 offset:0x3200
	s_waitcnt lgkmcnt(0)
	s_nop 0
	v_mfma_f32_32x32x16_bf16 v[114:129], v[150:153], v[158:161], v[114:129]
	v_mfma_f32_32x32x16_bf16 v[114:129], v[154:157], v[162:165], v[114:129]
	ds_read_b64_tr_b16 v[158:159], v149 offset:0x400
	ds_read_b64_tr_b16 v[160:161], v149 offset:0x1400
	ds_read_b64_tr_b16 v[162:163], v149 offset:0x2400
	ds_read_b64_tr_b16 v[164:165], v149 offset:0x3400
	s_waitcnt lgkmcnt(0)
	v_mfma_f32_32x32x16_bf16 v[98:113], v[150:153], v[166:169], v[98:113]
	v_mfma_f32_32x32x16_bf16 v[98:113], v[154:157], v[170:173], v[98:113]
	ds_read_b64_tr_b16 v[166:167], v149 offset:0x600
	ds_read_b64_tr_b16 v[168:169], v149 offset:0x1600
	ds_read_b64_tr_b16 v[170:171], v149 offset:0x2600
	ds_read_b64_tr_b16 v[172:173], v149 offset:0x3600
	s_waitcnt lgkmcnt(0)
	v_mfma_f32_32x32x16_bf16 v[82:97], v[150:153], v[158:161], v[82:97]
	v_mfma_f32_32x32x16_bf16 v[82:97], v[154:157], v[162:165], v[82:97]
	ds_read_b64_tr_b16 v[158:159], v149 offset:0x800
	ds_read_b64_tr_b16 v[160:161], v149 offset:0x1800
	ds_read_b64_tr_b16 v[162:163], v149 offset:0x2800
	ds_read_b64_tr_b16 v[164:165], v149 offset:0x3800
	s_waitcnt lgkmcnt(0)
	v_mfma_f32_32x32x16_bf16 v[66:81], v[150:153], v[166:169], v[66:81]
	v_mfma_f32_32x32x16_bf16 v[66:81], v[154:157], v[170:173], v[66:81]
	ds_read_b64_tr_b16 v[166:167], v149 offset:0xa00
	ds_read_b64_tr_b16 v[168:169], v149 offset:0x1a00
	ds_read_b64_tr_b16 v[170:171], v149 offset:0x2a00
	ds_read_b64_tr_b16 v[172:173], v149 offset:0x3a00
	s_waitcnt lgkmcnt(0)
	v_mfma_f32_32x32x16_bf16 v[50:65], v[150:153], v[158:161], v[50:65]
	v_mfma_f32_32x32x16_bf16 v[50:65], v[154:157], v[162:165], v[50:65]
	ds_read_b64_tr_b16 v[158:159], v149 offset:0xc00
	ds_read_b64_tr_b16 v[160:161], v149 offset:0x1c00
	ds_read_b64_tr_b16 v[162:163], v149 offset:0x2c00
	ds_read_b64_tr_b16 v[164:165], v149 offset:0x3c00
	s_waitcnt lgkmcnt(0)
	v_mfma_f32_32x32x16_bf16 v[34:49], v[150:153], v[166:169], v[34:49]
	v_mfma_f32_32x32x16_bf16 v[34:49], v[154:157], v[170:173], v[34:49]
	ds_read_b64_tr_b16 v[166:167], v149 offset:0xe00
	ds_read_b64_tr_b16 v[168:169], v149 offset:0x1e00
	ds_read_b64_tr_b16 v[170:171], v149 offset:0x2e00
	ds_read_b64_tr_b16 v[172:173], v149 offset:0x3e00
	s_waitcnt lgkmcnt(0)
	v_mfma_f32_32x32x16_bf16 v[18:33], v[150:153], v[158:161], v[18:33]
	v_mfma_f32_32x32x16_bf16 v[18:33], v[154:157], v[162:165], v[18:33]
	s_waitcnt lgkmcnt(0)
	v_mfma_f32_32x32x16_bf16 v[2:17], v[150:153], v[166:169], v[2:17]
	s_or_b32 s0, s94, 0x60
	v_subrev_u32_e32 v149, s0, v223
	v_lshl_add_u32 v150, v149, 2, s95
	v_add_u32_e32 v151, -4, v150
	ds_read2_b32 v[152:153], v151 offset1:1
	v_add_u32_e32 v151, -12, v150
	v_cmp_lt_i32_e32 vcc, -1, v149
	v_mfma_f32_32x32x16_bf16 v[2:17], v[154:157], v[170:173], v[2:17]
	ds_read2_b32 v[154:155], v151 offset1:1
	v_subrev_u32_e32 v151, 36, v150
	ds_read2_b32 v[156:157], v151 offset1:1
	v_subrev_u32_e32 v151, 44, v150
	ds_read2_b32 v[158:159], v151 offset1:1
	v_add_u32_e32 v151, 0xffffffbc, v150
	ds_read2_b32 v[160:161], v151 offset1:1
	v_add_u32_e32 v151, 0xffffffb4, v150
	ds_read2_b32 v[162:163], v151 offset1:1
	v_add_u32_e32 v151, 0xffffff9c, v150
	v_add_u32_e32 v150, 0xffffff94, v150
	s_waitcnt lgkmcnt(0)
	v_add_f32_e32 v130, v130, v153
	ds_read2_b32 v[164:165], v151 offset1:1
	ds_read2_b32 v[166:167], v150 offset1:1
	v_cndmask_b32_e32 v150, v234, v130, vcc
	v_add_f32_e32 v130, v131, v152
	v_cmp_lt_i32_e32 vcc, 0, v149
	s_nop 1
	v_cndmask_b32_e32 v151, v234, v130, vcc
	v_add_f32_e32 v130, v132, v155
	v_cmp_lt_i32_e32 vcc, 1, v149
	s_nop 1
	v_cndmask_b32_e32 v152, v234, v130, vcc
	v_add_f32_e32 v130, v133, v154
	v_cmp_lt_i32_e32 vcc, 2, v149
	s_nop 1
	v_cndmask_b32_e32 v153, v234, v130, vcc
	v_add_f32_e32 v130, v134, v157
	v_cmp_lt_i32_e32 vcc, 7, v149
	s_nop 1
	v_cndmask_b32_e32 v154, v234, v130, vcc
	v_add_f32_e32 v130, v135, v156
	v_cmp_lt_i32_e32 vcc, 8, v149
	s_nop 1
	v_cndmask_b32_e32 v155, v234, v130, vcc
	v_add_f32_e32 v130, v136, v159
	v_cmp_lt_i32_e32 vcc, 9, v149
	s_nop 1
	v_cndmask_b32_e32 v156, v234, v130, vcc
	v_add_f32_e32 v130, v137, v158
	v_cmp_lt_i32_e32 vcc, 10, v149
	s_nop 1
	v_cndmask_b32_e32 v157, v234, v130, vcc
	v_add_f32_e32 v130, v138, v161
	v_cmp_lt_i32_e32 vcc, 15, v149
	s_nop 1
	v_cndmask_b32_e32 v158, v234, v130, vcc
	v_add_f32_e32 v130, v139, v160
	v_cmp_lt_i32_e32 vcc, 16, v149
	s_nop 1
	v_cndmask_b32_e32 v159, v234, v130, vcc
	v_add_f32_e32 v130, v140, v163
	v_cmp_lt_i32_e32 vcc, 17, v149
	s_nop 1
	v_cndmask_b32_e32 v160, v234, v130, vcc
	v_add_f32_e32 v130, v141, v162
	v_cmp_lt_i32_e32 vcc, 18, v149
	s_nop 1
	v_cndmask_b32_e32 v161, v234, v130, vcc
	s_waitcnt lgkmcnt(0)
	v_add_f32_e32 v130, v142, v165
	v_cmp_lt_i32_e32 vcc, 23, v149
	s_nop 1
	v_cndmask_b32_e32 v162, v234, v130, vcc
	v_add_f32_e32 v130, v143, v164
	v_cmp_lt_i32_e32 vcc, 24, v149
	s_nop 1
	v_cndmask_b32_e32 v163, v234, v130, vcc
	v_add_f32_e32 v130, v144, v167
	v_cmp_lt_i32_e32 vcc, 25, v149
	s_nop 1
	v_cndmask_b32_e32 v164, v234, v130, vcc
	v_add_f32_e32 v130, v145, v166
	v_cmp_lt_i32_e32 vcc, 26, v149
	s_nop 1
	v_cndmask_b32_e32 v165, v234, v130, vcc
	v_max_f32_e32 v130, v150, v151
	v_max3_f32 v130, v130, v152, v153
	v_max3_f32 v130, v130, v154, v155
	v_max3_f32 v130, v130, v156, v157
	v_max3_f32 v130, v130, v158, v159
	v_max3_f32 v130, v130, v160, v161
	v_max3_f32 v130, v130, v162, v163
	v_max3_f32 v130, v130, v164, v165
	v_mov_b32_e32 v131, v130
	s_nop 1
	v_permlane32_swap_b32_e32 v130, v131
	v_max_f32_e32 v131, v131, v131
	v_max_f32_e32 v130, v130, v130
	v_max_f32_e32 v130, v130, v131
	v_add_f32_e32 v130, 0, v130
	v_sub_f32_e32 v131, v130, v242
	v_mul_f32_e32 v131, 0x3db504f3, v131
	v_cmp_ge_f32_e32 vcc, s75, v131
	v_max_f32_e32 v131, v242, v242
	v_max_f32_e32 v166, v131, v130
	v_sub_f32_e32 v130, v242, v166
	v_mul_f32_e32 v130, 0x3e0293ee, v130
	v_exp_f32_e32 v130, v130
	s_cmp_eq_u64 vcc, exec
	s_cselect_b64 s[10:11], -1, 0
	v_cndmask_b32_e64 v149, v130, 1.0, s[10:11]
	v_cmp_gt_f32_e32 vcc, 1.0, v149
	s_cbranch_vccz .LBB0_772
	s_and_saveexec_b64 s[16:17], s[8:9]
	s_movk_i32 s78, 0x1800
	ds_write_b32 v220, v149 offset:128
	s_or_b64 exec, exec, s[16:17]
	s_waitcnt lgkmcnt(0)
	ds_read_b128 v[142:145], v219 offset:224
	ds_read_b128 v[138:141], v219 offset:192
	ds_read_b128 v[134:137], v219 offset:160
	ds_read_b128 v[130:133], v219 offset:128
	s_waitcnt lgkmcnt(0)
	v_pk_mul_f32 v[128:129], v[128:129], v[144:145]
	v_pk_mul_f32 v[124:125], v[124:125], v[140:141]
	v_pk_mul_f32 v[120:121], v[120:121], v[136:137]
	v_pk_mul_f32 v[116:117], v[116:117], v[132:133]
	v_pk_mul_f32 v[126:127], v[126:127], v[142:143]
	v_pk_mul_f32 v[122:123], v[122:123], v[138:139]
	v_pk_mul_f32 v[118:119], v[118:119], v[134:135]
	v_pk_mul_f32 v[114:115], v[114:115], v[130:131]
	v_pk_mul_f32 v[112:113], v[112:113], v[144:145]
	v_pk_mul_f32 v[108:109], v[108:109], v[140:141]
	v_pk_mul_f32 v[104:105], v[104:105], v[136:137]
	v_pk_mul_f32 v[100:101], v[100:101], v[132:133]
	v_pk_mul_f32 v[110:111], v[110:111], v[142:143]
	v_pk_mul_f32 v[106:107], v[106:107], v[138:139]
	v_pk_mul_f32 v[102:103], v[102:103], v[134:135]
	v_pk_mul_f32 v[98:99], v[98:99], v[130:131]
	v_pk_mul_f32 v[96:97], v[96:97], v[144:145]
	v_pk_mul_f32 v[92:93], v[92:93], v[140:141]
	v_pk_mul_f32 v[88:89], v[88:89], v[136:137]
	v_pk_mul_f32 v[84:85], v[84:85], v[132:133]
	v_pk_mul_f32 v[94:95], v[94:95], v[142:143]
	v_pk_mul_f32 v[90:91], v[90:91], v[138:139]
	v_pk_mul_f32 v[86:87], v[86:87], v[134:135]
	v_pk_mul_f32 v[82:83], v[82:83], v[130:131]
	v_pk_mul_f32 v[80:81], v[80:81], v[144:145]
	v_pk_mul_f32 v[76:77], v[76:77], v[140:141]
	v_pk_mul_f32 v[72:73], v[72:73], v[136:137]
	v_pk_mul_f32 v[68:69], v[68:69], v[132:133]
	v_pk_mul_f32 v[78:79], v[78:79], v[142:143]
	v_pk_mul_f32 v[74:75], v[74:75], v[138:139]
	v_pk_mul_f32 v[70:71], v[70:71], v[134:135]
	v_pk_mul_f32 v[66:67], v[66:67], v[130:131]
	v_pk_mul_f32 v[64:65], v[64:65], v[144:145]
	v_pk_mul_f32 v[60:61], v[60:61], v[140:141]
	v_pk_mul_f32 v[56:57], v[56:57], v[136:137]
	v_pk_mul_f32 v[52:53], v[52:53], v[132:133]
	v_pk_mul_f32 v[62:63], v[62:63], v[142:143]
	v_pk_mul_f32 v[58:59], v[58:59], v[138:139]
	v_pk_mul_f32 v[54:55], v[54:55], v[134:135]
	v_pk_mul_f32 v[50:51], v[50:51], v[130:131]
	v_pk_mul_f32 v[48:49], v[48:49], v[144:145]
	v_pk_mul_f32 v[44:45], v[44:45], v[140:141]
	v_pk_mul_f32 v[40:41], v[40:41], v[136:137]
	v_pk_mul_f32 v[36:37], v[36:37], v[132:133]
	v_pk_mul_f32 v[46:47], v[46:47], v[142:143]
	v_pk_mul_f32 v[42:43], v[42:43], v[138:139]
	v_pk_mul_f32 v[38:39], v[38:39], v[134:135]
	v_pk_mul_f32 v[34:35], v[34:35], v[130:131]
	v_pk_mul_f32 v[32:33], v[32:33], v[144:145]
	v_pk_mul_f32 v[28:29], v[28:29], v[140:141]
	v_pk_mul_f32 v[24:25], v[24:25], v[136:137]
	v_pk_mul_f32 v[20:21], v[20:21], v[132:133]
	v_pk_mul_f32 v[30:31], v[30:31], v[142:143]
	v_pk_mul_f32 v[26:27], v[26:27], v[138:139]
	v_pk_mul_f32 v[22:23], v[22:23], v[134:135]
	v_pk_mul_f32 v[18:19], v[18:19], v[130:131]
	v_pk_mul_f32 v[16:17], v[16:17], v[144:145]
	v_pk_mul_f32 v[12:13], v[12:13], v[140:141]
	v_pk_mul_f32 v[8:9], v[8:9], v[136:137]
	v_pk_mul_f32 v[4:5], v[4:5], v[132:133]
	v_pk_mul_f32 v[14:15], v[14:15], v[142:143]
	v_pk_mul_f32 v[10:11], v[10:11], v[138:139]
	v_pk_mul_f32 v[6:7], v[6:7], v[134:135]
	v_pk_mul_f32 v[2:3], v[2:3], v[130:131]
	s_branch .LBB0_773

.LBB0_773:
	v_cndmask_b32_e64 v130, v166, v242, s[10:11]
	v_mul_f32_e64 v130, -v130, s62
	v_fmamk_f32 v131, v150, 0x3e0293ee, v130
	v_fmamk_f32 v132, v151, 0x3e0293ee, v130
	v_exp_f32_e32 v150, v131
	v_fmamk_f32 v133, v152, 0x3e0293ee, v130
	v_exp_f32_e32 v132, v132
	v_fmamk_f32 v134, v153, 0x3e0293ee, v130
	v_exp_f32_e32 v133, v133
	v_fmamk_f32 v135, v154, 0x3e0293ee, v130
	v_fmamk_f32 v136, v155, 0x3e0293ee, v130
	v_fmamk_f32 v137, v156, 0x3e0293ee, v130
	v_fmamk_f32 v138, v157, 0x3e0293ee, v130
	v_fmamk_f32 v139, v158, 0x3e0293ee, v130
	v_fmamk_f32 v140, v159, 0x3e0293ee, v130
	v_fmamk_f32 v141, v160, 0x3e0293ee, v130
	v_fmamk_f32 v142, v161, 0x3e0293ee, v130
	v_fmamk_f32 v143, v162, 0x3e0293ee, v130
	v_fmamk_f32 v144, v163, 0x3e0293ee, v130
	v_fmamk_f32 v145, v164, 0x3e0293ee, v130
	v_fmac_f32_e32 v130, 0x3e0293ee, v165
	v_exp_f32_e32 v134, v134
	v_exp_f32_e32 v135, v135
	v_exp_f32_e32 v151, v130
	v_add_f32_e32 v130, 0, v150
	v_exp_f32_e32 v136, v136
	v_add_f32_e32 v130, v132, v130
	v_exp_f32_e32 v137, v137
	v_add_f32_e32 v130, v133, v130
	v_exp_f32_e32 v138, v138
	v_add_f32_e32 v130, v134, v130
	v_exp_f32_e32 v139, v139
	v_add_f32_e32 v130, v135, v130
	v_exp_f32_e32 v140, v140
	v_add_f32_e32 v130, v136, v130
	v_exp_f32_e32 v141, v141
	v_add_f32_e32 v130, v137, v130
	v_exp_f32_e32 v142, v142
	v_add_f32_e32 v130, v138, v130
	v_exp_f32_e32 v143, v143
	v_add_f32_e32 v130, v139, v130
	v_exp_f32_e32 v144, v144
	v_add_f32_e32 v130, v140, v130
	v_exp_f32_e32 v145, v145
	v_add_f32_e32 v130, v141, v130
	v_add_f32_e32 v130, v142, v130
	v_add_f32_e32 v130, v143, v130
	v_add_f32_e32 v130, v144, v130
	v_add_f32_e32 v130, v145, v130
	v_add_f32_e32 v130, v151, v130
	v_mov_b32_e32 v131, v130
	s_nop 1
	v_permlane32_swap_b32_e32 v130, v131
	v_cvt_pk_bf16_f32 v132, v150, v132
	v_cvt_pk_bf16_f32 v133, v133, v134
	v_cvt_pk_bf16_f32 v134, v135, v136
	v_cvt_pk_bf16_f32 v135, v137, v138
	v_cvt_pk_bf16_f32 v136, v139, v140
	v_cvt_pk_bf16_f32 v137, v141, v142
	v_cvt_pk_bf16_f32 v138, v143, v144
	v_cvt_pk_bf16_f32 v139, v145, v151
	s_nop 0
	v_permlane32_swap_b32_e32 v132, v134
	v_permlane32_swap_b32_e32 v133, v135
	v_permlane32_swap_b32_e32 v136, v138
	v_permlane32_swap_b32_e32 v137, v139
	s_cmp_lg_u32 0, -1
	s_cselect_b32 s0, 0, 0
	s_add_i32 s0, s0, 0x1c000
	v_add_u32_e32 v144, s0, v222
	ds_read_b64_tr_b16 v[140:141], v144 offset:0
	ds_read_b64_tr_b16 v[142:143], v144 offset:0x1000
	ds_read_b64_tr_b16 v[150:151], v144 offset:0x2000
	ds_read_b64_tr_b16 v[152:153], v144 offset:0x3000
	ds_read_b64_tr_b16 v[154:155], v144 offset:0x200
	ds_read_b64_tr_b16 v[156:157], v144 offset:0x1200
	ds_read_b64_tr_b16 v[158:159], v144 offset:0x2200
	ds_read_b64_tr_b16 v[160:161], v144 offset:0x3200
	s_waitcnt lgkmcnt(0)
	s_nop 0
	v_mfma_f32_32x32x16_bf16 v[114:129], v[132:135], v[140:143], v[114:129]
	v_mfma_f32_32x32x16_bf16 v[114:129], v[136:139], v[150:153], v[114:129]
	ds_read_b64_tr_b16 v[140:141], v144 offset:0x400
	ds_read_b64_tr_b16 v[142:143], v144 offset:0x1400
	ds_read_b64_tr_b16 v[150:151], v144 offset:0x2400
	ds_read_b64_tr_b16 v[152:153], v144 offset:0x3400
	s_waitcnt lgkmcnt(0)
	v_mfma_f32_32x32x16_bf16 v[98:113], v[132:135], v[154:157], v[98:113]
	v_mfma_f32_32x32x16_bf16 v[98:113], v[136:139], v[158:161], v[98:113]
	ds_read_b64_tr_b16 v[154:155], v144 offset:0x600
	ds_read_b64_tr_b16 v[156:157], v144 offset:0x1600
	ds_read_b64_tr_b16 v[158:159], v144 offset:0x2600
	ds_read_b64_tr_b16 v[160:161], v144 offset:0x3600
	s_waitcnt lgkmcnt(0)
	v_mfma_f32_32x32x16_bf16 v[82:97], v[132:135], v[140:143], v[82:97]
	v_mfma_f32_32x32x16_bf16 v[82:97], v[136:139], v[150:153], v[82:97]
	ds_read_b64_tr_b16 v[140:141], v144 offset:0x800
	ds_read_b64_tr_b16 v[142:143], v144 offset:0x1800
	ds_read_b64_tr_b16 v[150:151], v144 offset:0x2800
	ds_read_b64_tr_b16 v[152:153], v144 offset:0x3800
	s_waitcnt lgkmcnt(0)
	v_mfma_f32_32x32x16_bf16 v[66:81], v[132:135], v[154:157], v[66:81]
	v_mfma_f32_32x32x16_bf16 v[66:81], v[136:139], v[158:161], v[66:81]
	ds_read_b64_tr_b16 v[154:155], v144 offset:0xa00
	ds_read_b64_tr_b16 v[156:157], v144 offset:0x1a00
	ds_read_b64_tr_b16 v[158:159], v144 offset:0x2a00
	ds_read_b64_tr_b16 v[160:161], v144 offset:0x3a00
	s_waitcnt lgkmcnt(0)
	v_mfma_f32_32x32x16_bf16 v[50:65], v[132:135], v[140:143], v[50:65]
	v_mfma_f32_32x32x16_bf16 v[50:65], v[136:139], v[150:153], v[50:65]
	ds_read_b64_tr_b16 v[140:141], v144 offset:0xc00
	ds_read_b64_tr_b16 v[142:143], v144 offset:0x1c00
	ds_read_b64_tr_b16 v[150:151], v144 offset:0x2c00
	ds_read_b64_tr_b16 v[152:153], v144 offset:0x3c00
	s_waitcnt lgkmcnt(0)
	v_mfma_f32_32x32x16_bf16 v[34:49], v[132:135], v[154:157], v[34:49]
	v_mfma_f32_32x32x16_bf16 v[34:49], v[136:139], v[158:161], v[34:49]
	ds_read_b64_tr_b16 v[154:155], v144 offset:0xe00
	ds_read_b64_tr_b16 v[156:157], v144 offset:0x1e00
	ds_read_b64_tr_b16 v[158:159], v144 offset:0x2e00
	ds_read_b64_tr_b16 v[160:161], v144 offset:0x3e00
	s_waitcnt lgkmcnt(0)
	v_mfma_f32_32x32x16_bf16 v[18:33], v[132:135], v[140:143], v[18:33]
	v_mfma_f32_32x32x16_bf16 v[18:33], v[136:139], v[150:153], v[18:33]
	s_waitcnt lgkmcnt(0)
	v_mfma_f32_32x32x16_bf16 v[2:17], v[132:135], v[154:157], v[2:17]
	v_mfma_f32_32x32x16_bf16 v[2:17], v[136:139], v[158:161], v[2:17]
	s_and_saveexec_b64 s[10:11], s[8:9]
	v_add_f32_e32 v0, v0, v148
	v_fmac_f32_e32 v0, v221, v208
	v_add_f32_e32 v130, v130, v131
	v_fmac_f32_e32 v130, v0, v149
	ds_write_b32 v220, v130
	s_or_b64 exec, exec, s[10:11]
	s_waitcnt lgkmcnt(0)
	ds_read_b128 v[134:137], v219
	ds_read_b128 v[138:141], v219 offset:32
	ds_read_b128 v[142:145], v219 offset:64
	s_lshl_b32 s0, s85, 15
	s_add_i32 s0, s0, 0
	s_waitcnt lgkmcnt(0)
	v_rcp_f32_e32 v132, v136
	v_rcp_f32_e32 v131, v137
	v_rcp_f32_e32 v130, v138
	v_rcp_f32_e32 v186, v139
	ds_read_b128 v[136:139], v219 offset:96
	v_rcp_f32_e32 v134, v134
	v_rcp_f32_e32 v133, v135
	v_rcp_f32_e32 v193, v140
	v_rcp_f32_e32 v192, v141
	v_rcp_f32_e32 v191, v142
	v_rcp_f32_e32 v190, v143
	v_rcp_f32_e32 v189, v144
	v_rcp_f32_e32 v188, v145
	s_waitcnt lgkmcnt(0)
	v_rcp_f32_e32 v187, v136
	v_rcp_f32_e32 v185, v137
	v_rcp_f32_e32 v183, v138
	v_rcp_f32_e32 v0, v139
	s_waitcnt lgkmcnt(0)
	s_barrier
	v_lshlrev_b32_e32 v135, 12, v216
	s_cmp_lg_u32 s5, 1
	v_add3_u32 v182, s0, v218, v135
	s_cbranch_scc1 .LBB0_777
	v_mul_f32_e32 v135, v147, v134
	v_mul_f32_e32 v136, v114, v135
	v_mul_f32_e32 v137, v98, v135
	ds_write2_b32 v182, v136, v137 offset1:32
	v_mul_f32_e32 v136, v82, v135
	v_mul_f32_e32 v137, v66, v135
	ds_write2_b32 v182, v136, v137 offset0:64 offset1:96
	v_mul_f32_e32 v136, v50, v135
	v_mul_f32_e32 v137, v34, v135
	ds_write2_b32 v182, v136, v137 offset0:128 offset1:160
	v_mul_f32_e32 v136, v18, v135
	v_mul_f32_e32 v135, v2, v135
	ds_write2_b32 v182, v136, v135 offset0:192 offset1:224
	v_mul_f32_e32 v135, v147, v133
	v_mul_f32_e32 v136, v115, v135
	v_mul_f32_e32 v137, v99, v135
	v_add_u32_e32 v138, 0x400, v182
	ds_write2_b32 v138, v136, v137 offset1:32
	v_mul_f32_e32 v136, v83, v135
	v_mul_f32_e32 v137, v67, v135
	ds_write2_b32 v138, v136, v137 offset0:64 offset1:96
	v_mul_f32_e32 v136, v51, v135
	v_mul_f32_e32 v137, v35, v135
	ds_write2_b32 v138, v136, v137 offset0:128 offset1:160
	v_mul_f32_e32 v136, v19, v135
	v_mul_f32_e32 v135, v3, v135
	ds_write2_b32 v138, v136, v135 offset0:192 offset1:224
	v_mul_f32_e32 v135, v147, v132
	v_mul_f32_e32 v136, v116, v135
	v_mul_f32_e32 v137, v100, v135
	v_add_u32_e32 v138, 0x800, v182
	ds_write2_b32 v138, v136, v137 offset1:32
	v_mul_f32_e32 v136, v84, v135
	v_mul_f32_e32 v137, v68, v135
	ds_write2_b32 v138, v136, v137 offset0:64 offset1:96
	v_mul_f32_e32 v136, v52, v135
	v_mul_f32_e32 v137, v36, v135
	ds_write2_b32 v138, v136, v137 offset0:128 offset1:160
	v_mul_f32_e32 v136, v20, v135
	v_mul_f32_e32 v135, v4, v135
	ds_write2_b32 v138, v136, v135 offset0:192 offset1:224
	v_mul_f32_e32 v135, v147, v131
	v_mul_f32_e32 v136, v117, v135
	v_mul_f32_e32 v137, v101, v135
	v_add_u32_e32 v138, 0xc00, v182
	ds_write2_b32 v138, v136, v137 offset1:32
	v_mul_f32_e32 v136, v85, v135
	v_mul_f32_e32 v137, v69, v135
	ds_write2_b32 v138, v136, v137 offset0:64 offset1:96
	v_mul_f32_e32 v136, v53, v135
	v_mul_f32_e32 v137, v37, v135
	ds_write2_b32 v138, v136, v137 offset0:128 offset1:160
	v_mul_f32_e32 v136, v21, v135
	v_mul_f32_e32 v135, v5, v135
	ds_write2_b32 v138, v136, v135 offset0:192 offset1:224
	v_mul_f32_e32 v135, v147, v130
	v_mul_f32_e32 v136, v118, v135
	v_mul_f32_e32 v137, v102, v135
	v_add_u32_e32 v138, 0x2000, v182
	ds_write2_b32 v138, v136, v137 offset1:32
	v_mul_f32_e32 v136, v86, v135
	v_mul_f32_e32 v137, v70, v135
	ds_write2_b32 v138, v136, v137 offset0:64 offset1:96
	v_mul_f32_e32 v136, v54, v135
	v_mul_f32_e32 v137, v38, v135
	ds_write2_b32 v138, v136, v137 offset0:128 offset1:160
	v_mul_f32_e32 v136, v22, v135
	v_mul_f32_e32 v135, v6, v135
	ds_write2_b32 v138, v136, v135 offset0:192 offset1:224
	v_mul_f32_e32 v135, v147, v186
	v_mul_f32_e32 v136, v119, v135
	v_mul_f32_e32 v137, v103, v135
	v_add_u32_e32 v138, 0x2400, v182
	ds_write2_b32 v138, v136, v137 offset1:32
	v_mul_f32_e32 v136, v87, v135
	v_mul_f32_e32 v137, v71, v135
	ds_write2_b32 v138, v136, v137 offset0:64 offset1:96
	v_mul_f32_e32 v136, v55, v135
	v_mul_f32_e32 v137, v39, v135
	ds_write2_b32 v138, v136, v137 offset0:128 offset1:160
	v_mul_f32_e32 v136, v23, v135
	v_mul_f32_e32 v135, v7, v135
	ds_write2_b32 v138, v136, v135 offset0:192 offset1:224
	v_mul_f32_e32 v135, v147, v193
	v_mul_f32_e32 v136, v120, v135
	v_mul_f32_e32 v137, v104, v135
	v_add_u32_e32 v138, 0x2800, v182
	ds_write2_b32 v138, v136, v137 offset1:32
	v_mul_f32_e32 v136, v88, v135
	v_mul_f32_e32 v137, v72, v135
	ds_write2_b32 v138, v136, v137 offset0:64 offset1:96
	v_mul_f32_e32 v136, v56, v135
	v_mul_f32_e32 v137, v40, v135
	ds_write2_b32 v138, v136, v137 offset0:128 offset1:160
	v_mul_f32_e32 v136, v24, v135
	v_mul_f32_e32 v135, v8, v135
	ds_write2_b32 v138, v136, v135 offset0:192 offset1:224
	v_mul_f32_e32 v135, v147, v192
	v_mul_f32_e32 v136, v121, v135
	v_mul_f32_e32 v137, v105, v135
	v_add_u32_e32 v138, 0x2c00, v182
	ds_write2_b32 v138, v136, v137 offset1:32
	v_mul_f32_e32 v136, v89, v135
	v_mul_f32_e32 v137, v73, v135
	ds_write2_b32 v138, v136, v137 offset0:64 offset1:96
	v_mul_f32_e32 v136, v57, v135
	v_mul_f32_e32 v137, v41, v135
	ds_write2_b32 v138, v136, v137 offset0:128 offset1:160
	v_mul_f32_e32 v136, v25, v135
	v_mul_f32_e32 v135, v9, v135
	ds_write2_b32 v138, v136, v135 offset0:192 offset1:224
	v_mul_f32_e32 v135, v147, v191
	v_mul_f32_e32 v136, v122, v135
	v_mul_f32_e32 v137, v106, v135
	v_add_u32_e32 v138, 0x4000, v182
	ds_write2_b32 v138, v136, v137 offset1:32
	v_mul_f32_e32 v136, v90, v135
	v_mul_f32_e32 v137, v74, v135
	ds_write2_b32 v138, v136, v137 offset0:64 offset1:96
	v_mul_f32_e32 v136, v58, v135
	v_mul_f32_e32 v137, v42, v135
	ds_write2_b32 v138, v136, v137 offset0:128 offset1:160
	v_mul_f32_e32 v136, v26, v135
	v_mul_f32_e32 v135, v10, v135
	ds_write2_b32 v138, v136, v135 offset0:192 offset1:224
	v_mul_f32_e32 v135, v147, v190
	v_mul_f32_e32 v136, v123, v135
	v_mul_f32_e32 v137, v107, v135
	v_add_u32_e32 v138, 0x4400, v182
	ds_write2_b32 v138, v136, v137 offset1:32
	v_mul_f32_e32 v136, v91, v135
	v_mul_f32_e32 v137, v75, v135
	ds_write2_b32 v138, v136, v137 offset0:64 offset1:96
	v_mul_f32_e32 v136, v59, v135
	v_mul_f32_e32 v137, v43, v135
	ds_write2_b32 v138, v136, v137 offset0:128 offset1:160
	v_mul_f32_e32 v136, v27, v135
	v_mul_f32_e32 v135, v11, v135
	ds_write2_b32 v138, v136, v135 offset0:192 offset1:224
	v_mul_f32_e32 v135, v147, v189
	v_mul_f32_e32 v136, v124, v135
	v_mul_f32_e32 v137, v108, v135
	v_add_u32_e32 v138, 0x4800, v182
	ds_write2_b32 v138, v136, v137 offset1:32
	v_mul_f32_e32 v136, v92, v135
	v_mul_f32_e32 v137, v76, v135
	ds_write2_b32 v138, v136, v137 offset0:64 offset1:96
	v_mul_f32_e32 v136, v60, v135
	v_mul_f32_e32 v137, v44, v135
	ds_write2_b32 v138, v136, v137 offset0:128 offset1:160
	v_mul_f32_e32 v136, v28, v135
	v_mul_f32_e32 v135, v12, v135
	ds_write2_b32 v138, v136, v135 offset0:192 offset1:224
	v_mul_f32_e32 v135, v147, v188
	v_mul_f32_e32 v136, v125, v135
	v_mul_f32_e32 v137, v109, v135
	v_add_u32_e32 v138, 0x4c00, v182
	ds_write2_b32 v138, v136, v137 offset1:32
	v_mul_f32_e32 v136, v93, v135
	v_mul_f32_e32 v137, v77, v135
	ds_write2_b32 v138, v136, v137 offset0:64 offset1:96
	v_mul_f32_e32 v136, v61, v135
	v_mul_f32_e32 v137, v45, v135
	ds_write2_b32 v138, v136, v137 offset0:128 offset1:160
	v_mul_f32_e32 v136, v29, v135
	v_mul_f32_e32 v135, v13, v135
	ds_write2_b32 v138, v136, v135 offset0:192 offset1:224
	v_mul_f32_e32 v135, v147, v187
	v_mul_f32_e32 v136, v126, v135
	v_mul_f32_e32 v137, v110, v135
	v_add_u32_e32 v138, 0x6000, v182
	ds_write2_b32 v138, v136, v137 offset1:32
	v_mul_f32_e32 v136, v94, v135
	v_mul_f32_e32 v137, v78, v135
	ds_write2_b32 v138, v136, v137 offset0:64 offset1:96
	v_mul_f32_e32 v136, v62, v135
	v_mul_f32_e32 v137, v46, v135
	ds_write2_b32 v138, v136, v137 offset0:128 offset1:160
	v_mul_f32_e32 v136, v30, v135
	v_mul_f32_e32 v135, v14, v135
	ds_write2_b32 v138, v136, v135 offset0:192 offset1:224
	v_mul_f32_e32 v135, v147, v185
	v_mul_f32_e32 v136, v127, v135
	v_mul_f32_e32 v137, v111, v135
	v_add_u32_e32 v138, 0x6400, v182
	ds_write2_b32 v138, v136, v137 offset1:32
	v_mul_f32_e32 v136, v95, v135
	v_mul_f32_e32 v137, v79, v135
	ds_write2_b32 v138, v136, v137 offset0:64 offset1:96
	v_mul_f32_e32 v136, v63, v135
	v_mul_f32_e32 v137, v47, v135
	ds_write2_b32 v138, v136, v137 offset0:128 offset1:160
	v_mul_f32_e32 v136, v31, v135
	v_mul_f32_e32 v135, v15, v135
	ds_write2_b32 v138, v136, v135 offset0:192 offset1:224
	v_mul_f32_e32 v135, v147, v183
	v_mul_f32_e32 v136, v128, v135
	v_mul_f32_e32 v137, v112, v135
	v_add_u32_e32 v138, 0x6800, v182
	ds_write2_b32 v138, v136, v137 offset1:32
	v_mul_f32_e32 v136, v96, v135
	v_mul_f32_e32 v137, v80, v135
	ds_write2_b32 v138, v136, v137 offset0:64 offset1:96
	v_mul_f32_e32 v136, v64, v135
	v_mul_f32_e32 v137, v48, v135
	ds_write2_b32 v138, v136, v137 offset0:128 offset1:160
	v_mul_f32_e32 v136, v32, v135
	v_mul_f32_e32 v135, v16, v135
	ds_write2_b32 v138, v136, v135 offset0:192 offset1:224
	v_mul_f32_e32 v135, v147, v0
	v_mul_f32_e32 v136, v129, v135
	v_mul_f32_e32 v137, v113, v135
	v_add_u32_e32 v138, 0x6c00, v182
	ds_write2_b32 v138, v136, v137 offset1:32
	v_mul_f32_e32 v136, v97, v135
	v_mul_f32_e32 v137, v81, v135
	ds_write2_b32 v138, v136, v137 offset0:64 offset1:96
	v_mul_f32_e32 v136, v65, v135
	v_mul_f32_e32 v137, v49, v135
	ds_write2_b32 v138, v136, v137 offset0:128 offset1:160
	v_mul_f32_e32 v136, v33, v135
	v_mul_f32_e32 v135, v17, v135
	ds_write2_b32 v138, v136, v135 offset0:192 offset1:224

.LBB0_1102:
	s_add_u32 s2, s22, 0xfff80080
	s_addc_u32 s20, s23, -1
	s_add_i32 s45, 0, 0x10000
	s_cmp_eq_u32 s44, 28
	s_cselect_b32 s25, s15, s20
	s_cselect_b32 s24, s40, s2
	s_cselect_b32 s21, s13, s43
	s_cselect_b32 s20, s41, s42
	s_add_u32 s100, s22, 0xfff80000
	s_addc_u32 s101, s23, -1
	s_add_i32 s2, 0, 0x14000
	v_add_u32_e32 v142, s45, v226
	v_add_u32_e32 v160, s2, v226
	s_mov_b32 m0, s38
	ds_read_b128 v[130:133], v142
	ds_read_b128 v[134:137], v142 offset:1024
	ds_read_b128 v[138:141], v142 offset:2048
	ds_read_b128 v[142:145], v142 offset:3072
	global_load_lds_dwordx4 v194, s[100:101]
	s_mov_b32 m0, s39
	ds_read_b128 v[148:151], v160
	ds_read_b128 v[152:155], v160 offset:1024
	ds_read_b128 v[156:159], v160 offset:2048
	ds_read_b128 v[160:163], v160 offset:3072
	global_load_lds_dwordx4 v206, s[100:101]
	s_add_i32 m0, s30, 0xc000
	ds_read_b128 v[164:167], v228
	ds_read_b128 v[168:171], v228 offset:1024
	ds_read_b128 v[172:175], v228 offset:2048
	ds_read_b128 v[176:179], v228 offset:3072
	global_load_lds_dwordx4 v194, s[22:23]
	s_add_i32 m0, s30, 0xe000
	ds_read_b128 v[180:183], v228 offset:4096
	ds_read_b128 v[184:187], v228 offset:5120
	ds_read_b128 v[208:211], v228 offset:6144
	ds_read_b128 v[212:215], v228 offset:7168
	global_load_lds_dwordx4 v206, s[22:23]
	s_waitcnt vmcnt(8)
	s_waitcnt lgkmcnt(0)
	s_barrier
	s_waitcnt lgkmcnt(0)
	v_mfma_f32_16x16x32_bf16 v[126:129], v[130:133], v[164:167], v[126:129]
	v_mfma_f32_16x16x32_bf16 v[122:125], v[138:141], v[164:167], v[122:125]
	v_mfma_f32_16x16x32_bf16 v[110:113], v[130:133], v[172:175], v[110:113]
	v_mfma_f32_16x16x32_bf16 v[106:109], v[138:141], v[172:175], v[106:109]
	v_mfma_f32_16x16x32_bf16 v[94:97], v[130:133], v[180:183], v[94:97]
	v_mfma_f32_16x16x32_bf16 v[90:93], v[138:141], v[180:183], v[90:93]
	v_mfma_f32_16x16x32_bf16 v[78:81], v[130:133], v[208:211], v[78:81]
	v_mfma_f32_16x16x32_bf16 v[74:77], v[138:141], v[208:211], v[74:77]
	v_mfma_f32_16x16x32_bf16 v[126:129], v[134:137], v[168:171], v[126:129]
	v_mfma_f32_16x16x32_bf16 v[122:125], v[142:145], v[168:171], v[122:125]
	v_mfma_f32_16x16x32_bf16 v[110:113], v[134:137], v[176:179], v[110:113]
	v_mfma_f32_16x16x32_bf16 v[106:109], v[142:145], v[176:179], v[106:109]
	s_setprio 1
	v_mfma_f32_16x16x32_bf16 v[94:97], v[134:137], v[184:187], v[94:97]
	v_mfma_f32_16x16x32_bf16 v[90:93], v[142:145], v[184:187], v[90:93]
	v_mfma_f32_16x16x32_bf16 v[78:81], v[134:137], v[212:215], v[78:81]
	v_mfma_f32_16x16x32_bf16 v[74:77], v[142:145], v[212:215], v[74:77]
	v_mfma_f32_16x16x32_bf16 v[118:121], v[148:151], v[164:167], v[118:121]
	v_mfma_f32_16x16x32_bf16 v[114:117], v[156:159], v[164:167], v[114:117]
	v_mfma_f32_16x16x32_bf16 v[102:105], v[148:151], v[172:175], v[102:105]
	v_mfma_f32_16x16x32_bf16 v[98:101], v[156:159], v[172:175], v[98:101]
	v_mfma_f32_16x16x32_bf16 v[86:89], v[148:151], v[180:183], v[86:89]
	v_mfma_f32_16x16x32_bf16 v[82:85], v[156:159], v[180:183], v[82:85]
	v_mfma_f32_16x16x32_bf16 v[70:73], v[148:151], v[208:211], v[70:73]
	v_mfma_f32_16x16x32_bf16 v[66:69], v[156:159], v[208:211], v[66:69]
	v_mfma_f32_16x16x32_bf16 v[118:121], v[152:155], v[168:171], v[118:121]
	v_mfma_f32_16x16x32_bf16 v[114:117], v[160:163], v[168:171], v[114:117]
	v_mfma_f32_16x16x32_bf16 v[102:105], v[152:155], v[176:179], v[102:105]
	v_mfma_f32_16x16x32_bf16 v[98:101], v[160:163], v[176:179], v[98:101]
	v_mfma_f32_16x16x32_bf16 v[86:89], v[152:155], v[184:187], v[86:89]
	v_mfma_f32_16x16x32_bf16 v[82:85], v[160:163], v[184:187], v[82:85]
	v_mfma_f32_16x16x32_bf16 v[70:73], v[152:155], v[212:215], v[70:73]
	v_mfma_f32_16x16x32_bf16 v[66:69], v[160:163], v[212:215], v[66:69]
	s_setprio 0
	s_barrier
	s_add_u32 s46, s20, 0x80000
	s_addc_u32 s47, s21, 0
	s_add_i32 s45, s45, s29
	s_mov_b32 m0, s45
	ds_read_b128 v[164:167], v228 offset:16384
	ds_read_b128 v[168:171], v228 offset:17408
	global_load_lds_dwordx4 v0, s[20:21]
	s_add_i32 m0, s45, 0x2000
	s_add_i32 s2, s2, s29
	ds_read_b128 v[172:175], v228 offset:18432
	ds_read_b128 v[176:179], v228 offset:19456
	global_load_lds_dwordx4 v188, s[20:21]
	s_mov_b32 m0, s2
	ds_read_b128 v[180:183], v228 offset:20480
	ds_read_b128 v[184:187], v228 offset:21504
	global_load_lds_dwordx4 v0, s[46:47]
	s_add_i32 m0, s2, 0x2000
	ds_read_b128 v[208:211], v228 offset:22528
	ds_read_b128 v[212:215], v228 offset:23552
	global_load_lds_dwordx4 v188, s[46:47]
	s_waitcnt vmcnt(6)
	s_waitcnt lgkmcnt(0)
	s_barrier
	s_waitcnt lgkmcnt(0)
	v_mfma_f32_16x16x32_bf16 v[62:65], v[130:133], v[164:167], v[62:65]
	v_mfma_f32_16x16x32_bf16 v[58:61], v[138:141], v[164:167], v[58:61]
	v_mfma_f32_16x16x32_bf16 v[46:49], v[130:133], v[172:175], v[46:49]
	v_mfma_f32_16x16x32_bf16 v[42:45], v[138:141], v[172:175], v[42:45]
	v_mfma_f32_16x16x32_bf16 v[30:33], v[130:133], v[180:183], v[30:33]
	v_mfma_f32_16x16x32_bf16 v[26:29], v[138:141], v[180:183], v[26:29]
	v_mfma_f32_16x16x32_bf16 v[14:17], v[130:133], v[208:211], v[14:17]
	v_mfma_f32_16x16x32_bf16 v[10:13], v[138:141], v[208:211], v[10:13]
	v_mfma_f32_16x16x32_bf16 v[62:65], v[134:137], v[168:171], v[62:65]
	v_mfma_f32_16x16x32_bf16 v[58:61], v[142:145], v[168:171], v[58:61]
	v_mfma_f32_16x16x32_bf16 v[46:49], v[134:137], v[176:179], v[46:49]
	v_mfma_f32_16x16x32_bf16 v[42:45], v[142:145], v[176:179], v[42:45]
	s_setprio 1
	v_mfma_f32_16x16x32_bf16 v[30:33], v[134:137], v[184:187], v[30:33]
	v_mfma_f32_16x16x32_bf16 v[26:29], v[142:145], v[184:187], v[26:29]
	v_mfma_f32_16x16x32_bf16 v[14:17], v[134:137], v[212:215], v[14:17]
	v_mfma_f32_16x16x32_bf16 v[10:13], v[142:145], v[212:215], v[10:13]
	v_mfma_f32_16x16x32_bf16 v[54:57], v[148:151], v[164:167], v[54:57]
	v_mfma_f32_16x16x32_bf16 v[50:53], v[156:159], v[164:167], v[50:53]
	v_mfma_f32_16x16x32_bf16 v[38:41], v[148:151], v[172:175], v[38:41]
	v_mfma_f32_16x16x32_bf16 v[34:37], v[156:159], v[172:175], v[34:37]
	v_mfma_f32_16x16x32_bf16 v[22:25], v[148:151], v[180:183], v[22:25]
	v_mfma_f32_16x16x32_bf16 v[18:21], v[156:159], v[180:183], v[18:21]
	v_mfma_f32_16x16x32_bf16 v[6:9], v[148:151], v[208:211], v[6:9]
	v_mfma_f32_16x16x32_bf16 v[2:5], v[156:159], v[208:211], v[2:5]
	v_mfma_f32_16x16x32_bf16 v[54:57], v[152:155], v[168:171], v[54:57]
	v_mfma_f32_16x16x32_bf16 v[50:53], v[160:163], v[168:171], v[50:53]
	v_mfma_f32_16x16x32_bf16 v[38:41], v[152:155], v[176:179], v[38:41]
	v_mfma_f32_16x16x32_bf16 v[34:37], v[160:163], v[176:179], v[34:37]
	v_mfma_f32_16x16x32_bf16 v[22:25], v[152:155], v[184:187], v[22:25]
	v_mfma_f32_16x16x32_bf16 v[18:21], v[160:163], v[184:187], v[18:21]
	v_mfma_f32_16x16x32_bf16 v[6:9], v[152:155], v[212:215], v[6:9]
	v_mfma_f32_16x16x32_bf16 v[2:5], v[160:163], v[212:215], v[2:5]
	s_setprio 0
	s_barrier
	s_add_u32 s24, s24, 0x80000
	s_addc_u32 s25, s25, 0
	s_add_u32 s100, s24, 0xfff80000
	s_addc_u32 s101, s25, -1
	s_add_i32 s2, 0, 0x18000
	s_add_i32 s45, 0, 0x1c000
	v_add_u32_e32 v142, s2, v226
	v_add_u32_e32 v160, s45, v226
	s_mov_b32 m0, s30
	ds_read_b128 v[130:133], v142
	ds_read_b128 v[134:137], v142 offset:1024
	ds_read_b128 v[138:141], v142 offset:2048
	ds_read_b128 v[142:145], v142 offset:3072
	global_load_lds_dwordx4 v192, s[100:101]
	s_mov_b32 m0, s31
	ds_read_b128 v[148:151], v160
	ds_read_b128 v[152:155], v160 offset:1024
	ds_read_b128 v[156:159], v160 offset:2048
	ds_read_b128 v[160:163], v160 offset:3072
	global_load_lds_dwordx4 v190, s[100:101]
	s_mov_b32 m0, s35
	ds_read_b128 v[164:167], v228 offset:32768
	ds_read_b128 v[168:171], v228 offset:33792
	ds_read_b128 v[172:175], v228 offset:34816
	ds_read_b128 v[176:179], v228 offset:35840
	global_load_lds_dwordx4 v192, s[24:25]
	s_mov_b32 m0, s36
	ds_read_b128 v[180:183], v228 offset:36864
	ds_read_b128 v[184:187], v228 offset:37888
	ds_read_b128 v[208:211], v228 offset:38912
	ds_read_b128 v[212:215], v228 offset:39936
	global_load_lds_dwordx4 v190, s[24:25]
	s_waitcnt vmcnt(8)
	s_waitcnt lgkmcnt(0)
	s_barrier
	s_waitcnt lgkmcnt(0)
	v_mfma_f32_16x16x32_bf16 v[126:129], v[130:133], v[164:167], v[126:129]
	v_mfma_f32_16x16x32_bf16 v[122:125], v[138:141], v[164:167], v[122:125]
	v_mfma_f32_16x16x32_bf16 v[110:113], v[130:133], v[172:175], v[110:113]
	v_mfma_f32_16x16x32_bf16 v[106:109], v[138:141], v[172:175], v[106:109]
	v_mfma_f32_16x16x32_bf16 v[94:97], v[130:133], v[180:183], v[94:97]
	v_mfma_f32_16x16x32_bf16 v[90:93], v[138:141], v[180:183], v[90:93]
	v_mfma_f32_16x16x32_bf16 v[78:81], v[130:133], v[208:211], v[78:81]
	v_mfma_f32_16x16x32_bf16 v[74:77], v[138:141], v[208:211], v[74:77]
	v_mfma_f32_16x16x32_bf16 v[126:129], v[134:137], v[168:171], v[126:129]
	v_mfma_f32_16x16x32_bf16 v[122:125], v[142:145], v[168:171], v[122:125]
	v_mfma_f32_16x16x32_bf16 v[110:113], v[134:137], v[176:179], v[110:113]
	v_mfma_f32_16x16x32_bf16 v[106:109], v[142:145], v[176:179], v[106:109]
	s_setprio 1
	v_mfma_f32_16x16x32_bf16 v[94:97], v[134:137], v[184:187], v[94:97]
	v_mfma_f32_16x16x32_bf16 v[90:93], v[142:145], v[184:187], v[90:93]
	v_mfma_f32_16x16x32_bf16 v[78:81], v[134:137], v[212:215], v[78:81]
	v_mfma_f32_16x16x32_bf16 v[74:77], v[142:145], v[212:215], v[74:77]
	v_mfma_f32_16x16x32_bf16 v[118:121], v[148:151], v[164:167], v[118:121]
	v_mfma_f32_16x16x32_bf16 v[114:117], v[156:159], v[164:167], v[114:117]
	v_mfma_f32_16x16x32_bf16 v[102:105], v[148:151], v[172:175], v[102:105]
	v_mfma_f32_16x16x32_bf16 v[98:101], v[156:159], v[172:175], v[98:101]
	v_mfma_f32_16x16x32_bf16 v[86:89], v[148:151], v[180:183], v[86:89]
	v_mfma_f32_16x16x32_bf16 v[82:85], v[156:159], v[180:183], v[82:85]
	v_mfma_f32_16x16x32_bf16 v[70:73], v[148:151], v[208:211], v[70:73]
	v_mfma_f32_16x16x32_bf16 v[66:69], v[156:159], v[208:211], v[66:69]
	v_mfma_f32_16x16x32_bf16 v[118:121], v[152:155], v[168:171], v[118:121]
	v_mfma_f32_16x16x32_bf16 v[114:117], v[160:163], v[168:171], v[114:117]
	v_mfma_f32_16x16x32_bf16 v[102:105], v[152:155], v[176:179], v[102:105]
	v_mfma_f32_16x16x32_bf16 v[98:101], v[160:163], v[176:179], v[98:101]
	v_mfma_f32_16x16x32_bf16 v[86:89], v[152:155], v[184:187], v[86:89]
	v_mfma_f32_16x16x32_bf16 v[82:85], v[160:163], v[184:187], v[82:85]
	v_mfma_f32_16x16x32_bf16 v[70:73], v[152:155], v[212:215], v[70:73]
	v_mfma_f32_16x16x32_bf16 v[66:69], v[160:163], v[212:215], v[66:69]
	s_setprio 0
	s_barrier
	s_add_u32 s20, s20, 0x80080
	s_addc_u32 s21, s21, 0
	s_add_u32 s46, s46, 0xfff80080
	s_addc_u32 s47, s47, -1
	s_add_i32 s2, s2, s29
	s_mov_b32 m0, s2
	ds_read_b128 v[164:167], v228 offset:49152
	ds_read_b128 v[168:171], v228 offset:50176
	global_load_lds_dwordx4 v0, s[46:47]
	s_add_i32 m0, s2, 0x2000
	s_add_i32 s2, s45, s29
	ds_read_b128 v[172:175], v228 offset:51200
	ds_read_b128 v[176:179], v228 offset:52224
	global_load_lds_dwordx4 v188, s[46:47]
	s_mov_b32 m0, s2
	ds_read_b128 v[180:183], v228 offset:53248
	ds_read_b128 v[184:187], v228 offset:54272
	global_load_lds_dwordx4 v0, s[20:21]
	s_add_i32 m0, s2, 0x2000
	ds_read_b128 v[208:211], v228 offset:55296
	ds_read_b128 v[212:215], v228 offset:56320
	global_load_lds_dwordx4 v188, s[20:21]
	s_waitcnt vmcnt(6)
	s_waitcnt lgkmcnt(0)
	s_barrier
	s_waitcnt lgkmcnt(0)
	v_mfma_f32_16x16x32_bf16 v[62:65], v[130:133], v[164:167], v[62:65]
	v_mfma_f32_16x16x32_bf16 v[58:61], v[138:141], v[164:167], v[58:61]
	v_mfma_f32_16x16x32_bf16 v[46:49], v[130:133], v[172:175], v[46:49]
	v_mfma_f32_16x16x32_bf16 v[42:45], v[138:141], v[172:175], v[42:45]
	v_mfma_f32_16x16x32_bf16 v[30:33], v[130:133], v[180:183], v[30:33]
	v_mfma_f32_16x16x32_bf16 v[26:29], v[138:141], v[180:183], v[26:29]
	v_mfma_f32_16x16x32_bf16 v[14:17], v[130:133], v[208:211], v[14:17]
	v_mfma_f32_16x16x32_bf16 v[10:13], v[138:141], v[208:211], v[10:13]
	v_mfma_f32_16x16x32_bf16 v[62:65], v[134:137], v[168:171], v[62:65]
	v_mfma_f32_16x16x32_bf16 v[58:61], v[142:145], v[168:171], v[58:61]
	v_mfma_f32_16x16x32_bf16 v[46:49], v[134:137], v[176:179], v[46:49]
	v_mfma_f32_16x16x32_bf16 v[42:45], v[142:145], v[176:179], v[42:45]
	s_setprio 1
	v_mfma_f32_16x16x32_bf16 v[30:33], v[134:137], v[184:187], v[30:33]
	v_mfma_f32_16x16x32_bf16 v[26:29], v[142:145], v[184:187], v[26:29]
	v_mfma_f32_16x16x32_bf16 v[14:17], v[134:137], v[212:215], v[14:17]
	v_mfma_f32_16x16x32_bf16 v[10:13], v[142:145], v[212:215], v[10:13]
	v_mfma_f32_16x16x32_bf16 v[54:57], v[148:151], v[164:167], v[54:57]
	v_mfma_f32_16x16x32_bf16 v[50:53], v[156:159], v[164:167], v[50:53]
	v_mfma_f32_16x16x32_bf16 v[38:41], v[148:151], v[172:175], v[38:41]
	v_mfma_f32_16x16x32_bf16 v[34:37], v[156:159], v[172:175], v[34:37]
	v_mfma_f32_16x16x32_bf16 v[22:25], v[148:151], v[180:183], v[22:25]
	v_mfma_f32_16x16x32_bf16 v[18:21], v[156:159], v[180:183], v[18:21]
	v_mfma_f32_16x16x32_bf16 v[6:9], v[148:151], v[208:211], v[6:9]
	v_mfma_f32_16x16x32_bf16 v[2:5], v[156:159], v[208:211], v[2:5]
	v_mfma_f32_16x16x32_bf16 v[54:57], v[152:155], v[168:171], v[54:57]
	v_mfma_f32_16x16x32_bf16 v[50:53], v[160:163], v[168:171], v[50:53]
	v_mfma_f32_16x16x32_bf16 v[38:41], v[152:155], v[176:179], v[38:41]
	v_mfma_f32_16x16x32_bf16 v[34:37], v[160:163], v[176:179], v[34:37]
	v_mfma_f32_16x16x32_bf16 v[22:25], v[152:155], v[184:187], v[22:25]
	v_mfma_f32_16x16x32_bf16 v[18:21], v[160:163], v[184:187], v[18:21]
	v_mfma_f32_16x16x32_bf16 v[6:9], v[152:155], v[212:215], v[6:9]
	v_mfma_f32_16x16x32_bf16 v[2:5], v[160:163], v[212:215], v[2:5]
	s_setprio 0
	s_barrier
	s_add_i32 s44, s44, 2
	s_add_u32 s22, s22, 0x100
	s_addc_u32 s23, s23, 0
	s_add_u32 s42, s42, 0x100
	s_addc_u32 s43, s43, 0
	s_cmp_gt_u32 s44, 29
	s_cbranch_scc0 .LBB0_1102
	s_nop 0
	s_nop 0
	s_nop 0
	s_nop 0
	s_nop 0
	s_nop 0
	s_nop 0
	s_nop 0
	v_lshl_or_b32 v210, s3, 8, v227
	v_lshl_add_u32 v224, s34, 8, v147
	v_ashrrev_i32_e32 v211, 31, v210
	v_lshlrev_b64 v[130:131], 1, v[210:211]
	v_ashrrev_i32_e32 v225, 31, v224
	v_lshl_add_u64 v[132:133], s[8:9], 0, v[130:131]
	v_lshlrev_b64 v[134:135], 12, v[224:225]
	v_lshl_add_u64 v[136:137], v[132:133], 0, v[134:135]
	global_load_dwordx4 v[240:243], v[136:137], off
	global_load_dwordx4 v[244:247], v[136:137], off offset:256
	v_or_b32_e32 v222, 16, v224
	v_or_b32_e32 v220, 32, v224
	v_or_b32_e32 v218, 48, v224
	v_add_u32_e32 v216, 0x80, v224
	v_add_u32_e32 v214, 0x90, v224
	v_add_u32_e32 v212, 0xa0, v224
	v_add_u32_e32 v208, 0xb0, v224
	v_ashrrev_i32_e32 v223, 31, v222
	v_ashrrev_i32_e32 v221, 31, v220
	v_ashrrev_i32_e32 v219, 31, v218
	v_ashrrev_i32_e32 v217, 31, v216
	v_ashrrev_i32_e32 v215, 31, v214
	v_ashrrev_i32_e32 v213, 31, v212
	v_ashrrev_i32_e32 v209, 31, v208
	v_lshlrev_b64 v[136:137], 12, v[222:223]
	v_lshlrev_b64 v[138:139], 12, v[220:221]
	v_lshlrev_b64 v[140:141], 12, v[218:219]
	v_lshlrev_b64 v[142:143], 12, v[216:217]
	v_lshlrev_b64 v[144:145], 12, v[214:215]
	v_lshlrev_b64 v[148:149], 12, v[212:213]
	v_lshlrev_b64 v[150:151], 12, v[208:209]
	v_lshl_add_u64 v[134:135], s[8:9], 0, v[134:135]
	v_lshl_add_u64 v[136:137], v[132:133], 0, v[136:137]
	v_lshl_add_u64 v[138:139], v[132:133], 0, v[138:139]
	v_lshl_add_u64 v[140:141], v[132:133], 0, v[140:141]
	v_lshl_add_u64 v[142:143], v[132:133], 0, v[142:143]
	v_lshl_add_u64 v[144:145], v[132:133], 0, v[144:145]
	v_lshl_add_u64 v[236:237], v[132:133], 0, v[148:149]
	v_lshl_add_u64 v[132:133], v[132:133], 0, v[150:151]
	v_lshl_add_u64 v[248:249], v[134:135], 0, v[130:131]
	global_load_dwordx4 v[184:187], v[136:137], off
	global_load_dwordx4 v[180:183], v[136:137], off offset:256
	global_load_dwordx4 v[176:179], v[138:139], off
	global_load_dwordx4 v[172:175], v[138:139], off offset:256
	global_load_dwordx4 v[168:171], v[140:141], off
	global_load_dwordx4 v[164:167], v[140:141], off offset:256
	global_load_dwordx4 v[160:163], v[142:143], off
	global_load_dwordx4 v[156:159], v[142:143], off offset:256
	global_load_dwordx4 v[152:155], v[144:145], off
	global_load_dwordx4 v[148:151], v[144:145], off offset:256
	s_nop 0
	global_load_dwordx4 v[142:145], v[236:237], off
	global_load_dwordx4 v[138:141], v[236:237], off offset:256
	global_load_dwordx4 v[134:137], v[132:133], off
	s_nop 0
	global_load_dwordx4 v[130:133], v[132:133], off offset:256
	s_lshl_b32 s20, s3, 2
	s_ashr_i32 s21, s20, 31
	s_waitcnt vmcnt(0)
	v_lshlrev_b32_e32 v236, 16, v240
	v_and_b32_e32 v237, 0xffff0000, v240
	v_lshlrev_b32_e32 v250, 16, v242
	v_and_b32_e32 v251, 0xffff0000, v242
	v_lshlrev_b32_e32 v242, 16, v243
	v_and_b32_e32 v243, 0xffff0000, v243
	v_lshlrev_b32_e32 v240, 16, v241
	v_and_b32_e32 v241, 0xffff0000, v241
	v_pk_add_f32 v[126:127], v[126:127], v[236:237]
	v_pk_add_f32 v[236:237], v[124:125], v[242:243]
	v_pk_add_f32 v[124:125], v[122:123], v[250:251]
	v_pk_add_f32 v[128:129], v[128:129], v[240:241]
	v_cvt_pk_bf16_f32 v122, v126, v127
	v_lshlrev_b32_e32 v252, 16, v244
	v_cvt_pk_bf16_f32 v123, v128, v129
	v_cvt_pk_bf16_f32 v124, v124, v125
	v_cvt_pk_bf16_f32 v125, v236, v237
	global_store_dwordx4 v[248:249], v[122:125], off
	v_lshlrev_b32_e32 v126, 16, v122
	v_lshlrev_b32_e32 v127, 16, v123
	v_and_b32_e32 v122, 0xffff0000, v122
	v_and_b32_e32 v123, 0xffff0000, v123
	v_lshlrev_b32_e32 v128, 16, v124
	v_and_b32_e32 v124, 0xffff0000, v124
	v_lshlrev_b32_e32 v129, 16, v125
	v_and_b32_e32 v125, 0xffff0000, v125
	v_mul_f32_e32 v122, v122, v122
	v_mul_f32_e32 v123, v123, v123
	v_mul_f32_e32 v124, v124, v124
	v_mul_f32_e32 v125, v125, v125
	v_fmac_f32_e32 v122, v126, v126
	v_fmac_f32_e32 v123, v127, v127
	v_fmac_f32_e32 v124, v128, v128
	v_fmac_f32_e32 v125, v129, v129
	v_add_f32_e32 v122, v122, v123
	v_add_f32_e32 v123, v124, v125
	v_and_b32_e32 v253, 0xffff0000, v244
	v_add_f32_e32 v128, v122, v123
	v_lshlrev_b32_e32 v122, 16, v245
	v_and_b32_e32 v123, 0xffff0000, v245
	v_lshlrev_b32_e32 v124, 16, v246
	v_and_b32_e32 v125, 0xffff0000, v246
	v_lshlrev_b32_e32 v126, 16, v247
	v_and_b32_e32 v127, 0xffff0000, v247
	v_pk_add_f32 v[120:121], v[120:121], v[122:123]
	v_pk_add_f32 v[118:119], v[118:119], v[252:253]
	v_pk_add_f32 v[122:123], v[116:117], v[126:127]
	v_pk_add_f32 v[116:117], v[114:115], v[124:125]
	v_cvt_pk_bf16_f32 v114, v118, v119
	v_cvt_pk_bf16_f32 v115, v120, v121
	s_nop 0
	v_cvt_pk_bf16_f32 v116, v116, v117
	v_cvt_pk_bf16_f32 v117, v122, v123
	global_store_dwordx4 v[248:249], v[114:117], off offset:256
	v_lshlrev_b32_e32 v118, 16, v114
	v_lshlrev_b32_e32 v119, 16, v115
	v_and_b32_e32 v114, 0xffff0000, v114
	v_and_b32_e32 v115, 0xffff0000, v115
	v_mul_f32_e32 v114, v114, v114
	v_mul_f32_e32 v115, v115, v115
	v_lshlrev_b32_e32 v120, 16, v116
	v_and_b32_e32 v116, 0xffff0000, v116
	v_lshlrev_b32_e32 v121, 16, v117
	v_and_b32_e32 v117, 0xffff0000, v117
	v_fmac_f32_e32 v114, v118, v118
	v_fmac_f32_e32 v115, v119, v119
	v_add_f32_e32 v114, v114, v115
	v_mul_f32_e32 v115, v116, v116
	v_mul_f32_e32 v116, v117, v117
	v_fmac_f32_e32 v115, v120, v120
	v_fmac_f32_e32 v116, v121, v121
	v_add_f32_e32 v115, v115, v116
	v_add_f32_e32 v114, v114, v115
	s_mov_b32 s2, 0
	v_add_f32_e32 v114, v128, v114
	v_mbcnt_lo_u32_b32 v115, -1, s2
	v_mbcnt_hi_u32_b32 v115, -1, v115
	v_lshlrev_b32_e32 v115, 2, v115
	v_xor_b32_e32 v115, 64, v115
	ds_bpermute_b32 v115, v115, v114
	s_mov_b32 s2, 0
	s_waitcnt lgkmcnt(0)
	v_add_f32_e32 v114, v114, v115
	v_mbcnt_lo_u32_b32 v115, -1, s2
	v_mbcnt_hi_u32_b32 v115, -1, v115
	v_lshlrev_b32_e32 v115, 2, v115
	v_xor_b32_e32 v115, 0x80, v115
	ds_bpermute_b32 v115, v115, v114
	s_and_saveexec_b64 s[22:23], s[4:5]
	s_cbranch_execz .LBB0_1105
	v_lshlrev_b64 v[116:117], 7, v[224:225]
	v_lshl_add_u64 v[116:117], s[10:11], 0, v[116:117]
	v_lshl_add_u64 v[116:117], s[20:21], 2, v[116:117]
	s_lshl_b32 s50, s37, 2
	v_lshl_add_u64 v[116:117], v[116:117], 0, s[50:51]
	s_waitcnt lgkmcnt(0)
	v_add_f32_e32 v114, v114, v115
	global_store_dword v[116:117], v114, off
